# rsq+NR replaces sqrt/div in rstd chains; EpiResid epilogue hand-pipelined (loads 2-4 row groups ahead)
# speedup vs baseline: 1.0073x; 1.0073x over previous
.LBB0_389:
	v_lshl_add_u32 v202, s39, 8, v170
	v_ashrrev_i32_e32 v203, 31, v202
	v_lshlrev_b64 v[130:131], 6, v[202:203]
	v_lshl_add_u64 v[130:131], v[168:169], 0, v[130:131]
	global_load_dwordx4 v[158:161], v[130:131], off
	v_or_b32_e32 v200, 16, v202
	v_ashrrev_i32_e32 v201, 31, v200
	v_lshlrev_b64 v[130:131], 6, v[200:201]
	v_lshl_add_u64 v[130:131], v[168:169], 0, v[130:131]
	global_load_dwordx4 v[154:157], v[130:131], off
	v_or_b32_e32 v198, 32, v202
	v_ashrrev_i32_e32 v199, 31, v198
	v_lshlrev_b64 v[130:131], 6, v[198:199]
	v_or_b32_e32 v196, 48, v202
	v_lshl_add_u64 v[130:131], v[168:169], 0, v[130:131]
	v_ashrrev_i32_e32 v197, 31, v196
	global_load_dwordx4 v[150:153], v[130:131], off
	v_lshlrev_b64 v[130:131], 6, v[196:197]
	v_add_u32_e32 v194, 0x80, v202
	v_lshl_add_u64 v[130:131], v[168:169], 0, v[130:131]
	v_ashrrev_i32_e32 v195, 31, v194
	global_load_dwordx4 v[146:149], v[130:131], off
	v_lshlrev_b64 v[130:131], 6, v[194:195]
	v_add_u32_e32 v192, 0x90, v202
	v_lshl_add_u64 v[130:131], v[168:169], 0, v[130:131]
	v_ashrrev_i32_e32 v193, 31, v192
	global_load_dwordx4 v[142:145], v[130:131], off
	v_lshlrev_b64 v[130:131], 6, v[192:193]
	v_add_u32_e32 v190, 0xa0, v202
	v_and_b32_e32 v175, 64, v230
	v_lshl_add_u64 v[130:131], v[168:169], 0, v[130:131]
	v_ashrrev_i32_e32 v191, 31, v190
	v_xor_b32_e32 v174, 16, v230
	v_add_u32_e32 v175, 64, v175
	global_load_dwordx4 v[138:141], v[130:131], off
	v_lshlrev_b64 v[130:131], 6, v[190:191]
	v_add_u32_e32 v188, 0xb0, v202
	v_cmp_lt_i32_e32 vcc, v174, v175
	v_lshl_add_u64 v[130:131], v[168:169], 0, v[130:131]
	v_ashrrev_i32_e32 v189, 31, v188
	v_cndmask_b32_e32 v174, v230, v174, vcc
	global_load_dwordx4 v[134:137], v[130:131], off
	v_lshlrev_b64 v[130:131], 6, v[188:189]
	v_lshlrev_b32_e32 v189, 2, v174
	v_xor_b32_e32 v174, 32, v230
	v_cmp_lt_i32_e32 vcc, v174, v175
	v_lshl_add_u64 v[130:131], v[168:169], 0, v[130:131]
	global_load_dwordx4 v[130:133], v[130:131], off
	v_cndmask_b32_e32 v174, v230, v174, vcc
	v_lshlrev_b32_e32 v191, 2, v174
	v_lshl_or_b32 v204, s38, 7, v183
	v_ashrrev_i32_e32 v205, 31, v204
	s_mov_b64 s[40:41], 0x6000
	s_waitcnt vmcnt(0)
	v_mov_b32_e32 v174, v159
	v_mov_b32_e32 v175, v160
	v_mov_b32_e32 v159, v161
	v_pk_add_f32 v[158:159], v[174:175], v[158:159]
	s_nop 0
	v_add_f32_e32 v158, v158, v159
	ds_bpermute_b32 v159, v189, v158
	s_waitcnt lgkmcnt(0)
	v_add_f32_e32 v158, v158, v159
	ds_bpermute_b32 v159, v191, v158
	s_waitcnt lgkmcnt(0)
	v_add_f32_e32 v158, v158, v159
	v_fmamk_f32 v158, v158, 0x3a800000, v223
	s_nop 0
	s_nop 0
	s_nop 0
	s_nop 1
	s_nop 1
	s_nop 0
	v_mov_b32_e32 v160, v155
	v_mov_b32_e32 v161, v156
	v_mov_b32_e32 v155, v157
	v_pk_add_f32 v[154:155], v[160:161], v[154:155]
	v_rsq_f32_e32 v159, v158
	s_nop 0
	v_mul_f32_e32 v158, v158, v159
	v_fma_f32 v158, -v158, v159, 1.0
	v_mul_f32_e32 v158, 0.5, v158
	v_fma_f32 v158, v159, v158, v159
	v_add_f32_e32 v154, v154, v155
	ds_bpermute_b32 v155, v189, v154
	s_waitcnt lgkmcnt(0)
	v_add_f32_e32 v154, v154, v155
	ds_bpermute_b32 v155, v191, v154
	s_waitcnt lgkmcnt(0)
	v_add_f32_e32 v154, v154, v155
	v_fmamk_f32 v154, v154, 0x3a800000, v223
	s_nop 0
	s_nop 0
	s_nop 0
	s_nop 1
	s_nop 1
	s_nop 0
	v_pk_mul_f32 v[126:127], v[126:127], v[158:159] op_sel_hi:[1,0]
	v_pk_mul_f32 v[118:119], v[118:119], v[158:159] op_sel_hi:[1,0]
	v_pk_mul_f32 v[128:129], v[128:129], v[158:159] op_sel_hi:[1,0]
	v_mul_f32_e32 v118, v126, v118
	v_mul_f32_e32 v126, 0xbfb8aa3b, v126
	v_exp_f32_e32 v126, v126
	v_mul_f32_e32 v119, v127, v119
	v_pk_mul_f32 v[120:121], v[120:121], v[158:159] op_sel_hi:[1,0]
	v_add_f32_e32 v126, 1.0, v126
	v_rcp_f32_e32 v126, v126
	v_mov_b32_e32 v156, v151
	v_mov_b32_e32 v157, v152
	v_mul_f32_e32 v118, v118, v126
	v_mul_f32_e32 v126, 0xbfb8aa3b, v127
	v_exp_f32_e32 v126, v126
	v_mov_b32_e32 v151, v153
	v_pk_add_f32 v[150:151], v[156:157], v[150:151]
	v_pk_mul_f32 v[122:123], v[122:123], v[158:159] op_sel_hi:[1,0]
	v_add_f32_e32 v126, 1.0, v126
	v_rcp_f32_e32 v126, v126
	v_add_f32_e32 v150, v150, v151
	ds_bpermute_b32 v151, v189, v150
	v_pk_mul_f32 v[114:115], v[114:115], v[158:159] op_sel_hi:[1,0]
	v_mul_f32_e32 v119, v119, v126
	v_cvt_pk_bf16_f32 v118, v118, v119
	v_mul_f32_e32 v119, v128, v120
	v_mul_f32_e32 v120, 0xbfb8aa3b, v128
	v_exp_f32_e32 v120, v120
	s_waitcnt lgkmcnt(0)
	v_add_f32_e32 v150, v150, v151
	ds_bpermute_b32 v151, v191, v150
	v_mul_f32_e32 v114, v122, v114
	v_add_f32_e32 v120, 1.0, v120
	v_rcp_f32_e32 v120, v120
	v_mul_f32_e32 v115, v123, v115
	s_waitcnt lgkmcnt(0)
	v_add_f32_e32 v150, v150, v151
	v_fmamk_f32 v150, v150, 0x3a800000, v223
	v_mul_f32_e32 v119, v119, v120
	v_mul_f32_e32 v120, v129, v121
	v_mul_f32_e32 v121, 0xbfb8aa3b, v129
	v_exp_f32_e32 v121, v121
	v_pk_mul_f32 v[124:125], v[124:125], v[158:159] op_sel_hi:[1,0]
	v_add_f32_e32 v121, 1.0, v121
	v_rcp_f32_e32 v121, v121
	v_pk_mul_f32 v[116:117], v[116:117], v[158:159] op_sel_hi:[1,0]
	v_mul_f32_e32 v120, v120, v121
	v_cvt_pk_bf16_f32 v119, v119, v120
	v_mul_f32_e32 v120, 0xbfb8aa3b, v122
	v_exp_f32_e32 v120, v120
	s_nop 0
	v_add_f32_e32 v120, 1.0, v120
	v_rcp_f32_e32 v120, v120
	s_nop 0
	v_mul_f32_e32 v114, v114, v120
	v_mul_f32_e32 v120, 0xbfb8aa3b, v123
	v_exp_f32_e32 v120, v120
	v_rsq_f32_e32 v155, v154
	s_nop 0
	v_mul_f32_e32 v154, v154, v155
	v_fma_f32 v154, -v154, v155, 1.0
	v_mul_f32_e32 v154, 0.5, v154
	v_fma_f32 v154, v155, v154, v155
	v_add_f32_e32 v120, 1.0, v120
	v_rcp_f32_e32 v120, v120
	s_nop 0
	v_mul_f32_e32 v115, v115, v120
	v_cvt_pk_bf16_f32 v120, v114, v115
	v_mul_f32_e32 v115, 0xbfb8aa3b, v124
	v_mul_f32_e32 v114, v124, v116
	v_exp_f32_e32 v115, v115
	v_mul_f32_e32 v116, 0xbfb8aa3b, v125
	v_exp_f32_e32 v116, v116
	v_add_f32_e32 v115, 1.0, v115
	v_rcp_f32_e32 v115, v115
	v_add_f32_e32 v116, 1.0, v116
	v_rcp_f32_e32 v116, v116
	v_mul_f32_e32 v114, v114, v115
	v_mul_f32_e32 v115, v125, v117
	v_mul_f32_e32 v115, v115, v116
	v_cvt_pk_bf16_f32 v121, v114, v115
	v_mov_b64_e32 v[114:115], s[10:11]
	v_mad_i64_i32 v[122:123], s[2:3], v202, s64, v[114:115]
	v_lshlrev_b64 v[116:117], 1, v[204:205]
	v_lshl_add_u64 v[122:123], v[122:123], 0, v[116:117]
	v_pk_mul_f32 v[110:111], v[110:111], v[154:155] op_sel_hi:[1,0]
	global_store_dwordx4 v[122:123], v[118:121], off
	v_pk_mul_f32 v[102:103], v[102:103], v[154:155] op_sel_hi:[1,0]
	v_pk_mul_f32 v[112:113], v[112:113], v[154:155] op_sel_hi:[1,0]
	v_pk_mul_f32 v[118:119], v[100:101], v[154:155] op_sel_hi:[1,0]
	v_pk_mul_f32 v[100:101], v[98:99], v[154:155] op_sel_hi:[1,0]
	v_mul_f32_e32 v99, 0xbfb8aa3b, v110
	v_mul_f32_e32 v98, v110, v102
	v_exp_f32_e32 v99, v99
	v_mul_f32_e32 v102, 0xbfb8aa3b, v111
	v_exp_f32_e32 v102, v102
	v_add_f32_e32 v99, 1.0, v99
	v_rcp_f32_e32 v99, v99
	v_add_f32_e32 v102, 1.0, v102
	v_rcp_f32_e32 v102, v102
	v_mul_f32_e32 v98, v98, v99
	v_mul_f32_e32 v99, v111, v103
	v_mul_f32_e32 v99, v99, v102
	v_mul_f32_e32 v102, 0xbfb8aa3b, v112
	v_exp_f32_e32 v102, v102
	v_mul_f32_e32 v103, 0xbfb8aa3b, v113
	v_exp_f32_e32 v103, v103
	v_mov_b32_e32 v152, v147
	v_mov_b32_e32 v153, v148
	v_mov_b32_e32 v147, v149
	v_pk_add_f32 v[146:147], v[152:153], v[146:147]
	v_add_f32_e32 v102, 1.0, v102
	v_add_f32_e32 v146, v146, v147
	v_rcp_f32_e32 v102, v102
	v_add_f32_e32 v103, 1.0, v103
	ds_bpermute_b32 v147, v189, v146
	v_rcp_f32_e32 v103, v103
	v_pk_mul_f32 v[104:105], v[104:105], v[154:155] op_sel_hi:[1,0]
	v_cvt_pk_bf16_f32 v98, v98, v99
	v_pk_mul_f32 v[106:107], v[106:107], v[154:155] op_sel_hi:[1,0]
	v_mul_f32_e32 v99, v112, v104
	v_mul_f32_e32 v99, v99, v102
	v_mul_f32_e32 v102, v113, v105
	v_mul_f32_e32 v102, v102, v103
	s_waitcnt lgkmcnt(0)
	v_add_f32_e32 v146, v146, v147
	v_cvt_pk_bf16_f32 v99, v99, v102
	v_mul_f32_e32 v102, 0xbfb8aa3b, v106
	ds_bpermute_b32 v147, v191, v146
	v_exp_f32_e32 v102, v102
	v_mul_f32_e32 v100, v106, v100
	v_pk_mul_f32 v[108:109], v[108:109], v[154:155] op_sel_hi:[1,0]
	v_mul_f32_e32 v101, v107, v101
	v_add_f32_e32 v102, 1.0, v102
	s_waitcnt lgkmcnt(0)
	v_add_f32_e32 v146, v146, v147
	v_rcp_f32_e32 v102, v102
	v_fmamk_f32 v146, v146, 0x3a800000, v223
	v_mul_f32_e32 v100, v100, v102
	v_mul_f32_e32 v102, 0xbfb8aa3b, v107
	v_exp_f32_e32 v102, v102
	v_mul_f32_e32 v103, 0xbfb8aa3b, v109
	v_add_f32_e32 v102, 1.0, v102
	v_rcp_f32_e32 v102, v102
	s_nop 0
	v_mul_f32_e32 v101, v101, v102
	v_mul_f32_e32 v102, 0xbfb8aa3b, v108
	v_exp_f32_e32 v102, v102
	v_exp_f32_e32 v103, v103
	v_add_f32_e32 v102, 1.0, v102
	v_rcp_f32_e32 v102, v102
	v_add_f32_e32 v103, 1.0, v103
	v_rcp_f32_e32 v103, v103
	v_cvt_pk_bf16_f32 v100, v100, v101
	v_mul_f32_e32 v101, v108, v118
	v_rsq_f32_e32 v151, v150
	s_nop 0
	v_mul_f32_e32 v150, v150, v151
	v_fma_f32 v150, -v150, v151, 1.0
	v_mul_f32_e32 v150, 0.5, v150
	v_fma_f32 v150, v151, v150, v151
	v_mul_f32_e32 v101, v101, v102
	v_mul_f32_e32 v102, v109, v119
	v_mul_f32_e32 v102, v102, v103
	v_cvt_pk_bf16_f32 v101, v101, v102
	v_mad_i64_i32 v[102:103], s[2:3], v200, s64, v[114:115]
	v_lshl_add_u64 v[102:103], v[102:103], 0, v[116:117]
	v_pk_mul_f32 v[94:95], v[94:95], v[150:151] op_sel_hi:[1,0]
	global_store_dwordx4 v[102:103], v[98:101], off
	v_pk_mul_f32 v[86:87], v[86:87], v[150:151] op_sel_hi:[1,0]
	v_pk_mul_f32 v[96:97], v[96:97], v[150:151] op_sel_hi:[1,0]
	v_pk_mul_f32 v[98:99], v[84:85], v[150:151] op_sel_hi:[1,0]
	v_pk_mul_f32 v[84:85], v[82:83], v[150:151] op_sel_hi:[1,0]
	v_mul_f32_e32 v83, 0xbfb8aa3b, v94
	v_mul_f32_e32 v82, v94, v86
	v_exp_f32_e32 v83, v83
	v_mul_f32_e32 v86, 0xbfb8aa3b, v95
	v_exp_f32_e32 v86, v86
	v_add_f32_e32 v83, 1.0, v83
	v_rcp_f32_e32 v83, v83
	v_add_f32_e32 v86, 1.0, v86
	v_rcp_f32_e32 v86, v86
	v_mul_f32_e32 v82, v82, v83
	v_mul_f32_e32 v83, v95, v87
	v_mul_f32_e32 v83, v83, v86
	v_mul_f32_e32 v86, 0xbfb8aa3b, v96
	v_exp_f32_e32 v86, v86
	v_mul_f32_e32 v87, 0xbfb8aa3b, v97
	v_exp_f32_e32 v87, v87
	v_mov_b32_e32 v148, v143
	v_mov_b32_e32 v149, v144
	v_mov_b32_e32 v143, v145
	v_pk_add_f32 v[142:143], v[148:149], v[142:143]
	v_add_f32_e32 v86, 1.0, v86
	v_add_f32_e32 v142, v142, v143
	v_rcp_f32_e32 v86, v86
	v_add_f32_e32 v87, 1.0, v87
	ds_bpermute_b32 v143, v189, v142
	v_rcp_f32_e32 v87, v87
	v_pk_mul_f32 v[88:89], v[88:89], v[150:151] op_sel_hi:[1,0]
	v_cvt_pk_bf16_f32 v82, v82, v83
	v_pk_mul_f32 v[90:91], v[90:91], v[150:151] op_sel_hi:[1,0]
	v_mul_f32_e32 v83, v96, v88
	v_mul_f32_e32 v83, v83, v86
	v_mul_f32_e32 v86, v97, v89
	v_mul_f32_e32 v86, v86, v87
	s_waitcnt lgkmcnt(0)
	v_add_f32_e32 v142, v142, v143
	v_cvt_pk_bf16_f32 v83, v83, v86
	v_mul_f32_e32 v86, 0xbfb8aa3b, v90
	ds_bpermute_b32 v143, v191, v142
	v_exp_f32_e32 v86, v86
	v_mul_f32_e32 v84, v90, v84
	v_pk_mul_f32 v[92:93], v[92:93], v[150:151] op_sel_hi:[1,0]
	v_mul_f32_e32 v85, v91, v85
	v_add_f32_e32 v86, 1.0, v86
	s_waitcnt lgkmcnt(0)
	v_add_f32_e32 v142, v142, v143
	v_rcp_f32_e32 v86, v86
	v_fmamk_f32 v142, v142, 0x3a800000, v223
	v_mul_f32_e32 v84, v84, v86
	v_mul_f32_e32 v86, 0xbfb8aa3b, v91
	v_exp_f32_e32 v86, v86
	v_mul_f32_e32 v87, 0xbfb8aa3b, v93
	v_add_f32_e32 v86, 1.0, v86
	v_rcp_f32_e32 v86, v86
	s_nop 0
	v_mul_f32_e32 v85, v85, v86
	v_mul_f32_e32 v86, 0xbfb8aa3b, v92
	v_exp_f32_e32 v86, v86
	v_exp_f32_e32 v87, v87
	v_add_f32_e32 v86, 1.0, v86
	v_rcp_f32_e32 v86, v86
	v_add_f32_e32 v87, 1.0, v87
	v_rcp_f32_e32 v87, v87
	v_cvt_pk_bf16_f32 v84, v84, v85
	v_mul_f32_e32 v85, v92, v98
	v_rsq_f32_e32 v147, v146
	s_nop 0
	v_mul_f32_e32 v146, v146, v147
	v_fma_f32 v146, -v146, v147, 1.0
	v_mul_f32_e32 v146, 0.5, v146
	v_fma_f32 v146, v147, v146, v147
	v_mul_f32_e32 v85, v85, v86
	v_mul_f32_e32 v86, v93, v99
	v_mul_f32_e32 v86, v86, v87
	v_cvt_pk_bf16_f32 v85, v85, v86
	v_mad_i64_i32 v[86:87], s[2:3], v198, s64, v[114:115]
	v_lshl_add_u64 v[86:87], v[86:87], 0, v[116:117]
	v_pk_mul_f32 v[78:79], v[78:79], v[146:147] op_sel_hi:[1,0]
	global_store_dwordx4 v[86:87], v[82:85], off
	v_pk_mul_f32 v[70:71], v[70:71], v[146:147] op_sel_hi:[1,0]
	v_pk_mul_f32 v[80:81], v[80:81], v[146:147] op_sel_hi:[1,0]
	v_pk_mul_f32 v[82:83], v[68:69], v[146:147] op_sel_hi:[1,0]
	v_pk_mul_f32 v[68:69], v[66:67], v[146:147] op_sel_hi:[1,0]
	v_mul_f32_e32 v67, 0xbfb8aa3b, v78
	v_mul_f32_e32 v66, v78, v70
	v_exp_f32_e32 v67, v67
	v_mul_f32_e32 v70, 0xbfb8aa3b, v79
	v_exp_f32_e32 v70, v70
	v_add_f32_e32 v67, 1.0, v67
	v_rcp_f32_e32 v67, v67
	v_add_f32_e32 v70, 1.0, v70
	v_rcp_f32_e32 v70, v70
	v_mul_f32_e32 v66, v66, v67
	v_mul_f32_e32 v67, v79, v71
	v_mul_f32_e32 v67, v67, v70
	v_mul_f32_e32 v70, 0xbfb8aa3b, v80
	v_exp_f32_e32 v70, v70
	v_mul_f32_e32 v71, 0xbfb8aa3b, v81
	v_exp_f32_e32 v71, v71
	v_mov_b32_e32 v144, v139
	v_mov_b32_e32 v145, v140
	v_mov_b32_e32 v139, v141
	v_pk_add_f32 v[138:139], v[144:145], v[138:139]
	v_add_f32_e32 v70, 1.0, v70
	v_add_f32_e32 v138, v138, v139
	v_rcp_f32_e32 v70, v70
	v_add_f32_e32 v71, 1.0, v71
	ds_bpermute_b32 v139, v189, v138
	v_rcp_f32_e32 v71, v71
	v_pk_mul_f32 v[72:73], v[72:73], v[146:147] op_sel_hi:[1,0]
	v_cvt_pk_bf16_f32 v66, v66, v67
	v_pk_mul_f32 v[74:75], v[74:75], v[146:147] op_sel_hi:[1,0]
	v_mul_f32_e32 v67, v80, v72
	v_mul_f32_e32 v67, v67, v70
	v_mul_f32_e32 v70, v81, v73
	v_mul_f32_e32 v70, v70, v71
	s_waitcnt lgkmcnt(0)
	v_add_f32_e32 v138, v138, v139
	v_cvt_pk_bf16_f32 v67, v67, v70
	v_mul_f32_e32 v70, 0xbfb8aa3b, v74
	ds_bpermute_b32 v139, v191, v138
	v_exp_f32_e32 v70, v70
	v_mul_f32_e32 v68, v74, v68
	v_pk_mul_f32 v[76:77], v[76:77], v[146:147] op_sel_hi:[1,0]
	v_mul_f32_e32 v69, v75, v69
	v_add_f32_e32 v70, 1.0, v70
	s_waitcnt lgkmcnt(0)
	v_add_f32_e32 v138, v138, v139
	v_rcp_f32_e32 v70, v70
	v_fmamk_f32 v138, v138, 0x3a800000, v223
	v_mul_f32_e32 v68, v68, v70
	v_mul_f32_e32 v70, 0xbfb8aa3b, v75
	v_exp_f32_e32 v70, v70
	v_mul_f32_e32 v71, 0xbfb8aa3b, v77
	v_add_f32_e32 v70, 1.0, v70
	v_rcp_f32_e32 v70, v70
	s_nop 0
	v_mul_f32_e32 v69, v69, v70
	v_mul_f32_e32 v70, 0xbfb8aa3b, v76
	v_exp_f32_e32 v70, v70
	v_exp_f32_e32 v71, v71
	v_add_f32_e32 v70, 1.0, v70
	v_rcp_f32_e32 v70, v70
	v_add_f32_e32 v71, 1.0, v71
	v_rcp_f32_e32 v71, v71
	v_cvt_pk_bf16_f32 v68, v68, v69
	v_mul_f32_e32 v69, v76, v82
	v_rsq_f32_e32 v143, v142
	s_nop 0
	v_mul_f32_e32 v142, v142, v143
	v_fma_f32 v142, -v142, v143, 1.0
	v_mul_f32_e32 v142, 0.5, v142
	v_fma_f32 v142, v143, v142, v143
	v_mul_f32_e32 v69, v69, v70
	v_mul_f32_e32 v70, v77, v83
	v_mul_f32_e32 v70, v70, v71
	v_cvt_pk_bf16_f32 v69, v69, v70
	v_mad_i64_i32 v[70:71], s[2:3], v196, s64, v[114:115]
	v_lshl_add_u64 v[70:71], v[70:71], 0, v[116:117]
	v_pk_mul_f32 v[62:63], v[62:63], v[142:143] op_sel_hi:[1,0]
	global_store_dwordx4 v[70:71], v[66:69], off
	v_pk_mul_f32 v[54:55], v[54:55], v[142:143] op_sel_hi:[1,0]
	v_pk_mul_f32 v[64:65], v[64:65], v[142:143] op_sel_hi:[1,0]
	v_pk_mul_f32 v[66:67], v[52:53], v[142:143] op_sel_hi:[1,0]
	v_pk_mul_f32 v[52:53], v[50:51], v[142:143] op_sel_hi:[1,0]
	v_mul_f32_e32 v51, 0xbfb8aa3b, v62
	v_mul_f32_e32 v50, v62, v54
	v_exp_f32_e32 v51, v51
	v_mul_f32_e32 v54, 0xbfb8aa3b, v63
	v_exp_f32_e32 v54, v54
	v_add_f32_e32 v51, 1.0, v51
	v_rcp_f32_e32 v51, v51
	v_add_f32_e32 v54, 1.0, v54
	v_rcp_f32_e32 v54, v54
	v_mul_f32_e32 v50, v50, v51
	v_mul_f32_e32 v51, v63, v55
	v_mul_f32_e32 v51, v51, v54
	v_mul_f32_e32 v54, 0xbfb8aa3b, v64
	v_exp_f32_e32 v54, v54
	v_mul_f32_e32 v55, 0xbfb8aa3b, v65
	v_exp_f32_e32 v55, v55
	v_mov_b32_e32 v140, v135
	v_mov_b32_e32 v141, v136
	v_mov_b32_e32 v135, v137
	v_pk_add_f32 v[134:135], v[140:141], v[134:135]
	v_add_f32_e32 v54, 1.0, v54
	v_add_f32_e32 v134, v134, v135
	v_rcp_f32_e32 v54, v54
	v_add_f32_e32 v55, 1.0, v55
	ds_bpermute_b32 v135, v189, v134
	v_rcp_f32_e32 v55, v55
	v_pk_mul_f32 v[56:57], v[56:57], v[142:143] op_sel_hi:[1,0]
	v_cvt_pk_bf16_f32 v50, v50, v51
	v_pk_mul_f32 v[58:59], v[58:59], v[142:143] op_sel_hi:[1,0]
	v_mul_f32_e32 v51, v64, v56
	v_mul_f32_e32 v51, v51, v54
	v_mul_f32_e32 v54, v65, v57
	v_mul_f32_e32 v54, v54, v55
	s_waitcnt lgkmcnt(0)
	v_add_f32_e32 v134, v134, v135
	v_cvt_pk_bf16_f32 v51, v51, v54
	v_mul_f32_e32 v54, 0xbfb8aa3b, v58
	ds_bpermute_b32 v135, v191, v134
	v_exp_f32_e32 v54, v54
	v_mul_f32_e32 v52, v58, v52
	v_pk_mul_f32 v[60:61], v[60:61], v[142:143] op_sel_hi:[1,0]
	v_mul_f32_e32 v53, v59, v53
	v_add_f32_e32 v54, 1.0, v54
	s_waitcnt lgkmcnt(0)
	v_add_f32_e32 v134, v134, v135
	v_rcp_f32_e32 v54, v54
	v_fmamk_f32 v134, v134, 0x3a800000, v223
	v_mul_f32_e32 v52, v52, v54
	v_mul_f32_e32 v54, 0xbfb8aa3b, v59
	v_exp_f32_e32 v54, v54
	v_mul_f32_e32 v55, 0xbfb8aa3b, v61
	v_add_f32_e32 v54, 1.0, v54
	v_rcp_f32_e32 v54, v54
	s_nop 0
	v_mul_f32_e32 v53, v53, v54
	v_mul_f32_e32 v54, 0xbfb8aa3b, v60
	v_exp_f32_e32 v54, v54
	v_exp_f32_e32 v55, v55
	v_add_f32_e32 v54, 1.0, v54
	v_rcp_f32_e32 v54, v54
	v_add_f32_e32 v55, 1.0, v55
	v_rcp_f32_e32 v55, v55
	v_cvt_pk_bf16_f32 v52, v52, v53
	v_mul_f32_e32 v53, v60, v66
	v_rsq_f32_e32 v139, v138
	s_nop 0
	v_mul_f32_e32 v138, v138, v139
	v_fma_f32 v138, -v138, v139, 1.0
	v_mul_f32_e32 v138, 0.5, v138
	v_fma_f32 v138, v139, v138, v139
	v_mul_f32_e32 v53, v53, v54
	v_mul_f32_e32 v54, v61, v67
	v_mul_f32_e32 v54, v54, v55
	v_cvt_pk_bf16_f32 v53, v53, v54
	v_mad_i64_i32 v[54:55], s[2:3], v194, s64, v[114:115]
	v_lshl_add_u64 v[54:55], v[54:55], 0, v[116:117]
	v_pk_mul_f32 v[46:47], v[46:47], v[138:139] op_sel_hi:[1,0]
	global_store_dwordx4 v[54:55], v[50:53], off
	v_pk_mul_f32 v[38:39], v[38:39], v[138:139] op_sel_hi:[1,0]
	v_pk_mul_f32 v[48:49], v[48:49], v[138:139] op_sel_hi:[1,0]
	v_pk_mul_f32 v[50:51], v[36:37], v[138:139] op_sel_hi:[1,0]
	v_pk_mul_f32 v[36:37], v[34:35], v[138:139] op_sel_hi:[1,0]
	v_mul_f32_e32 v35, 0xbfb8aa3b, v46
	v_mul_f32_e32 v34, v46, v38
	v_exp_f32_e32 v35, v35
	v_mul_f32_e32 v38, 0xbfb8aa3b, v47
	v_exp_f32_e32 v38, v38
	v_add_f32_e32 v35, 1.0, v35
	v_rcp_f32_e32 v35, v35
	v_add_f32_e32 v38, 1.0, v38
	v_rcp_f32_e32 v38, v38
	v_mul_f32_e32 v34, v34, v35
	v_mul_f32_e32 v35, v47, v39
	v_mul_f32_e32 v35, v35, v38
	v_mul_f32_e32 v38, 0xbfb8aa3b, v48
	v_exp_f32_e32 v38, v38
	v_mul_f32_e32 v39, 0xbfb8aa3b, v49
	v_exp_f32_e32 v39, v39
	v_mov_b32_e32 v136, v131
	v_mov_b32_e32 v137, v132
	v_mov_b32_e32 v131, v133
	v_pk_add_f32 v[130:131], v[136:137], v[130:131]
	v_add_f32_e32 v38, 1.0, v38
	v_add_f32_e32 v130, v130, v131
	v_rcp_f32_e32 v38, v38
	v_add_f32_e32 v39, 1.0, v39
	ds_bpermute_b32 v131, v189, v130
	v_rcp_f32_e32 v39, v39
	v_pk_mul_f32 v[40:41], v[40:41], v[138:139] op_sel_hi:[1,0]
	v_cvt_pk_bf16_f32 v34, v34, v35
	v_pk_mul_f32 v[42:43], v[42:43], v[138:139] op_sel_hi:[1,0]
	v_mul_f32_e32 v35, v48, v40
	v_mul_f32_e32 v35, v35, v38
	v_mul_f32_e32 v38, v49, v41
	v_mul_f32_e32 v38, v38, v39
	s_waitcnt lgkmcnt(0)
	v_add_f32_e32 v130, v130, v131
	v_cvt_pk_bf16_f32 v35, v35, v38
	v_mul_f32_e32 v38, 0xbfb8aa3b, v42
	ds_bpermute_b32 v131, v191, v130
	v_exp_f32_e32 v38, v38
	v_mul_f32_e32 v36, v42, v36
	v_pk_mul_f32 v[44:45], v[44:45], v[138:139] op_sel_hi:[1,0]
	v_mul_f32_e32 v37, v43, v37
	v_add_f32_e32 v38, 1.0, v38
	s_waitcnt lgkmcnt(0)
	v_add_f32_e32 v130, v130, v131
	v_rcp_f32_e32 v38, v38
	v_fmamk_f32 v130, v130, 0x3a800000, v223
	v_mul_f32_e32 v36, v36, v38
	v_mul_f32_e32 v38, 0xbfb8aa3b, v43
	v_exp_f32_e32 v38, v38
	v_mul_f32_e32 v39, 0xbfb8aa3b, v45
	v_add_f32_e32 v38, 1.0, v38
	v_rcp_f32_e32 v38, v38
	s_nop 0
	v_mul_f32_e32 v37, v37, v38
	v_mul_f32_e32 v38, 0xbfb8aa3b, v44
	v_exp_f32_e32 v38, v38
	v_exp_f32_e32 v39, v39
	v_add_f32_e32 v38, 1.0, v38
	v_rcp_f32_e32 v38, v38
	v_add_f32_e32 v39, 1.0, v39
	v_rcp_f32_e32 v39, v39
	v_cvt_pk_bf16_f32 v36, v36, v37
	v_mul_f32_e32 v37, v44, v50
	v_rsq_f32_e32 v135, v134
	s_nop 0
	v_mul_f32_e32 v134, v134, v135
	v_fma_f32 v134, -v134, v135, 1.0
	v_mul_f32_e32 v134, 0.5, v134
	v_fma_f32 v134, v135, v134, v135
	v_mul_f32_e32 v37, v37, v38
	v_mul_f32_e32 v38, v45, v51
	v_mul_f32_e32 v38, v38, v39
	v_cvt_pk_bf16_f32 v37, v37, v38
	v_mad_i64_i32 v[38:39], s[2:3], v192, s64, v[114:115]
	v_lshl_add_u64 v[38:39], v[38:39], 0, v[116:117]
	v_pk_mul_f32 v[30:31], v[30:31], v[134:135] op_sel_hi:[1,0]
	global_store_dwordx4 v[38:39], v[34:37], off
	v_pk_mul_f32 v[22:23], v[22:23], v[134:135] op_sel_hi:[1,0]
	v_pk_mul_f32 v[32:33], v[32:33], v[134:135] op_sel_hi:[1,0]
	v_pk_mul_f32 v[34:35], v[20:21], v[134:135] op_sel_hi:[1,0]
	v_pk_mul_f32 v[20:21], v[18:19], v[134:135] op_sel_hi:[1,0]
	v_mul_f32_e32 v19, 0xbfb8aa3b, v30
	v_mul_f32_e32 v18, v30, v22
	v_exp_f32_e32 v19, v19
	v_mul_f32_e32 v22, 0xbfb8aa3b, v31
	v_exp_f32_e32 v22, v22
	v_pk_mul_f32 v[24:25], v[24:25], v[134:135] op_sel_hi:[1,0]
	v_add_f32_e32 v19, 1.0, v19
	v_rcp_f32_e32 v19, v19
	v_add_f32_e32 v22, 1.0, v22
	v_rcp_f32_e32 v22, v22
	v_pk_mul_f32 v[26:27], v[26:27], v[134:135] op_sel_hi:[1,0]
	v_mul_f32_e32 v18, v18, v19
	v_mul_f32_e32 v19, v31, v23
	v_mul_f32_e32 v19, v19, v22
	v_mul_f32_e32 v22, 0xbfb8aa3b, v32
	v_exp_f32_e32 v22, v22
	v_mul_f32_e32 v23, 0xbfb8aa3b, v33
	v_exp_f32_e32 v23, v23
	v_cvt_pk_bf16_f32 v18, v18, v19
	v_add_f32_e32 v22, 1.0, v22
	v_rcp_f32_e32 v22, v22
	v_add_f32_e32 v23, 1.0, v23
	v_rcp_f32_e32 v23, v23
	v_mul_f32_e32 v19, v32, v24
	v_mul_f32_e32 v19, v19, v22
	v_mul_f32_e32 v22, v33, v25
	v_mul_f32_e32 v22, v22, v23
	v_cvt_pk_bf16_f32 v19, v19, v22
	v_mul_f32_e32 v22, 0xbfb8aa3b, v26
	v_exp_f32_e32 v22, v22
	v_mul_f32_e32 v20, v26, v20
	v_pk_mul_f32 v[28:29], v[28:29], v[134:135] op_sel_hi:[1,0]
	v_mul_f32_e32 v21, v27, v21
	v_add_f32_e32 v22, 1.0, v22
	v_rcp_f32_e32 v22, v22
	v_mul_f32_e32 v23, 0xbfb8aa3b, v29
	v_exp_f32_e32 v23, v23
	v_mul_f32_e32 v20, v20, v22
	v_mul_f32_e32 v22, 0xbfb8aa3b, v27
	v_exp_f32_e32 v22, v22
	v_add_f32_e32 v23, 1.0, v23
	v_rcp_f32_e32 v23, v23
	v_add_f32_e32 v22, 1.0, v22
	v_rcp_f32_e32 v22, v22
	v_rsq_f32_e32 v131, v130
	s_nop 0
	v_mul_f32_e32 v130, v130, v131
	v_fma_f32 v130, -v130, v131, 1.0
	v_mul_f32_e32 v130, 0.5, v130
	v_fma_f32 v130, v131, v130, v131
	v_pk_mul_f32 v[14:15], v[14:15], v[130:131] op_sel_hi:[1,0]
	v_pk_mul_f32 v[6:7], v[6:7], v[130:131] op_sel_hi:[1,0]
	v_mul_f32_e32 v21, v21, v22
	v_mul_f32_e32 v22, 0xbfb8aa3b, v28
	v_exp_f32_e32 v22, v22
	v_cvt_pk_bf16_f32 v20, v20, v21
	v_mul_f32_e32 v21, v28, v34
	v_pk_mul_f32 v[16:17], v[16:17], v[130:131] op_sel_hi:[1,0]
	v_add_f32_e32 v22, 1.0, v22
	v_rcp_f32_e32 v22, v22
	v_pk_mul_f32 v[8:9], v[8:9], v[130:131] op_sel_hi:[1,0]
	v_pk_mul_f32 v[10:11], v[10:11], v[130:131] op_sel_hi:[1,0]
	v_pk_mul_f32 v[12:13], v[12:13], v[130:131] op_sel_hi:[1,0]
	v_mul_f32_e32 v21, v21, v22
	v_mul_f32_e32 v22, v29, v35
	v_mul_f32_e32 v22, v22, v23
	v_cvt_pk_bf16_f32 v21, v21, v22
	v_mad_i64_i32 v[22:23], s[2:3], v190, s64, v[114:115]
	v_lshl_add_u64 v[22:23], v[22:23], 0, v[116:117]
	global_store_dwordx4 v[22:23], v[18:21], off
	s_andn2_b64 vcc, exec, s[4:5]
	s_nop 0
	v_pk_mul_f32 v[18:19], v[4:5], v[130:131] op_sel_hi:[1,0]
	v_pk_mul_f32 v[4:5], v[2:3], v[130:131] op_sel_hi:[1,0]
	v_mul_f32_e32 v3, 0xbfb8aa3b, v14
	v_mul_f32_e32 v2, v14, v6
	v_exp_f32_e32 v3, v3
	v_mul_f32_e32 v6, 0xbfb8aa3b, v15
	v_exp_f32_e32 v6, v6
	v_mul_f32_e32 v4, v10, v4
	v_add_f32_e32 v3, 1.0, v3
	v_rcp_f32_e32 v3, v3
	v_add_f32_e32 v6, 1.0, v6
	v_rcp_f32_e32 v6, v6
	v_mul_f32_e32 v5, v11, v5
	v_mul_f32_e32 v2, v2, v3
	v_mul_f32_e32 v3, v15, v7
	v_mul_f32_e32 v3, v3, v6
	v_mul_f32_e32 v6, 0xbfb8aa3b, v16
	v_exp_f32_e32 v6, v6
	v_mul_f32_e32 v7, 0xbfb8aa3b, v17
	v_exp_f32_e32 v7, v7
	v_cvt_pk_bf16_f32 v2, v2, v3
	v_add_f32_e32 v6, 1.0, v6
	v_rcp_f32_e32 v6, v6
	v_add_f32_e32 v7, 1.0, v7
	v_rcp_f32_e32 v7, v7
	v_mul_f32_e32 v3, v16, v8
	v_mul_f32_e32 v3, v3, v6
	v_mul_f32_e32 v6, v17, v9
	v_mul_f32_e32 v6, v6, v7
	v_cvt_pk_bf16_f32 v3, v3, v6
	v_mul_f32_e32 v6, 0xbfb8aa3b, v10
	v_exp_f32_e32 v6, v6
	v_mul_f32_e32 v7, 0xbfb8aa3b, v13
	v_exp_f32_e32 v7, v7
	v_add_f32_e32 v6, 1.0, v6
	v_rcp_f32_e32 v6, v6
	v_add_f32_e32 v7, 1.0, v7
	v_rcp_f32_e32 v7, v7
	v_mul_f32_e32 v4, v4, v6
	v_mul_f32_e32 v6, 0xbfb8aa3b, v11
	v_exp_f32_e32 v6, v6
	s_nop 0
	v_add_f32_e32 v6, 1.0, v6
	v_rcp_f32_e32 v6, v6
	s_nop 0
	v_mul_f32_e32 v5, v5, v6
	v_mul_f32_e32 v6, 0xbfb8aa3b, v12
	v_exp_f32_e32 v6, v6
	v_cvt_pk_bf16_f32 v4, v4, v5
	v_mul_f32_e32 v5, v12, v18
	v_add_f32_e32 v6, 1.0, v6
	v_rcp_f32_e32 v6, v6
	s_nop 0
	v_mul_f32_e32 v5, v5, v6
	v_mul_f32_e32 v6, v13, v19
	v_mul_f32_e32 v6, v6, v7
	v_cvt_pk_bf16_f32 v5, v5, v6
	v_mad_i64_i32 v[6:7], s[2:3], v188, s64, v[114:115]
	v_lshl_add_u64 v[6:7], v[6:7], 0, v[116:117]
	s_mov_b64 s[2:3], -1
	global_store_dwordx4 v[6:7], v[2:5], off
	s_cbranch_vccnz .LBB0_382
	s_andn2_b64 vcc, exec, s[8:9]
	s_cbranch_vccnz .LBB0_381
	s_barrier
	s_branch .LBB0_381

.LBB0_468:
	v_lshl_add_u32 v158, s49, 8, v162
	v_lshl_or_b32 v159, s47, 8, v164
	v_lshlrev_b32_e32 v160, 2, v159
	v_lshl_add_u32 v156, v158, 12, v160
	global_load_dwordx4 v[54:57], v160, s[16:17]
	global_load_dwordx4 v[50:53], v160, s[16:17] offset:16
	global_load_dwordx4 v[30:33], v160, s[16:17] offset:512
	global_load_dwordx4 v[26:29], v160, s[16:17] offset:528
	global_load_dwordx4 v[188:191], v156, s[0:1]
	global_load_dwordx4 v[192:195], v156, s[0:1] offset:16
	global_load_dwordx4 v[196:199], v156, s[0:1] offset:512
	global_load_dwordx4 v[200:203], v156, s[0:1] offset:528
	v_add_u32_e32 v157, 0x10000, v156
	global_load_dwordx4 v[204:207], v157, s[0:1]
	global_load_dwordx4 v[208:211], v157, s[0:1] offset:16
	global_load_dwordx4 v[212:215], v157, s[0:1] offset:512
	global_load_dwordx4 v[216:219], v157, s[0:1] offset:528
	s_lshl_b32 s24, s47, 2
	s_add_i32 s24, s24, s41
	s_lshl_b32 s24, s24, 2
	v_lshlrev_b32_e32 v174, 6, v158
	v_add_u32_e32 v174, s24, v174
	v_mbcnt_hi_u32_b32 v166, -1, v253
	v_xor_b32_e32 v167, 32, v166
	v_xor_b32_e32 v166, 16, v166
	v_lshlrev_b32_e32 v166, 2, v166
	v_lshlrev_b32_e32 v167, 2, v167
	s_waitcnt vmcnt(4)
	v_pk_fma_f32 v[142:143], v[142:143], 0.5, v[188:189] op_sel_hi:[1,0,1]
	v_pk_fma_f32 v[144:145], v[144:145], 0.5, v[190:191] op_sel_hi:[1,0,1]
	v_pk_fma_f32 v[138:139], v[138:139], 0.5, v[192:193] op_sel_hi:[1,0,1]
	v_pk_fma_f32 v[140:141], v[140:141], 0.5, v[194:195] op_sel_hi:[1,0,1]
	v_pk_fma_f32 v[134:135], v[134:135], 0.5, v[196:197] op_sel_hi:[1,0,1]
	v_pk_fma_f32 v[136:137], v[136:137], 0.5, v[198:199] op_sel_hi:[1,0,1]
	v_pk_fma_f32 v[130:131], v[130:131], 0.5, v[200:201] op_sel_hi:[1,0,1]
	v_pk_fma_f32 v[132:133], v[132:133], 0.5, v[202:203] op_sel_hi:[1,0,1]
	v_add_u32_e32 v157, 0x20000, v156
	global_load_dwordx4 v[188:191], v157, s[0:1]
	global_load_dwordx4 v[192:195], v157, s[0:1] offset:16
	global_load_dwordx4 v[196:199], v157, s[0:1] offset:512
	global_load_dwordx4 v[200:203], v157, s[0:1] offset:528
	v_mov_b32_e32 v159, v156
	global_store_dwordx4 v159, v[142:145], s[12:13]
	global_store_dwordx4 v159, v[138:141], s[12:13] offset:16
	global_store_dwordx4 v159, v[134:137], s[12:13] offset:512
	global_store_dwordx4 v159, v[130:133], s[12:13] offset:528
	v_mul_f32_e32 v169, v145, v145
	v_mul_f32_e32 v168, v143, v143
	v_fmac_f32_e32 v168, v142, v142
	v_fmac_f32_e32 v169, v144, v144
	v_add_f32_e32 v168, v168, v169
	v_mul_f32_e32 v169, v139, v139
	v_fmac_f32_e32 v169, v138, v138
	v_add_f32_e32 v168, v169, v168
	v_mul_f32_e32 v169, v141, v141
	v_fmac_f32_e32 v169, v140, v140
	v_add_f32_e32 v170, v169, v168
	v_mul_f32_e32 v169, v137, v137
	v_mul_f32_e32 v168, v135, v135
	v_fmac_f32_e32 v168, v134, v134
	v_fmac_f32_e32 v169, v136, v136
	v_add_f32_e32 v168, v168, v169
	v_mul_f32_e32 v169, v131, v131
	v_fmac_f32_e32 v169, v130, v130
	v_add_f32_e32 v168, v169, v168
	v_mul_f32_e32 v169, v133, v133
	v_fmac_f32_e32 v169, v132, v132
	v_add_f32_e32 v168, v169, v168
	v_add_f32_e32 v168, v170, v168
	ds_bpermute_b32 v169, v166, v168
	v_pk_mul_f32 v[142:143], v[54:55], v[142:143]
	v_pk_mul_f32 v[144:145], v[56:57], v[144:145]
	v_pk_mul_f32 v[138:139], v[50:51], v[138:139]
	v_pk_mul_f32 v[140:141], v[52:53], v[140:141]
	v_cvt_pk_bf16_f32 v142, v142, v143
	v_cvt_pk_bf16_f32 v143, v144, v145
	v_cvt_pk_bf16_f32 v144, v138, v139
	v_cvt_pk_bf16_f32 v145, v140, v141
	v_pk_mul_f32 v[134:135], v[30:31], v[134:135]
	v_pk_mul_f32 v[136:137], v[32:33], v[136:137]
	v_pk_mul_f32 v[130:131], v[26:27], v[130:131]
	v_pk_mul_f32 v[132:133], v[28:29], v[132:133]
	v_cvt_pk_bf16_f32 v134, v134, v135
	v_cvt_pk_bf16_f32 v135, v136, v137
	v_cvt_pk_bf16_f32 v136, v130, v131
	v_cvt_pk_bf16_f32 v137, v132, v133
	v_lshrrev_b32_e32 v160, 1, v159
	global_store_dwordx4 v160, v[142:145], s[18:19]
	global_store_dwordx4 v160, v[134:137], s[18:19] offset:256
	s_waitcnt lgkmcnt(0)
	v_add_f32_e32 v169, v168, v169
	ds_bpermute_b32 v170, v167, v169
	v_mov_b32_e32 v161, v174
	s_waitcnt lgkmcnt(0)
	v_add_f32_e32 v169, v169, v170
	s_and_saveexec_b64 s[2:3], s[6:7]
	global_store_dword v161, v169, s[14:15]
	s_or_b64 exec, exec, s[2:3]
	v_add_u32_e32 v157, 0x30000, v156
	global_load_dwordx4 v[142:145], v157, s[0:1]
	global_load_dwordx4 v[138:141], v157, s[0:1] offset:16
	global_load_dwordx4 v[134:137], v157, s[0:1] offset:512
	global_load_dwordx4 v[130:133], v157, s[0:1] offset:528
	s_waitcnt vmcnt(15)
	v_pk_fma_f32 v[126:127], v[126:127], 0.5, v[204:205] op_sel_hi:[1,0,1]
	v_pk_fma_f32 v[128:129], v[128:129], 0.5, v[206:207] op_sel_hi:[1,0,1]
	v_pk_fma_f32 v[122:123], v[122:123], 0.5, v[208:209] op_sel_hi:[1,0,1]
	v_pk_fma_f32 v[124:125], v[124:125], 0.5, v[210:211] op_sel_hi:[1,0,1]
	v_pk_fma_f32 v[118:119], v[118:119], 0.5, v[212:213] op_sel_hi:[1,0,1]
	v_pk_fma_f32 v[120:121], v[120:121], 0.5, v[214:215] op_sel_hi:[1,0,1]
	v_pk_fma_f32 v[114:115], v[114:115], 0.5, v[216:217] op_sel_hi:[1,0,1]
	v_pk_fma_f32 v[116:117], v[116:117], 0.5, v[218:219] op_sel_hi:[1,0,1]
	v_add_u32_e32 v157, 0x80000, v156
	global_load_dwordx4 v[204:207], v157, s[0:1]
	global_load_dwordx4 v[208:211], v157, s[0:1] offset:16
	global_load_dwordx4 v[212:215], v157, s[0:1] offset:512
	global_load_dwordx4 v[216:219], v157, s[0:1] offset:528
	v_add_u32_e32 v159, 0x10000, v156
	global_store_dwordx4 v159, v[126:129], s[12:13]
	global_store_dwordx4 v159, v[122:125], s[12:13] offset:16
	global_store_dwordx4 v159, v[118:121], s[12:13] offset:512
	global_store_dwordx4 v159, v[114:117], s[12:13] offset:528
	v_mul_f32_e32 v169, v129, v129
	v_mul_f32_e32 v168, v127, v127
	v_fmac_f32_e32 v168, v126, v126
	v_fmac_f32_e32 v169, v128, v128
	v_add_f32_e32 v168, v168, v169
	v_mul_f32_e32 v169, v123, v123
	v_fmac_f32_e32 v169, v122, v122
	v_add_f32_e32 v168, v169, v168
	v_mul_f32_e32 v169, v125, v125
	v_fmac_f32_e32 v169, v124, v124
	v_add_f32_e32 v170, v169, v168
	v_mul_f32_e32 v169, v121, v121
	v_mul_f32_e32 v168, v119, v119
	v_fmac_f32_e32 v168, v118, v118
	v_fmac_f32_e32 v169, v120, v120
	v_add_f32_e32 v168, v168, v169
	v_mul_f32_e32 v169, v115, v115
	v_fmac_f32_e32 v169, v114, v114
	v_add_f32_e32 v168, v169, v168
	v_mul_f32_e32 v169, v117, v117
	v_fmac_f32_e32 v169, v116, v116
	v_add_f32_e32 v168, v169, v168
	v_add_f32_e32 v168, v170, v168
	ds_bpermute_b32 v169, v166, v168
	v_pk_mul_f32 v[126:127], v[54:55], v[126:127]
	v_pk_mul_f32 v[128:129], v[56:57], v[128:129]
	v_pk_mul_f32 v[122:123], v[50:51], v[122:123]
	v_pk_mul_f32 v[124:125], v[52:53], v[124:125]
	v_cvt_pk_bf16_f32 v126, v126, v127
	v_cvt_pk_bf16_f32 v127, v128, v129
	v_cvt_pk_bf16_f32 v128, v122, v123
	v_cvt_pk_bf16_f32 v129, v124, v125
	v_pk_mul_f32 v[118:119], v[30:31], v[118:119]
	v_pk_mul_f32 v[120:121], v[32:33], v[120:121]
	v_pk_mul_f32 v[114:115], v[26:27], v[114:115]
	v_pk_mul_f32 v[116:117], v[28:29], v[116:117]
	v_cvt_pk_bf16_f32 v118, v118, v119
	v_cvt_pk_bf16_f32 v119, v120, v121
	v_cvt_pk_bf16_f32 v120, v114, v115
	v_cvt_pk_bf16_f32 v121, v116, v117
	v_lshrrev_b32_e32 v160, 1, v159
	global_store_dwordx4 v160, v[126:129], s[18:19]
	global_store_dwordx4 v160, v[118:121], s[18:19] offset:256
	s_waitcnt lgkmcnt(0)
	v_add_f32_e32 v169, v168, v169
	ds_bpermute_b32 v170, v167, v169
	v_add_u32_e32 v161, 0x400, v174
	s_waitcnt lgkmcnt(0)
	v_add_f32_e32 v169, v169, v170
	s_and_saveexec_b64 s[2:3], s[6:7]
	global_store_dword v161, v169, s[14:15]
	s_or_b64 exec, exec, s[2:3]
	v_add_u32_e32 v157, 0x90000, v156
	global_load_dwordx4 v[126:129], v157, s[0:1]
	global_load_dwordx4 v[122:125], v157, s[0:1] offset:16
	global_load_dwordx4 v[118:121], v157, s[0:1] offset:512
	global_load_dwordx4 v[114:117], v157, s[0:1] offset:528
	s_waitcnt vmcnt(26)
	v_pk_fma_f32 v[110:111], v[110:111], 0.5, v[188:189] op_sel_hi:[1,0,1]
	v_pk_fma_f32 v[112:113], v[112:113], 0.5, v[190:191] op_sel_hi:[1,0,1]
	v_pk_fma_f32 v[106:107], v[106:107], 0.5, v[192:193] op_sel_hi:[1,0,1]
	v_pk_fma_f32 v[108:109], v[108:109], 0.5, v[194:195] op_sel_hi:[1,0,1]
	v_pk_fma_f32 v[102:103], v[102:103], 0.5, v[196:197] op_sel_hi:[1,0,1]
	v_pk_fma_f32 v[104:105], v[104:105], 0.5, v[198:199] op_sel_hi:[1,0,1]
	v_pk_fma_f32 v[98:99], v[98:99], 0.5, v[200:201] op_sel_hi:[1,0,1]
	v_pk_fma_f32 v[100:101], v[100:101], 0.5, v[202:203] op_sel_hi:[1,0,1]
	v_add_u32_e32 v157, 0xa0000, v156
	global_load_dwordx4 v[188:191], v157, s[0:1]
	global_load_dwordx4 v[192:195], v157, s[0:1] offset:16
	global_load_dwordx4 v[196:199], v157, s[0:1] offset:512
	global_load_dwordx4 v[200:203], v157, s[0:1] offset:528
	v_add_u32_e32 v159, 0x20000, v156
	global_store_dwordx4 v159, v[110:113], s[12:13]
	global_store_dwordx4 v159, v[106:109], s[12:13] offset:16
	global_store_dwordx4 v159, v[102:105], s[12:13] offset:512
	global_store_dwordx4 v159, v[98:101], s[12:13] offset:528
	v_mul_f32_e32 v169, v113, v113
	v_mul_f32_e32 v168, v111, v111
	v_fmac_f32_e32 v168, v110, v110
	v_fmac_f32_e32 v169, v112, v112
	v_add_f32_e32 v168, v168, v169
	v_mul_f32_e32 v169, v107, v107
	v_fmac_f32_e32 v169, v106, v106
	v_add_f32_e32 v168, v169, v168
	v_mul_f32_e32 v169, v109, v109
	v_fmac_f32_e32 v169, v108, v108
	v_add_f32_e32 v170, v169, v168
	v_mul_f32_e32 v169, v105, v105
	v_mul_f32_e32 v168, v103, v103
	v_fmac_f32_e32 v168, v102, v102
	v_fmac_f32_e32 v169, v104, v104
	v_add_f32_e32 v168, v168, v169
	v_mul_f32_e32 v169, v99, v99
	v_fmac_f32_e32 v169, v98, v98
	v_add_f32_e32 v168, v169, v168
	v_mul_f32_e32 v169, v101, v101
	v_fmac_f32_e32 v169, v100, v100
	v_add_f32_e32 v168, v169, v168
	v_add_f32_e32 v168, v170, v168
	ds_bpermute_b32 v169, v166, v168
	v_pk_mul_f32 v[110:111], v[54:55], v[110:111]
	v_pk_mul_f32 v[112:113], v[56:57], v[112:113]
	v_pk_mul_f32 v[106:107], v[50:51], v[106:107]
	v_pk_mul_f32 v[108:109], v[52:53], v[108:109]
	v_cvt_pk_bf16_f32 v110, v110, v111
	v_cvt_pk_bf16_f32 v111, v112, v113
	v_cvt_pk_bf16_f32 v112, v106, v107
	v_cvt_pk_bf16_f32 v113, v108, v109
	v_pk_mul_f32 v[102:103], v[30:31], v[102:103]
	v_pk_mul_f32 v[104:105], v[32:33], v[104:105]
	v_pk_mul_f32 v[98:99], v[26:27], v[98:99]
	v_pk_mul_f32 v[100:101], v[28:29], v[100:101]
	v_cvt_pk_bf16_f32 v102, v102, v103
	v_cvt_pk_bf16_f32 v103, v104, v105
	v_cvt_pk_bf16_f32 v104, v98, v99
	v_cvt_pk_bf16_f32 v105, v100, v101
	v_lshrrev_b32_e32 v160, 1, v159
	global_store_dwordx4 v160, v[110:113], s[18:19]
	global_store_dwordx4 v160, v[102:105], s[18:19] offset:256
	s_waitcnt lgkmcnt(0)
	v_add_f32_e32 v169, v168, v169
	ds_bpermute_b32 v170, v167, v169
	v_add_u32_e32 v161, 0x800, v174
	s_waitcnt lgkmcnt(0)
	v_add_f32_e32 v169, v169, v170
	s_and_saveexec_b64 s[2:3], s[6:7]
	global_store_dword v161, v169, s[14:15]
	s_or_b64 exec, exec, s[2:3]
	v_add_u32_e32 v157, 0xb0000, v156
	global_load_dwordx4 v[110:113], v157, s[0:1]
	global_load_dwordx4 v[106:109], v157, s[0:1] offset:16
	global_load_dwordx4 v[102:105], v157, s[0:1] offset:512
	global_load_dwordx4 v[98:101], v157, s[0:1] offset:528
	s_waitcnt vmcnt(30)
	v_pk_fma_f32 v[94:95], v[94:95], 0.5, v[142:143] op_sel_hi:[1,0,1]
	v_pk_fma_f32 v[96:97], v[96:97], 0.5, v[144:145] op_sel_hi:[1,0,1]
	v_pk_fma_f32 v[90:91], v[90:91], 0.5, v[138:139] op_sel_hi:[1,0,1]
	v_pk_fma_f32 v[92:93], v[92:93], 0.5, v[140:141] op_sel_hi:[1,0,1]
	v_pk_fma_f32 v[86:87], v[86:87], 0.5, v[134:135] op_sel_hi:[1,0,1]
	v_pk_fma_f32 v[88:89], v[88:89], 0.5, v[136:137] op_sel_hi:[1,0,1]
	v_pk_fma_f32 v[82:83], v[82:83], 0.5, v[130:131] op_sel_hi:[1,0,1]
	v_pk_fma_f32 v[84:85], v[84:85], 0.5, v[132:133] op_sel_hi:[1,0,1]
	v_add_u32_e32 v159, 0x30000, v156
	global_store_dwordx4 v159, v[94:97], s[12:13]
	global_store_dwordx4 v159, v[90:93], s[12:13] offset:16
	global_store_dwordx4 v159, v[86:89], s[12:13] offset:512
	global_store_dwordx4 v159, v[82:85], s[12:13] offset:528
	v_mul_f32_e32 v169, v97, v97
	v_mul_f32_e32 v168, v95, v95
	v_fmac_f32_e32 v168, v94, v94
	v_fmac_f32_e32 v169, v96, v96
	v_add_f32_e32 v168, v168, v169
	v_mul_f32_e32 v169, v91, v91
	v_fmac_f32_e32 v169, v90, v90
	v_add_f32_e32 v168, v169, v168
	v_mul_f32_e32 v169, v93, v93
	v_fmac_f32_e32 v169, v92, v92
	v_add_f32_e32 v170, v169, v168
	v_mul_f32_e32 v169, v89, v89
	v_mul_f32_e32 v168, v87, v87
	v_fmac_f32_e32 v168, v86, v86
	v_fmac_f32_e32 v169, v88, v88
	v_add_f32_e32 v168, v168, v169
	v_mul_f32_e32 v169, v83, v83
	v_fmac_f32_e32 v169, v82, v82
	v_add_f32_e32 v168, v169, v168
	v_mul_f32_e32 v169, v85, v85
	v_fmac_f32_e32 v169, v84, v84
	v_add_f32_e32 v168, v169, v168
	v_add_f32_e32 v168, v170, v168
	ds_bpermute_b32 v169, v166, v168
	v_pk_mul_f32 v[94:95], v[54:55], v[94:95]
	v_pk_mul_f32 v[96:97], v[56:57], v[96:97]
	v_pk_mul_f32 v[90:91], v[50:51], v[90:91]
	v_pk_mul_f32 v[92:93], v[52:53], v[92:93]
	v_cvt_pk_bf16_f32 v94, v94, v95
	v_cvt_pk_bf16_f32 v95, v96, v97
	v_cvt_pk_bf16_f32 v96, v90, v91
	v_cvt_pk_bf16_f32 v97, v92, v93
	v_pk_mul_f32 v[86:87], v[30:31], v[86:87]
	v_pk_mul_f32 v[88:89], v[32:33], v[88:89]
	v_pk_mul_f32 v[82:83], v[26:27], v[82:83]
	v_pk_mul_f32 v[84:85], v[28:29], v[84:85]
	v_cvt_pk_bf16_f32 v86, v86, v87
	v_cvt_pk_bf16_f32 v87, v88, v89
	v_cvt_pk_bf16_f32 v88, v82, v83
	v_cvt_pk_bf16_f32 v89, v84, v85
	v_lshrrev_b32_e32 v160, 1, v159
	global_store_dwordx4 v160, v[94:97], s[18:19]
	global_store_dwordx4 v160, v[86:89], s[18:19] offset:256
	s_waitcnt lgkmcnt(0)
	v_add_f32_e32 v169, v168, v169
	ds_bpermute_b32 v170, v167, v169
	v_add_u32_e32 v161, 0xc00, v174
	s_waitcnt lgkmcnt(0)
	v_add_f32_e32 v169, v169, v170
	s_and_saveexec_b64 s[2:3], s[6:7]
	global_store_dword v161, v169, s[14:15]
	s_or_b64 exec, exec, s[2:3]
	s_waitcnt vmcnt(33)
	v_pk_fma_f32 v[78:79], v[78:79], 0.5, v[204:205] op_sel_hi:[1,0,1]
	v_pk_fma_f32 v[80:81], v[80:81], 0.5, v[206:207] op_sel_hi:[1,0,1]
	v_pk_fma_f32 v[74:75], v[74:75], 0.5, v[208:209] op_sel_hi:[1,0,1]
	v_pk_fma_f32 v[76:77], v[76:77], 0.5, v[210:211] op_sel_hi:[1,0,1]
	v_pk_fma_f32 v[70:71], v[70:71], 0.5, v[212:213] op_sel_hi:[1,0,1]
	v_pk_fma_f32 v[72:73], v[72:73], 0.5, v[214:215] op_sel_hi:[1,0,1]
	v_pk_fma_f32 v[66:67], v[66:67], 0.5, v[216:217] op_sel_hi:[1,0,1]
	v_pk_fma_f32 v[68:69], v[68:69], 0.5, v[218:219] op_sel_hi:[1,0,1]
	v_add_u32_e32 v159, 0x80000, v156
	global_store_dwordx4 v159, v[78:81], s[12:13]
	global_store_dwordx4 v159, v[74:77], s[12:13] offset:16
	global_store_dwordx4 v159, v[70:73], s[12:13] offset:512
	global_store_dwordx4 v159, v[66:69], s[12:13] offset:528
	v_mul_f32_e32 v169, v81, v81
	v_mul_f32_e32 v168, v79, v79
	v_fmac_f32_e32 v168, v78, v78
	v_fmac_f32_e32 v169, v80, v80
	v_add_f32_e32 v168, v168, v169
	v_mul_f32_e32 v169, v75, v75
	v_fmac_f32_e32 v169, v74, v74
	v_add_f32_e32 v168, v169, v168
	v_mul_f32_e32 v169, v77, v77
	v_fmac_f32_e32 v169, v76, v76
	v_add_f32_e32 v170, v169, v168
	v_mul_f32_e32 v169, v73, v73
	v_mul_f32_e32 v168, v71, v71
	v_fmac_f32_e32 v168, v70, v70
	v_fmac_f32_e32 v169, v72, v72
	v_add_f32_e32 v168, v168, v169
	v_mul_f32_e32 v169, v67, v67
	v_fmac_f32_e32 v169, v66, v66
	v_add_f32_e32 v168, v169, v168
	v_mul_f32_e32 v169, v69, v69
	v_fmac_f32_e32 v169, v68, v68
	v_add_f32_e32 v168, v169, v168
	v_add_f32_e32 v168, v170, v168
	ds_bpermute_b32 v169, v166, v168
	v_pk_mul_f32 v[78:79], v[54:55], v[78:79]
	v_pk_mul_f32 v[80:81], v[56:57], v[80:81]
	v_pk_mul_f32 v[74:75], v[50:51], v[74:75]
	v_pk_mul_f32 v[76:77], v[52:53], v[76:77]
	v_cvt_pk_bf16_f32 v78, v78, v79
	v_cvt_pk_bf16_f32 v79, v80, v81
	v_cvt_pk_bf16_f32 v80, v74, v75
	v_cvt_pk_bf16_f32 v81, v76, v77
	v_pk_mul_f32 v[70:71], v[30:31], v[70:71]
	v_pk_mul_f32 v[72:73], v[32:33], v[72:73]
	v_pk_mul_f32 v[66:67], v[26:27], v[66:67]
	v_pk_mul_f32 v[68:69], v[28:29], v[68:69]
	v_cvt_pk_bf16_f32 v70, v70, v71
	v_cvt_pk_bf16_f32 v71, v72, v73
	v_cvt_pk_bf16_f32 v72, v66, v67
	v_cvt_pk_bf16_f32 v73, v68, v69
	v_lshrrev_b32_e32 v160, 1, v159
	global_store_dwordx4 v160, v[78:81], s[18:19]
	global_store_dwordx4 v160, v[70:73], s[18:19] offset:256
	s_waitcnt lgkmcnt(0)
	v_add_f32_e32 v169, v168, v169
	ds_bpermute_b32 v170, v167, v169
	v_add_u32_e32 v161, 0x2000, v174
	s_waitcnt lgkmcnt(0)
	v_add_f32_e32 v169, v169, v170
	s_and_saveexec_b64 s[2:3], s[6:7]
	global_store_dword v161, v169, s[14:15]
	s_or_b64 exec, exec, s[2:3]
	s_waitcnt vmcnt(29)
	v_pk_fma_f32 v[62:63], v[62:63], 0.5, v[126:127] op_sel_hi:[1,0,1]
	v_pk_fma_f32 v[64:65], v[64:65], 0.5, v[128:129] op_sel_hi:[1,0,1]
	v_pk_fma_f32 v[58:59], v[58:59], 0.5, v[122:123] op_sel_hi:[1,0,1]
	v_pk_fma_f32 v[60:61], v[60:61], 0.5, v[124:125] op_sel_hi:[1,0,1]
	v_pk_fma_f32 v[46:47], v[46:47], 0.5, v[118:119] op_sel_hi:[1,0,1]
	v_pk_fma_f32 v[48:49], v[48:49], 0.5, v[120:121] op_sel_hi:[1,0,1]
	v_pk_fma_f32 v[42:43], v[42:43], 0.5, v[114:115] op_sel_hi:[1,0,1]
	v_pk_fma_f32 v[44:45], v[44:45], 0.5, v[116:117] op_sel_hi:[1,0,1]
	v_add_u32_e32 v159, 0x90000, v156
	global_store_dwordx4 v159, v[62:65], s[12:13]
	global_store_dwordx4 v159, v[58:61], s[12:13] offset:16
	global_store_dwordx4 v159, v[46:49], s[12:13] offset:512
	global_store_dwordx4 v159, v[42:45], s[12:13] offset:528
	v_mul_f32_e32 v169, v65, v65
	v_mul_f32_e32 v168, v63, v63
	v_fmac_f32_e32 v168, v62, v62
	v_fmac_f32_e32 v169, v64, v64
	v_add_f32_e32 v168, v168, v169
	v_mul_f32_e32 v169, v59, v59
	v_fmac_f32_e32 v169, v58, v58
	v_add_f32_e32 v168, v169, v168
	v_mul_f32_e32 v169, v61, v61
	v_fmac_f32_e32 v169, v60, v60
	v_add_f32_e32 v170, v169, v168
	v_mul_f32_e32 v169, v49, v49
	v_mul_f32_e32 v168, v47, v47
	v_fmac_f32_e32 v168, v46, v46
	v_fmac_f32_e32 v169, v48, v48
	v_add_f32_e32 v168, v168, v169
	v_mul_f32_e32 v169, v43, v43
	v_fmac_f32_e32 v169, v42, v42
	v_add_f32_e32 v168, v169, v168
	v_mul_f32_e32 v169, v45, v45
	v_fmac_f32_e32 v169, v44, v44
	v_add_f32_e32 v168, v169, v168
	v_add_f32_e32 v168, v170, v168
	ds_bpermute_b32 v169, v166, v168
	v_pk_mul_f32 v[62:63], v[54:55], v[62:63]
	v_pk_mul_f32 v[64:65], v[56:57], v[64:65]
	v_pk_mul_f32 v[58:59], v[50:51], v[58:59]
	v_pk_mul_f32 v[60:61], v[52:53], v[60:61]
	v_cvt_pk_bf16_f32 v62, v62, v63
	v_cvt_pk_bf16_f32 v63, v64, v65
	v_cvt_pk_bf16_f32 v64, v58, v59
	v_cvt_pk_bf16_f32 v65, v60, v61
	v_pk_mul_f32 v[46:47], v[30:31], v[46:47]
	v_pk_mul_f32 v[48:49], v[32:33], v[48:49]
	v_pk_mul_f32 v[42:43], v[26:27], v[42:43]
	v_pk_mul_f32 v[44:45], v[28:29], v[44:45]
	v_cvt_pk_bf16_f32 v46, v46, v47
	v_cvt_pk_bf16_f32 v47, v48, v49
	v_cvt_pk_bf16_f32 v48, v42, v43
	v_cvt_pk_bf16_f32 v49, v44, v45
	v_lshrrev_b32_e32 v160, 1, v159
	global_store_dwordx4 v160, v[62:65], s[18:19]
	global_store_dwordx4 v160, v[46:49], s[18:19] offset:256
	s_waitcnt lgkmcnt(0)
	v_add_f32_e32 v169, v168, v169
	ds_bpermute_b32 v170, v167, v169
	v_add_u32_e32 v161, 0x2400, v174
	s_waitcnt lgkmcnt(0)
	v_add_f32_e32 v169, v169, v170
	s_and_saveexec_b64 s[2:3], s[6:7]
	global_store_dword v161, v169, s[14:15]
	s_or_b64 exec, exec, s[2:3]
	s_waitcnt vmcnt(32)
	v_pk_fma_f32 v[38:39], v[38:39], 0.5, v[188:189] op_sel_hi:[1,0,1]
	v_pk_fma_f32 v[40:41], v[40:41], 0.5, v[190:191] op_sel_hi:[1,0,1]
	v_pk_fma_f32 v[34:35], v[34:35], 0.5, v[192:193] op_sel_hi:[1,0,1]
	v_pk_fma_f32 v[36:37], v[36:37], 0.5, v[194:195] op_sel_hi:[1,0,1]
	v_pk_fma_f32 v[22:23], v[22:23], 0.5, v[196:197] op_sel_hi:[1,0,1]
	v_pk_fma_f32 v[24:25], v[24:25], 0.5, v[198:199] op_sel_hi:[1,0,1]
	v_pk_fma_f32 v[18:19], v[18:19], 0.5, v[200:201] op_sel_hi:[1,0,1]
	v_pk_fma_f32 v[20:21], v[20:21], 0.5, v[202:203] op_sel_hi:[1,0,1]
	v_add_u32_e32 v159, 0xa0000, v156
	global_store_dwordx4 v159, v[38:41], s[12:13]
	global_store_dwordx4 v159, v[34:37], s[12:13] offset:16
	global_store_dwordx4 v159, v[22:25], s[12:13] offset:512
	global_store_dwordx4 v159, v[18:21], s[12:13] offset:528
	v_mul_f32_e32 v169, v41, v41
	v_mul_f32_e32 v168, v39, v39
	v_fmac_f32_e32 v168, v38, v38
	v_fmac_f32_e32 v169, v40, v40
	v_add_f32_e32 v168, v168, v169
	v_mul_f32_e32 v169, v35, v35
	v_fmac_f32_e32 v169, v34, v34
	v_add_f32_e32 v168, v169, v168
	v_mul_f32_e32 v169, v37, v37
	v_fmac_f32_e32 v169, v36, v36
	v_add_f32_e32 v170, v169, v168
	v_mul_f32_e32 v169, v25, v25
	v_mul_f32_e32 v168, v23, v23
	v_fmac_f32_e32 v168, v22, v22
	v_fmac_f32_e32 v169, v24, v24
	v_add_f32_e32 v168, v168, v169
	v_mul_f32_e32 v169, v19, v19
	v_fmac_f32_e32 v169, v18, v18
	v_add_f32_e32 v168, v169, v168
	v_mul_f32_e32 v169, v21, v21
	v_fmac_f32_e32 v169, v20, v20
	v_add_f32_e32 v168, v169, v168
	v_add_f32_e32 v168, v170, v168
	ds_bpermute_b32 v169, v166, v168
	v_pk_mul_f32 v[38:39], v[54:55], v[38:39]
	v_pk_mul_f32 v[40:41], v[56:57], v[40:41]
	v_pk_mul_f32 v[34:35], v[50:51], v[34:35]
	v_pk_mul_f32 v[36:37], v[52:53], v[36:37]
	v_cvt_pk_bf16_f32 v38, v38, v39
	v_cvt_pk_bf16_f32 v39, v40, v41
	v_cvt_pk_bf16_f32 v40, v34, v35
	v_cvt_pk_bf16_f32 v41, v36, v37
	v_pk_mul_f32 v[22:23], v[30:31], v[22:23]
	v_pk_mul_f32 v[24:25], v[32:33], v[24:25]
	v_pk_mul_f32 v[18:19], v[26:27], v[18:19]
	v_pk_mul_f32 v[20:21], v[28:29], v[20:21]
	v_cvt_pk_bf16_f32 v22, v22, v23
	v_cvt_pk_bf16_f32 v23, v24, v25
	v_cvt_pk_bf16_f32 v24, v18, v19
	v_cvt_pk_bf16_f32 v25, v20, v21
	v_lshrrev_b32_e32 v160, 1, v159
	global_store_dwordx4 v160, v[38:41], s[18:19]
	global_store_dwordx4 v160, v[22:25], s[18:19] offset:256
	s_waitcnt lgkmcnt(0)
	v_add_f32_e32 v169, v168, v169
	ds_bpermute_b32 v170, v167, v169
	v_add_u32_e32 v161, 0x2800, v174
	s_waitcnt lgkmcnt(0)
	v_add_f32_e32 v169, v169, v170
	s_and_saveexec_b64 s[2:3], s[6:7]
	global_store_dword v161, v169, s[14:15]
	s_or_b64 exec, exec, s[2:3]
	s_waitcnt vmcnt(28)
	v_pk_fma_f32 v[14:15], v[14:15], 0.5, v[110:111] op_sel_hi:[1,0,1]
	v_pk_fma_f32 v[16:17], v[16:17], 0.5, v[112:113] op_sel_hi:[1,0,1]
	v_pk_fma_f32 v[10:11], v[10:11], 0.5, v[106:107] op_sel_hi:[1,0,1]
	v_pk_fma_f32 v[12:13], v[12:13], 0.5, v[108:109] op_sel_hi:[1,0,1]
	v_pk_fma_f32 v[6:7], v[6:7], 0.5, v[102:103] op_sel_hi:[1,0,1]
	v_pk_fma_f32 v[8:9], v[8:9], 0.5, v[104:105] op_sel_hi:[1,0,1]
	v_pk_fma_f32 v[2:3], v[2:3], 0.5, v[98:99] op_sel_hi:[1,0,1]
	v_pk_fma_f32 v[4:5], v[4:5], 0.5, v[100:101] op_sel_hi:[1,0,1]
	v_add_u32_e32 v159, 0xb0000, v156
	global_store_dwordx4 v159, v[14:17], s[12:13]
	global_store_dwordx4 v159, v[10:13], s[12:13] offset:16
	global_store_dwordx4 v159, v[6:9], s[12:13] offset:512
	global_store_dwordx4 v159, v[2:5], s[12:13] offset:528
	v_mul_f32_e32 v169, v17, v17
	v_mul_f32_e32 v168, v15, v15
	v_fmac_f32_e32 v168, v14, v14
	v_fmac_f32_e32 v169, v16, v16
	v_add_f32_e32 v168, v168, v169
	v_mul_f32_e32 v169, v11, v11
	v_fmac_f32_e32 v169, v10, v10
	v_add_f32_e32 v168, v169, v168
	v_mul_f32_e32 v169, v13, v13
	v_fmac_f32_e32 v169, v12, v12
	v_add_f32_e32 v170, v169, v168
	v_mul_f32_e32 v169, v9, v9
	v_mul_f32_e32 v168, v7, v7
	v_fmac_f32_e32 v168, v6, v6
	v_fmac_f32_e32 v169, v8, v8
	v_add_f32_e32 v168, v168, v169
	v_mul_f32_e32 v169, v3, v3
	v_fmac_f32_e32 v169, v2, v2
	v_add_f32_e32 v168, v169, v168
	v_mul_f32_e32 v169, v5, v5
	v_fmac_f32_e32 v169, v4, v4
	v_add_f32_e32 v168, v169, v168
	v_add_f32_e32 v168, v170, v168
	ds_bpermute_b32 v169, v166, v168
	v_pk_mul_f32 v[14:15], v[54:55], v[14:15]
	v_pk_mul_f32 v[16:17], v[56:57], v[16:17]
	v_pk_mul_f32 v[10:11], v[50:51], v[10:11]
	v_pk_mul_f32 v[12:13], v[52:53], v[12:13]
	v_cvt_pk_bf16_f32 v14, v14, v15
	v_cvt_pk_bf16_f32 v15, v16, v17
	v_cvt_pk_bf16_f32 v16, v10, v11
	v_cvt_pk_bf16_f32 v17, v12, v13
	v_pk_mul_f32 v[6:7], v[30:31], v[6:7]
	v_pk_mul_f32 v[8:9], v[32:33], v[8:9]
	v_pk_mul_f32 v[2:3], v[26:27], v[2:3]
	v_pk_mul_f32 v[4:5], v[28:29], v[4:5]
	v_cvt_pk_bf16_f32 v6, v6, v7
	v_cvt_pk_bf16_f32 v7, v8, v9
	v_cvt_pk_bf16_f32 v8, v2, v3
	v_cvt_pk_bf16_f32 v9, v4, v5
	v_lshrrev_b32_e32 v160, 1, v159
	global_store_dwordx4 v160, v[14:17], s[18:19]
	global_store_dwordx4 v160, v[6:9], s[18:19] offset:256
	s_waitcnt lgkmcnt(0)
	v_add_f32_e32 v169, v168, v169
	ds_bpermute_b32 v170, v167, v169
	v_add_u32_e32 v161, 0x2c00, v174
	s_waitcnt lgkmcnt(0)
	v_add_f32_e32 v169, v169, v170
	s_and_saveexec_b64 s[2:3], s[6:7]
	global_store_dword v161, v169, s[14:15]
	s_or_b64 exec, exec, s[2:3]
	s_and_b64 vcc, exec, s[8:9]
	s_mov_b64 s[2:3], -1
	s_cbranch_vccnz .LBB0_453
	s_andn2_b64 vcc, exec, s[4:5]
	s_cbranch_vccnz .LBB0_452
	s_barrier
	s_branch .LBB0_452

.LBB0_552:
	v_lshl_add_u32 v218, s41, 8, v173
	v_ashrrev_i32_e32 v219, 31, v218
	v_lshlrev_b64 v[216:217], 6, v[218:219]
	v_lshl_add_u64 v[130:131], v[166:167], 0, v[216:217]
	global_load_dwordx4 v[174:177], v[130:131], off
	v_or_b32_e32 v214, 16, v218
	v_ashrrev_i32_e32 v215, 31, v214
	v_or_b32_e32 v210, 32, v218
	v_lshlrev_b64 v[212:213], 6, v[214:215]
	v_ashrrev_i32_e32 v211, 31, v210
	v_or_b32_e32 v206, 48, v218
	v_lshl_add_u64 v[130:131], v[166:167], 0, v[212:213]
	v_lshlrev_b64 v[208:209], 6, v[210:211]
	v_ashrrev_i32_e32 v207, 31, v206
	v_add_u32_e32 v202, 0x80, v218
	global_load_dwordx4 v[154:157], v[130:131], off
	v_lshl_add_u64 v[130:131], v[166:167], 0, v[208:209]
	v_lshlrev_b64 v[204:205], 6, v[206:207]
	v_ashrrev_i32_e32 v203, 31, v202
	v_add_u32_e32 v198, 0x90, v218
	global_load_dwordx4 v[150:153], v[130:131], off
	v_lshl_add_u64 v[130:131], v[166:167], 0, v[204:205]
	v_lshlrev_b64 v[200:201], 6, v[202:203]
	v_ashrrev_i32_e32 v199, 31, v198
	v_add_u32_e32 v194, 0xa0, v218
	global_load_dwordx4 v[146:149], v[130:131], off
	v_lshl_add_u64 v[130:131], v[166:167], 0, v[200:201]
	v_lshlrev_b64 v[196:197], 6, v[198:199]
	v_ashrrev_i32_e32 v195, 31, v194
	v_add_u32_e32 v190, 0xb0, v218
	global_load_dwordx4 v[142:145], v[130:131], off
	v_lshl_add_u64 v[130:131], v[166:167], 0, v[196:197]
	v_lshlrev_b64 v[192:193], 6, v[194:195]
	v_ashrrev_i32_e32 v191, 31, v190
	global_load_dwordx4 v[138:141], v[130:131], off
	v_lshl_add_u64 v[130:131], v[166:167], 0, v[192:193]
	v_lshlrev_b64 v[188:189], 6, v[190:191]
	global_load_dwordx4 v[134:137], v[130:131], off
	v_lshl_add_u64 v[130:131], v[166:167], 0, v[188:189]
	global_load_dwordx4 v[130:133], v[130:131], off
	v_mbcnt_hi_u32_b32 v170, -1, v253
	v_and_b32_e32 v191, 64, v170
	v_xor_b32_e32 v187, 16, v170
	v_add_u32_e32 v191, 64, v191
	v_cmp_lt_i32_e32 vcc, v187, v191
	v_xor_b32_e32 v195, 32, v170
	s_cmp_eq_u32 s40, 10
	v_cndmask_b32_e32 v187, v170, v187, vcc
	v_cmp_lt_i32_e32 vcc, v195, v191
	v_lshlrev_b32_e32 v187, 2, v187
	s_cselect_b64 s[10:11], -1, 0
	v_cndmask_b32_e32 v170, v170, v195, vcc
	v_lshlrev_b32_e32 v191, 2, v170
	s_and_b64 s[22:23], s[12:13], s[10:11]
	v_lshl_or_b32 v186, s40, 8, v225
	s_and_b64 s[22:23], s[22:23], s[6:7]
	s_waitcnt vmcnt(0)
	v_mov_b32_e32 v238, v175
	v_mov_b32_e32 v239, v176
	v_mov_b32_e32 v175, v177
	v_pk_add_f32 v[174:175], v[238:239], v[174:175]
	v_add_f32_e32 v154, v154, v155
	v_add_f32_e32 v170, v174, v175
	ds_bpermute_b32 v174, v187, v170
	v_add_f32_e32 v155, v156, v157
	v_add_f32_e32 v154, v154, v155
	v_add_f32_e32 v150, v150, v151
	v_add_f32_e32 v151, v152, v153
	s_waitcnt lgkmcnt(0)
	v_add_f32_e32 v170, v170, v174
	ds_bpermute_b32 v174, v191, v170
	v_add_f32_e32 v150, v150, v151
	v_add_f32_e32 v146, v146, v147
	v_add_f32_e32 v147, v148, v149
	v_add_f32_e32 v146, v146, v147
	s_waitcnt lgkmcnt(0)
	v_add_f32_e32 v170, v170, v174
	v_fmamk_f32 v170, v170, 0x3a800000, v223
	v_add_f32_e32 v142, v142, v143
	v_add_f32_e32 v143, v144, v145
	v_add_f32_e32 v138, v138, v139
	v_add_f32_e32 v139, v140, v141
	v_add_f32_e32 v134, v134, v135
	v_add_f32_e32 v135, v136, v137
	v_add_f32_e32 v130, v130, v131
	v_add_f32_e32 v131, v132, v133
	v_add_f32_e32 v142, v142, v143
	v_add_f32_e32 v138, v138, v139
	v_add_f32_e32 v134, v134, v135
	v_add_f32_e32 v130, v130, v131
	ds_bpermute_b32 v155, v187, v154
	ds_bpermute_b32 v151, v187, v150
	ds_bpermute_b32 v147, v187, v146
	ds_bpermute_b32 v143, v187, v142
	ds_bpermute_b32 v139, v187, v138
	ds_bpermute_b32 v135, v187, v134
	ds_bpermute_b32 v131, v187, v130
	s_waitcnt lgkmcnt(6)
	v_add_f32_e32 v154, v154, v155
	s_waitcnt lgkmcnt(5)
	v_add_f32_e32 v150, v150, v151
	s_waitcnt lgkmcnt(4)
	v_add_f32_e32 v146, v146, v147
	s_waitcnt lgkmcnt(3)
	v_add_f32_e32 v142, v142, v143
	s_waitcnt lgkmcnt(2)
	v_add_f32_e32 v138, v138, v139
	s_waitcnt lgkmcnt(1)
	v_add_f32_e32 v134, v134, v135
	s_waitcnt lgkmcnt(0)
	v_add_f32_e32 v130, v130, v131
	v_rsq_f32_e32 v174, v170
	s_nop 0
	v_mul_f32_e32 v170, v170, v174
	v_fma_f32 v170, -v170, v174, 1.0
	v_mul_f32_e32 v170, 0.5, v170
	v_fma_f32 v170, v174, v170, v174
	ds_bpermute_b32 v155, v191, v154
	ds_bpermute_b32 v151, v191, v150
	ds_bpermute_b32 v147, v191, v146
	ds_bpermute_b32 v143, v191, v142
	ds_bpermute_b32 v139, v191, v138
	ds_bpermute_b32 v135, v191, v134
	ds_bpermute_b32 v131, v191, v130
	v_pk_mul_f32 v[126:127], v[126:127], v[170:171] op_sel_hi:[1,0]
	v_pk_mul_f32 v[132:133], v[124:125], v[170:171] op_sel_hi:[1,0]
	v_pk_mul_f32 v[124:125], v[122:123], v[170:171] op_sel_hi:[1,0]
	v_cvt_pk_bf16_f32 v122, v126, v127
	v_mov_b64_e32 v[126:127], s[2:3]
	v_ashrrev_i32_e32 v187, 31, v186
	v_mad_i64_i32 v[126:127], s[10:11], v218, s64, v[126:127]
	v_pk_mul_f32 v[128:129], v[128:129], v[170:171] op_sel_hi:[1,0]
	v_lshl_add_u64 v[126:127], v[186:187], 1, v[126:127]
	v_cvt_pk_bf16_f32 v123, v128, v129
	v_cvt_pk_bf16_f32 v124, v124, v125
	v_cvt_pk_bf16_f32 v125, v132, v133
	v_pk_mul_f32 v[120:121], v[120:121], v[170:171] op_sel_hi:[1,0]
	v_pk_mul_f32 v[118:119], v[118:119], v[170:171] op_sel_hi:[1,0]
	v_pk_mul_f32 v[116:117], v[116:117], v[170:171] op_sel_hi:[1,0]
	v_pk_mul_f32 v[114:115], v[114:115], v[170:171] op_sel_hi:[1,0]
	global_store_dwordx4 v[126:127], v[122:125], off
	s_nop 1
	v_cvt_pk_bf16_f32 v122, v118, v119
	v_cvt_pk_bf16_f32 v123, v120, v121
	v_cvt_pk_bf16_f32 v124, v114, v115
	v_cvt_pk_bf16_f32 v125, v116, v117
	global_store_dwordx4 v[126:127], v[122:125], off offset:256
	s_and_saveexec_b64 s[10:11], s[22:23]
	s_cbranch_execz .LBB0_554
	v_lshl_add_u64 v[122:123], v[164:165], 0, v[216:217]
	global_store_dwordx4 v[122:123], v[118:121], off
	global_store_dwordx4 v[122:123], v[114:117], off offset:16
.LBB0_554:
	s_or_b64 exec, exec, s[10:11]
	s_waitcnt lgkmcnt(6)
	v_add_f32_e32 v114, v154, v155
	v_fmamk_f32 v114, v114, 0x3a800000, v223
	s_nop 1
	s_nop 0
	s_nop 1
	s_nop 1
	s_nop 1
	s_nop 0
	v_rsq_f32_e32 v115, v114
	s_nop 0
	v_mul_f32_e32 v114, v114, v115
	v_fma_f32 v114, -v114, v115, 1.0
	v_mul_f32_e32 v114, 0.5, v114
	v_fma_f32 v114, v115, v114, v115
	v_pk_mul_f32 v[110:111], v[110:111], v[114:115] op_sel_hi:[1,0]
	v_pk_mul_f32 v[116:117], v[108:109], v[114:115] op_sel_hi:[1,0]
	v_pk_mul_f32 v[108:109], v[106:107], v[114:115] op_sel_hi:[1,0]
	v_cvt_pk_bf16_f32 v106, v110, v111
	v_mov_b64_e32 v[110:111], s[2:3]
	v_mad_i64_i32 v[110:111], s[10:11], v214, s64, v[110:111]
	v_pk_mul_f32 v[112:113], v[112:113], v[114:115] op_sel_hi:[1,0]
	v_lshl_add_u64 v[110:111], v[186:187], 1, v[110:111]
	v_cvt_pk_bf16_f32 v107, v112, v113
	v_cvt_pk_bf16_f32 v108, v108, v109
	v_cvt_pk_bf16_f32 v109, v116, v117
	v_pk_mul_f32 v[104:105], v[104:105], v[114:115] op_sel_hi:[1,0]
	v_pk_mul_f32 v[102:103], v[102:103], v[114:115] op_sel_hi:[1,0]
	v_pk_mul_f32 v[100:101], v[100:101], v[114:115] op_sel_hi:[1,0]
	v_pk_mul_f32 v[98:99], v[98:99], v[114:115] op_sel_hi:[1,0]
	global_store_dwordx4 v[110:111], v[106:109], off
	s_nop 1
	v_cvt_pk_bf16_f32 v106, v102, v103
	v_cvt_pk_bf16_f32 v107, v104, v105
	v_cvt_pk_bf16_f32 v108, v98, v99
	v_cvt_pk_bf16_f32 v109, v100, v101
	global_store_dwordx4 v[110:111], v[106:109], off offset:256
	s_and_saveexec_b64 s[10:11], s[22:23]
	s_cbranch_execz .LBB0_556
	v_lshl_add_u64 v[106:107], v[164:165], 0, v[212:213]
	global_store_dwordx4 v[106:107], v[102:105], off
	global_store_dwordx4 v[106:107], v[98:101], off offset:16
.LBB0_556:
	s_or_b64 exec, exec, s[10:11]
	s_waitcnt lgkmcnt(5)
	v_add_f32_e32 v98, v150, v151
	v_fmamk_f32 v98, v98, 0x3a800000, v223
	s_nop 1
	s_nop 0
	s_nop 1
	s_nop 1
	s_nop 1
	s_nop 0
	v_rsq_f32_e32 v99, v98
	s_nop 0
	v_mul_f32_e32 v98, v98, v99
	v_fma_f32 v98, -v98, v99, 1.0
	v_mul_f32_e32 v98, 0.5, v98
	v_fma_f32 v98, v99, v98, v99
	v_pk_mul_f32 v[94:95], v[94:95], v[98:99] op_sel_hi:[1,0]
	v_pk_mul_f32 v[100:101], v[92:93], v[98:99] op_sel_hi:[1,0]
	v_pk_mul_f32 v[92:93], v[90:91], v[98:99] op_sel_hi:[1,0]
	v_cvt_pk_bf16_f32 v90, v94, v95
	v_mov_b64_e32 v[94:95], s[2:3]
	v_mad_i64_i32 v[94:95], s[10:11], v210, s64, v[94:95]
	v_pk_mul_f32 v[96:97], v[96:97], v[98:99] op_sel_hi:[1,0]
	v_lshl_add_u64 v[94:95], v[186:187], 1, v[94:95]
	v_cvt_pk_bf16_f32 v91, v96, v97
	v_cvt_pk_bf16_f32 v92, v92, v93
	v_cvt_pk_bf16_f32 v93, v100, v101
	v_pk_mul_f32 v[88:89], v[88:89], v[98:99] op_sel_hi:[1,0]
	v_pk_mul_f32 v[86:87], v[86:87], v[98:99] op_sel_hi:[1,0]
	v_pk_mul_f32 v[84:85], v[84:85], v[98:99] op_sel_hi:[1,0]
	v_pk_mul_f32 v[82:83], v[82:83], v[98:99] op_sel_hi:[1,0]
	global_store_dwordx4 v[94:95], v[90:93], off
	s_nop 1
	v_cvt_pk_bf16_f32 v90, v86, v87
	v_cvt_pk_bf16_f32 v91, v88, v89
	v_cvt_pk_bf16_f32 v92, v82, v83
	v_cvt_pk_bf16_f32 v93, v84, v85
	global_store_dwordx4 v[94:95], v[90:93], off offset:256
	s_and_saveexec_b64 s[10:11], s[22:23]
	s_cbranch_execz .LBB0_558
	v_lshl_add_u64 v[90:91], v[164:165], 0, v[208:209]
	global_store_dwordx4 v[90:91], v[86:89], off
	global_store_dwordx4 v[90:91], v[82:85], off offset:16
.LBB0_558:
	s_or_b64 exec, exec, s[10:11]
	s_waitcnt lgkmcnt(4)
	v_add_f32_e32 v82, v146, v147
	v_fmamk_f32 v82, v82, 0x3a800000, v223
	s_nop 1
	s_nop 0
	s_nop 1
	s_nop 1
	s_nop 1
	s_nop 0
	v_rsq_f32_e32 v83, v82
	s_nop 0
	v_mul_f32_e32 v82, v82, v83
	v_fma_f32 v82, -v82, v83, 1.0
	v_mul_f32_e32 v82, 0.5, v82
	v_fma_f32 v82, v83, v82, v83
	v_pk_mul_f32 v[78:79], v[78:79], v[82:83] op_sel_hi:[1,0]
	v_pk_mul_f32 v[84:85], v[76:77], v[82:83] op_sel_hi:[1,0]
	v_pk_mul_f32 v[76:77], v[74:75], v[82:83] op_sel_hi:[1,0]
	v_cvt_pk_bf16_f32 v74, v78, v79
	v_mov_b64_e32 v[78:79], s[2:3]
	v_mad_i64_i32 v[78:79], s[10:11], v206, s64, v[78:79]
	v_pk_mul_f32 v[80:81], v[80:81], v[82:83] op_sel_hi:[1,0]
	v_lshl_add_u64 v[78:79], v[186:187], 1, v[78:79]
	v_cvt_pk_bf16_f32 v75, v80, v81
	v_cvt_pk_bf16_f32 v76, v76, v77
	v_cvt_pk_bf16_f32 v77, v84, v85
	v_pk_mul_f32 v[72:73], v[72:73], v[82:83] op_sel_hi:[1,0]
	v_pk_mul_f32 v[70:71], v[70:71], v[82:83] op_sel_hi:[1,0]
	v_pk_mul_f32 v[68:69], v[68:69], v[82:83] op_sel_hi:[1,0]
	v_pk_mul_f32 v[66:67], v[66:67], v[82:83] op_sel_hi:[1,0]
	global_store_dwordx4 v[78:79], v[74:77], off
	s_nop 1
	v_cvt_pk_bf16_f32 v74, v70, v71
	v_cvt_pk_bf16_f32 v75, v72, v73
	v_cvt_pk_bf16_f32 v76, v66, v67
	v_cvt_pk_bf16_f32 v77, v68, v69
	global_store_dwordx4 v[78:79], v[74:77], off offset:256
	s_and_saveexec_b64 s[10:11], s[22:23]
	s_cbranch_execz .LBB0_560
	v_lshl_add_u64 v[74:75], v[164:165], 0, v[204:205]
	global_store_dwordx4 v[74:75], v[70:73], off
	global_store_dwordx4 v[74:75], v[66:69], off offset:16
.LBB0_560:
	s_or_b64 exec, exec, s[10:11]
	s_waitcnt lgkmcnt(3)
	v_add_f32_e32 v66, v142, v143
	v_fmamk_f32 v66, v66, 0x3a800000, v223
	s_nop 1
	s_nop 0
	s_nop 1
	s_nop 1
	s_nop 1
	s_nop 0
	v_rsq_f32_e32 v67, v66
	s_nop 0
	v_mul_f32_e32 v66, v66, v67
	v_fma_f32 v66, -v66, v67, 1.0
	v_mul_f32_e32 v66, 0.5, v66
	v_fma_f32 v66, v67, v66, v67
	v_pk_mul_f32 v[62:63], v[62:63], v[66:67] op_sel_hi:[1,0]
	v_pk_mul_f32 v[68:69], v[60:61], v[66:67] op_sel_hi:[1,0]
	v_pk_mul_f32 v[60:61], v[58:59], v[66:67] op_sel_hi:[1,0]
	v_cvt_pk_bf16_f32 v58, v62, v63
	v_mov_b64_e32 v[62:63], s[2:3]
	v_mad_i64_i32 v[62:63], s[10:11], v202, s64, v[62:63]
	v_pk_mul_f32 v[64:65], v[64:65], v[66:67] op_sel_hi:[1,0]
	v_lshl_add_u64 v[62:63], v[186:187], 1, v[62:63]
	v_cvt_pk_bf16_f32 v59, v64, v65
	v_cvt_pk_bf16_f32 v60, v60, v61
	v_cvt_pk_bf16_f32 v61, v68, v69
	v_pk_mul_f32 v[56:57], v[56:57], v[66:67] op_sel_hi:[1,0]
	v_pk_mul_f32 v[54:55], v[54:55], v[66:67] op_sel_hi:[1,0]
	v_pk_mul_f32 v[52:53], v[52:53], v[66:67] op_sel_hi:[1,0]
	v_pk_mul_f32 v[50:51], v[50:51], v[66:67] op_sel_hi:[1,0]
	global_store_dwordx4 v[62:63], v[58:61], off
	s_nop 1
	v_cvt_pk_bf16_f32 v58, v54, v55
	v_cvt_pk_bf16_f32 v59, v56, v57
	v_cvt_pk_bf16_f32 v60, v50, v51
	v_cvt_pk_bf16_f32 v61, v52, v53
	global_store_dwordx4 v[62:63], v[58:61], off offset:256
	s_and_saveexec_b64 s[10:11], s[22:23]
	s_cbranch_execz .LBB0_562
	v_lshl_add_u64 v[58:59], v[164:165], 0, v[200:201]
	global_store_dwordx4 v[58:59], v[54:57], off
	global_store_dwordx4 v[58:59], v[50:53], off offset:16
.LBB0_562:
	s_or_b64 exec, exec, s[10:11]
	s_waitcnt lgkmcnt(2)
	v_add_f32_e32 v50, v138, v139
	v_fmamk_f32 v50, v50, 0x3a800000, v223
	s_nop 1
	s_nop 0
	s_nop 1
	s_nop 1
	s_nop 1
	s_nop 0
	v_rsq_f32_e32 v51, v50
	s_nop 0
	v_mul_f32_e32 v50, v50, v51
	v_fma_f32 v50, -v50, v51, 1.0
	v_mul_f32_e32 v50, 0.5, v50
	v_fma_f32 v50, v51, v50, v51
	v_pk_mul_f32 v[46:47], v[46:47], v[50:51] op_sel_hi:[1,0]
	v_pk_mul_f32 v[52:53], v[44:45], v[50:51] op_sel_hi:[1,0]
	v_pk_mul_f32 v[44:45], v[42:43], v[50:51] op_sel_hi:[1,0]
	v_cvt_pk_bf16_f32 v42, v46, v47
	v_mov_b64_e32 v[46:47], s[2:3]
	v_mad_i64_i32 v[46:47], s[10:11], v198, s64, v[46:47]
	v_pk_mul_f32 v[48:49], v[48:49], v[50:51] op_sel_hi:[1,0]
	v_lshl_add_u64 v[46:47], v[186:187], 1, v[46:47]
	v_cvt_pk_bf16_f32 v43, v48, v49
	v_cvt_pk_bf16_f32 v44, v44, v45
	v_cvt_pk_bf16_f32 v45, v52, v53
	v_pk_mul_f32 v[40:41], v[40:41], v[50:51] op_sel_hi:[1,0]
	v_pk_mul_f32 v[38:39], v[38:39], v[50:51] op_sel_hi:[1,0]
	v_pk_mul_f32 v[36:37], v[36:37], v[50:51] op_sel_hi:[1,0]
	v_pk_mul_f32 v[34:35], v[34:35], v[50:51] op_sel_hi:[1,0]
	global_store_dwordx4 v[46:47], v[42:45], off
	s_nop 1
	v_cvt_pk_bf16_f32 v42, v38, v39
	v_cvt_pk_bf16_f32 v43, v40, v41
	v_cvt_pk_bf16_f32 v44, v34, v35
	v_cvt_pk_bf16_f32 v45, v36, v37
	global_store_dwordx4 v[46:47], v[42:45], off offset:256
	s_and_saveexec_b64 s[10:11], s[22:23]
	s_cbranch_execz .LBB0_564
	v_lshl_add_u64 v[42:43], v[164:165], 0, v[196:197]
	global_store_dwordx4 v[42:43], v[38:41], off
	global_store_dwordx4 v[42:43], v[34:37], off offset:16
.LBB0_564:
	s_or_b64 exec, exec, s[10:11]
	s_waitcnt lgkmcnt(1)
	v_add_f32_e32 v34, v134, v135
	v_fmamk_f32 v34, v34, 0x3a800000, v223
	s_nop 1
	s_nop 0
	s_nop 1
	s_nop 1
	s_nop 1
	s_nop 0
	v_rsq_f32_e32 v35, v34
	s_nop 0
	v_mul_f32_e32 v34, v34, v35
	v_fma_f32 v34, -v34, v35, 1.0
	v_mul_f32_e32 v34, 0.5, v34
	v_fma_f32 v34, v35, v34, v35
	v_pk_mul_f32 v[30:31], v[30:31], v[34:35] op_sel_hi:[1,0]
	v_pk_mul_f32 v[36:37], v[28:29], v[34:35] op_sel_hi:[1,0]
	v_pk_mul_f32 v[28:29], v[26:27], v[34:35] op_sel_hi:[1,0]
	v_cvt_pk_bf16_f32 v26, v30, v31
	v_mov_b64_e32 v[30:31], s[2:3]
	v_mad_i64_i32 v[30:31], s[10:11], v194, s64, v[30:31]
	v_pk_mul_f32 v[32:33], v[32:33], v[34:35] op_sel_hi:[1,0]
	v_lshl_add_u64 v[30:31], v[186:187], 1, v[30:31]
	v_cvt_pk_bf16_f32 v27, v32, v33
	v_cvt_pk_bf16_f32 v28, v28, v29
	v_cvt_pk_bf16_f32 v29, v36, v37
	v_pk_mul_f32 v[24:25], v[24:25], v[34:35] op_sel_hi:[1,0]
	v_pk_mul_f32 v[22:23], v[22:23], v[34:35] op_sel_hi:[1,0]
	v_pk_mul_f32 v[20:21], v[20:21], v[34:35] op_sel_hi:[1,0]
	v_pk_mul_f32 v[18:19], v[18:19], v[34:35] op_sel_hi:[1,0]
	global_store_dwordx4 v[30:31], v[26:29], off
	s_nop 1
	v_cvt_pk_bf16_f32 v26, v22, v23
	v_cvt_pk_bf16_f32 v27, v24, v25
	v_cvt_pk_bf16_f32 v28, v18, v19
	v_cvt_pk_bf16_f32 v29, v20, v21
	global_store_dwordx4 v[30:31], v[26:29], off offset:256
	s_and_saveexec_b64 s[10:11], s[22:23]
	s_cbranch_execz .LBB0_566
	v_lshl_add_u64 v[26:27], v[164:165], 0, v[192:193]
	global_store_dwordx4 v[26:27], v[22:25], off
	global_store_dwordx4 v[26:27], v[18:21], off offset:16
.LBB0_566:
	s_or_b64 exec, exec, s[10:11]
	s_waitcnt lgkmcnt(0)
	v_add_f32_e32 v18, v130, v131
	v_fmamk_f32 v18, v18, 0x3a800000, v223
	s_nop 1
	s_nop 0
	s_nop 1
	s_nop 1
	s_nop 1
	s_nop 0
	v_rsq_f32_e32 v19, v18
	s_nop 0
	v_mul_f32_e32 v18, v18, v19
	v_fma_f32 v18, -v18, v19, 1.0
	v_mul_f32_e32 v18, 0.5, v18
	v_fma_f32 v18, v19, v18, v19
	v_pk_mul_f32 v[14:15], v[14:15], v[18:19] op_sel_hi:[1,0]
	v_pk_mul_f32 v[20:21], v[12:13], v[18:19] op_sel_hi:[1,0]
	v_pk_mul_f32 v[12:13], v[10:11], v[18:19] op_sel_hi:[1,0]
	v_cvt_pk_bf16_f32 v10, v14, v15
	v_mov_b64_e32 v[14:15], s[2:3]
	v_mad_i64_i32 v[14:15], s[10:11], v190, s64, v[14:15]
	v_pk_mul_f32 v[16:17], v[16:17], v[18:19] op_sel_hi:[1,0]
	v_lshl_add_u64 v[14:15], v[186:187], 1, v[14:15]
	v_cvt_pk_bf16_f32 v11, v16, v17
	v_cvt_pk_bf16_f32 v12, v12, v13
	v_cvt_pk_bf16_f32 v13, v20, v21
	v_pk_mul_f32 v[8:9], v[8:9], v[18:19] op_sel_hi:[1,0]
	v_pk_mul_f32 v[6:7], v[6:7], v[18:19] op_sel_hi:[1,0]
	v_pk_mul_f32 v[4:5], v[4:5], v[18:19] op_sel_hi:[1,0]
	v_pk_mul_f32 v[2:3], v[2:3], v[18:19] op_sel_hi:[1,0]
	global_store_dwordx4 v[14:15], v[10:13], off
	s_nop 1
	v_cvt_pk_bf16_f32 v10, v6, v7
	v_cvt_pk_bf16_f32 v11, v8, v9
	v_cvt_pk_bf16_f32 v12, v2, v3
	v_cvt_pk_bf16_f32 v13, v4, v5
	global_store_dwordx4 v[14:15], v[10:13], off offset:256
	s_and_saveexec_b64 s[10:11], s[22:23]
	s_cbranch_execz .LBB0_568
	v_lshl_add_u64 v[10:11], v[164:165], 0, v[188:189]
	global_store_dwordx4 v[10:11], v[6:9], off
	global_store_dwordx4 v[10:11], v[2:5], off offset:16

.LBB0_1697:
	v_lshl_add_u32 v158, s46, 8, v162
	v_lshl_or_b32 v159, s45, 8, v164
	v_lshlrev_b32_e32 v160, 2, v159
	v_lshl_add_u32 v156, v158, 12, v160
	global_load_dwordx4 v[54:57], v160, s[14:15]
	global_load_dwordx4 v[50:53], v160, s[14:15] offset:16
	global_load_dwordx4 v[30:33], v160, s[14:15] offset:512
	global_load_dwordx4 v[26:29], v160, s[14:15] offset:528
	global_load_dwordx4 v[188:191], v156, s[12:13]
	global_load_dwordx4 v[192:195], v156, s[12:13] offset:16
	global_load_dwordx4 v[196:199], v156, s[12:13] offset:512
	global_load_dwordx4 v[200:203], v156, s[12:13] offset:528
	v_add_u32_e32 v157, 0x10000, v156
	global_load_dwordx4 v[204:207], v157, s[12:13]
	global_load_dwordx4 v[208:211], v157, s[12:13] offset:16
	global_load_dwordx4 v[212:215], v157, s[12:13] offset:512
	global_load_dwordx4 v[216:219], v157, s[12:13] offset:528
	s_lshl_b32 s26, s45, 2
	s_add_i32 s26, s26, s41
	s_lshl_b32 s26, s26, 2
	v_lshlrev_b32_e32 v174, 6, v158
	v_add_u32_e32 v174, s26, v174
	v_mbcnt_hi_u32_b32 v166, -1, v253
	v_xor_b32_e32 v167, 32, v166
	v_xor_b32_e32 v166, 16, v166
	v_lshlrev_b32_e32 v166, 2, v166
	v_lshlrev_b32_e32 v167, 2, v167
	s_waitcnt vmcnt(4)
	v_pk_add_f32 v[142:143], v[142:143], v[188:189]
	v_pk_add_f32 v[144:145], v[144:145], v[190:191]
	v_pk_add_f32 v[138:139], v[138:139], v[192:193]
	v_pk_add_f32 v[140:141], v[140:141], v[194:195]
	v_pk_add_f32 v[134:135], v[134:135], v[196:197]
	v_pk_add_f32 v[136:137], v[136:137], v[198:199]
	v_pk_add_f32 v[130:131], v[130:131], v[200:201]
	v_pk_add_f32 v[132:133], v[132:133], v[202:203]
	v_add_u32_e32 v157, 0x20000, v156
	global_load_dwordx4 v[188:191], v157, s[12:13]
	global_load_dwordx4 v[192:195], v157, s[12:13] offset:16
	global_load_dwordx4 v[196:199], v157, s[12:13] offset:512
	global_load_dwordx4 v[200:203], v157, s[12:13] offset:528
	v_mov_b32_e32 v159, v156
	global_store_dwordx4 v159, v[142:145], s[12:13]
	global_store_dwordx4 v159, v[138:141], s[12:13] offset:16
	global_store_dwordx4 v159, v[134:137], s[12:13] offset:512
	global_store_dwordx4 v159, v[130:133], s[12:13] offset:528
	v_mul_f32_e32 v169, v145, v145
	v_mul_f32_e32 v168, v143, v143
	v_fmac_f32_e32 v168, v142, v142
	v_fmac_f32_e32 v169, v144, v144
	v_add_f32_e32 v168, v168, v169
	v_mul_f32_e32 v169, v139, v139
	v_fmac_f32_e32 v169, v138, v138
	v_add_f32_e32 v168, v169, v168
	v_mul_f32_e32 v169, v141, v141
	v_fmac_f32_e32 v169, v140, v140
	v_add_f32_e32 v170, v169, v168
	v_mul_f32_e32 v169, v137, v137
	v_mul_f32_e32 v168, v135, v135
	v_fmac_f32_e32 v168, v134, v134
	v_fmac_f32_e32 v169, v136, v136
	v_add_f32_e32 v168, v168, v169
	v_mul_f32_e32 v169, v131, v131
	v_fmac_f32_e32 v169, v130, v130
	v_add_f32_e32 v168, v169, v168
	v_mul_f32_e32 v169, v133, v133
	v_fmac_f32_e32 v169, v132, v132
	v_add_f32_e32 v168, v169, v168
	v_add_f32_e32 v168, v170, v168
	ds_bpermute_b32 v169, v166, v168
	v_pk_mul_f32 v[142:143], v[54:55], v[142:143]
	v_pk_mul_f32 v[144:145], v[56:57], v[144:145]
	v_pk_mul_f32 v[138:139], v[50:51], v[138:139]
	v_pk_mul_f32 v[140:141], v[52:53], v[140:141]
	v_cvt_pk_bf16_f32 v142, v142, v143
	v_cvt_pk_bf16_f32 v143, v144, v145
	v_cvt_pk_bf16_f32 v144, v138, v139
	v_cvt_pk_bf16_f32 v145, v140, v141
	v_pk_mul_f32 v[134:135], v[30:31], v[134:135]
	v_pk_mul_f32 v[136:137], v[32:33], v[136:137]
	v_pk_mul_f32 v[130:131], v[26:27], v[130:131]
	v_pk_mul_f32 v[132:133], v[28:29], v[132:133]
	v_cvt_pk_bf16_f32 v134, v134, v135
	v_cvt_pk_bf16_f32 v135, v136, v137
	v_cvt_pk_bf16_f32 v136, v130, v131
	v_cvt_pk_bf16_f32 v137, v132, v133
	v_lshrrev_b32_e32 v160, 1, v159
	global_store_dwordx4 v160, v[142:145], s[4:5]
	global_store_dwordx4 v160, v[134:137], s[4:5] offset:256
	s_waitcnt lgkmcnt(0)
	v_add_f32_e32 v169, v168, v169
	ds_bpermute_b32 v170, v167, v169
	v_mov_b32_e32 v161, v174
	s_waitcnt lgkmcnt(0)
	v_add_f32_e32 v169, v169, v170
	s_and_saveexec_b64 s[2:3], s[6:7]
	global_store_dword v161, v169, s[10:11]
	s_or_b64 exec, exec, s[2:3]
	v_add_u32_e32 v157, 0x30000, v156
	global_load_dwordx4 v[142:145], v157, s[12:13]
	global_load_dwordx4 v[138:141], v157, s[12:13] offset:16
	global_load_dwordx4 v[134:137], v157, s[12:13] offset:512
	global_load_dwordx4 v[130:133], v157, s[12:13] offset:528
	s_waitcnt vmcnt(15)
	v_pk_add_f32 v[126:127], v[126:127], v[204:205]
	v_pk_add_f32 v[128:129], v[128:129], v[206:207]
	v_pk_add_f32 v[122:123], v[122:123], v[208:209]
	v_pk_add_f32 v[124:125], v[124:125], v[210:211]
	v_pk_add_f32 v[118:119], v[118:119], v[212:213]
	v_pk_add_f32 v[120:121], v[120:121], v[214:215]
	v_pk_add_f32 v[114:115], v[114:115], v[216:217]
	v_pk_add_f32 v[116:117], v[116:117], v[218:219]
	v_add_u32_e32 v157, 0x80000, v156
	global_load_dwordx4 v[204:207], v157, s[12:13]
	global_load_dwordx4 v[208:211], v157, s[12:13] offset:16
	global_load_dwordx4 v[212:215], v157, s[12:13] offset:512
	global_load_dwordx4 v[216:219], v157, s[12:13] offset:528
	v_add_u32_e32 v159, 0x10000, v156
	global_store_dwordx4 v159, v[126:129], s[12:13]
	global_store_dwordx4 v159, v[122:125], s[12:13] offset:16
	global_store_dwordx4 v159, v[118:121], s[12:13] offset:512
	global_store_dwordx4 v159, v[114:117], s[12:13] offset:528
	v_mul_f32_e32 v169, v129, v129
	v_mul_f32_e32 v168, v127, v127
	v_fmac_f32_e32 v168, v126, v126
	v_fmac_f32_e32 v169, v128, v128
	v_add_f32_e32 v168, v168, v169
	v_mul_f32_e32 v169, v123, v123
	v_fmac_f32_e32 v169, v122, v122
	v_add_f32_e32 v168, v169, v168
	v_mul_f32_e32 v169, v125, v125
	v_fmac_f32_e32 v169, v124, v124
	v_add_f32_e32 v170, v169, v168
	v_mul_f32_e32 v169, v121, v121
	v_mul_f32_e32 v168, v119, v119
	v_fmac_f32_e32 v168, v118, v118
	v_fmac_f32_e32 v169, v120, v120
	v_add_f32_e32 v168, v168, v169
	v_mul_f32_e32 v169, v115, v115
	v_fmac_f32_e32 v169, v114, v114
	v_add_f32_e32 v168, v169, v168
	v_mul_f32_e32 v169, v117, v117
	v_fmac_f32_e32 v169, v116, v116
	v_add_f32_e32 v168, v169, v168
	v_add_f32_e32 v168, v170, v168
	ds_bpermute_b32 v169, v166, v168
	v_pk_mul_f32 v[126:127], v[54:55], v[126:127]
	v_pk_mul_f32 v[128:129], v[56:57], v[128:129]
	v_pk_mul_f32 v[122:123], v[50:51], v[122:123]
	v_pk_mul_f32 v[124:125], v[52:53], v[124:125]
	v_cvt_pk_bf16_f32 v126, v126, v127
	v_cvt_pk_bf16_f32 v127, v128, v129
	v_cvt_pk_bf16_f32 v128, v122, v123
	v_cvt_pk_bf16_f32 v129, v124, v125
	v_pk_mul_f32 v[118:119], v[30:31], v[118:119]
	v_pk_mul_f32 v[120:121], v[32:33], v[120:121]
	v_pk_mul_f32 v[114:115], v[26:27], v[114:115]
	v_pk_mul_f32 v[116:117], v[28:29], v[116:117]
	v_cvt_pk_bf16_f32 v118, v118, v119
	v_cvt_pk_bf16_f32 v119, v120, v121
	v_cvt_pk_bf16_f32 v120, v114, v115
	v_cvt_pk_bf16_f32 v121, v116, v117
	v_lshrrev_b32_e32 v160, 1, v159
	global_store_dwordx4 v160, v[126:129], s[4:5]
	global_store_dwordx4 v160, v[118:121], s[4:5] offset:256
	s_waitcnt lgkmcnt(0)
	v_add_f32_e32 v169, v168, v169
	ds_bpermute_b32 v170, v167, v169
	v_add_u32_e32 v161, 0x400, v174
	s_waitcnt lgkmcnt(0)
	v_add_f32_e32 v169, v169, v170
	s_and_saveexec_b64 s[2:3], s[6:7]
	global_store_dword v161, v169, s[10:11]
	s_or_b64 exec, exec, s[2:3]
	v_add_u32_e32 v157, 0x90000, v156
	global_load_dwordx4 v[126:129], v157, s[12:13]
	global_load_dwordx4 v[122:125], v157, s[12:13] offset:16
	global_load_dwordx4 v[118:121], v157, s[12:13] offset:512
	global_load_dwordx4 v[114:117], v157, s[12:13] offset:528
	s_waitcnt vmcnt(26)
	v_pk_add_f32 v[110:111], v[110:111], v[188:189]
	v_pk_add_f32 v[112:113], v[112:113], v[190:191]
	v_pk_add_f32 v[106:107], v[106:107], v[192:193]
	v_pk_add_f32 v[108:109], v[108:109], v[194:195]
	v_pk_add_f32 v[102:103], v[102:103], v[196:197]
	v_pk_add_f32 v[104:105], v[104:105], v[198:199]
	v_pk_add_f32 v[98:99], v[98:99], v[200:201]
	v_pk_add_f32 v[100:101], v[100:101], v[202:203]
	v_add_u32_e32 v157, 0xa0000, v156
	global_load_dwordx4 v[188:191], v157, s[12:13]
	global_load_dwordx4 v[192:195], v157, s[12:13] offset:16
	global_load_dwordx4 v[196:199], v157, s[12:13] offset:512
	global_load_dwordx4 v[200:203], v157, s[12:13] offset:528
	v_add_u32_e32 v159, 0x20000, v156
	global_store_dwordx4 v159, v[110:113], s[12:13]
	global_store_dwordx4 v159, v[106:109], s[12:13] offset:16
	global_store_dwordx4 v159, v[102:105], s[12:13] offset:512
	global_store_dwordx4 v159, v[98:101], s[12:13] offset:528
	v_mul_f32_e32 v169, v113, v113
	v_mul_f32_e32 v168, v111, v111
	v_fmac_f32_e32 v168, v110, v110
	v_fmac_f32_e32 v169, v112, v112
	v_add_f32_e32 v168, v168, v169
	v_mul_f32_e32 v169, v107, v107
	v_fmac_f32_e32 v169, v106, v106
	v_add_f32_e32 v168, v169, v168
	v_mul_f32_e32 v169, v109, v109
	v_fmac_f32_e32 v169, v108, v108
	v_add_f32_e32 v170, v169, v168
	v_mul_f32_e32 v169, v105, v105
	v_mul_f32_e32 v168, v103, v103
	v_fmac_f32_e32 v168, v102, v102
	v_fmac_f32_e32 v169, v104, v104
	v_add_f32_e32 v168, v168, v169
	v_mul_f32_e32 v169, v99, v99
	v_fmac_f32_e32 v169, v98, v98
	v_add_f32_e32 v168, v169, v168
	v_mul_f32_e32 v169, v101, v101
	v_fmac_f32_e32 v169, v100, v100
	v_add_f32_e32 v168, v169, v168
	v_add_f32_e32 v168, v170, v168
	ds_bpermute_b32 v169, v166, v168
	v_pk_mul_f32 v[110:111], v[54:55], v[110:111]
	v_pk_mul_f32 v[112:113], v[56:57], v[112:113]
	v_pk_mul_f32 v[106:107], v[50:51], v[106:107]
	v_pk_mul_f32 v[108:109], v[52:53], v[108:109]
	v_cvt_pk_bf16_f32 v110, v110, v111
	v_cvt_pk_bf16_f32 v111, v112, v113
	v_cvt_pk_bf16_f32 v112, v106, v107
	v_cvt_pk_bf16_f32 v113, v108, v109
	v_pk_mul_f32 v[102:103], v[30:31], v[102:103]
	v_pk_mul_f32 v[104:105], v[32:33], v[104:105]
	v_pk_mul_f32 v[98:99], v[26:27], v[98:99]
	v_pk_mul_f32 v[100:101], v[28:29], v[100:101]
	v_cvt_pk_bf16_f32 v102, v102, v103
	v_cvt_pk_bf16_f32 v103, v104, v105
	v_cvt_pk_bf16_f32 v104, v98, v99
	v_cvt_pk_bf16_f32 v105, v100, v101
	v_lshrrev_b32_e32 v160, 1, v159
	global_store_dwordx4 v160, v[110:113], s[4:5]
	global_store_dwordx4 v160, v[102:105], s[4:5] offset:256
	s_waitcnt lgkmcnt(0)
	v_add_f32_e32 v169, v168, v169
	ds_bpermute_b32 v170, v167, v169
	v_add_u32_e32 v161, 0x800, v174
	s_waitcnt lgkmcnt(0)
	v_add_f32_e32 v169, v169, v170
	s_and_saveexec_b64 s[2:3], s[6:7]
	global_store_dword v161, v169, s[10:11]
	s_or_b64 exec, exec, s[2:3]
	v_add_u32_e32 v157, 0xb0000, v156
	global_load_dwordx4 v[110:113], v157, s[12:13]
	global_load_dwordx4 v[106:109], v157, s[12:13] offset:16
	global_load_dwordx4 v[102:105], v157, s[12:13] offset:512
	global_load_dwordx4 v[98:101], v157, s[12:13] offset:528
	s_waitcnt vmcnt(30)
	v_pk_add_f32 v[94:95], v[94:95], v[142:143]
	v_pk_add_f32 v[96:97], v[96:97], v[144:145]
	v_pk_add_f32 v[90:91], v[90:91], v[138:139]
	v_pk_add_f32 v[92:93], v[92:93], v[140:141]
	v_pk_add_f32 v[86:87], v[86:87], v[134:135]
	v_pk_add_f32 v[88:89], v[88:89], v[136:137]
	v_pk_add_f32 v[82:83], v[82:83], v[130:131]
	v_pk_add_f32 v[84:85], v[84:85], v[132:133]
	v_add_u32_e32 v159, 0x30000, v156
	global_store_dwordx4 v159, v[94:97], s[12:13]
	global_store_dwordx4 v159, v[90:93], s[12:13] offset:16
	global_store_dwordx4 v159, v[86:89], s[12:13] offset:512
	global_store_dwordx4 v159, v[82:85], s[12:13] offset:528
	v_mul_f32_e32 v169, v97, v97
	v_mul_f32_e32 v168, v95, v95
	v_fmac_f32_e32 v168, v94, v94
	v_fmac_f32_e32 v169, v96, v96
	v_add_f32_e32 v168, v168, v169
	v_mul_f32_e32 v169, v91, v91
	v_fmac_f32_e32 v169, v90, v90
	v_add_f32_e32 v168, v169, v168
	v_mul_f32_e32 v169, v93, v93
	v_fmac_f32_e32 v169, v92, v92
	v_add_f32_e32 v170, v169, v168
	v_mul_f32_e32 v169, v89, v89
	v_mul_f32_e32 v168, v87, v87
	v_fmac_f32_e32 v168, v86, v86
	v_fmac_f32_e32 v169, v88, v88
	v_add_f32_e32 v168, v168, v169
	v_mul_f32_e32 v169, v83, v83
	v_fmac_f32_e32 v169, v82, v82
	v_add_f32_e32 v168, v169, v168
	v_mul_f32_e32 v169, v85, v85
	v_fmac_f32_e32 v169, v84, v84
	v_add_f32_e32 v168, v169, v168
	v_add_f32_e32 v168, v170, v168
	ds_bpermute_b32 v169, v166, v168
	v_pk_mul_f32 v[94:95], v[54:55], v[94:95]
	v_pk_mul_f32 v[96:97], v[56:57], v[96:97]
	v_pk_mul_f32 v[90:91], v[50:51], v[90:91]
	v_pk_mul_f32 v[92:93], v[52:53], v[92:93]
	v_cvt_pk_bf16_f32 v94, v94, v95
	v_cvt_pk_bf16_f32 v95, v96, v97
	v_cvt_pk_bf16_f32 v96, v90, v91
	v_cvt_pk_bf16_f32 v97, v92, v93
	v_pk_mul_f32 v[86:87], v[30:31], v[86:87]
	v_pk_mul_f32 v[88:89], v[32:33], v[88:89]
	v_pk_mul_f32 v[82:83], v[26:27], v[82:83]
	v_pk_mul_f32 v[84:85], v[28:29], v[84:85]
	v_cvt_pk_bf16_f32 v86, v86, v87
	v_cvt_pk_bf16_f32 v87, v88, v89
	v_cvt_pk_bf16_f32 v88, v82, v83
	v_cvt_pk_bf16_f32 v89, v84, v85
	v_lshrrev_b32_e32 v160, 1, v159
	global_store_dwordx4 v160, v[94:97], s[4:5]
	global_store_dwordx4 v160, v[86:89], s[4:5] offset:256
	s_waitcnt lgkmcnt(0)
	v_add_f32_e32 v169, v168, v169
	ds_bpermute_b32 v170, v167, v169
	v_add_u32_e32 v161, 0xc00, v174
	s_waitcnt lgkmcnt(0)
	v_add_f32_e32 v169, v169, v170
	s_and_saveexec_b64 s[2:3], s[6:7]
	global_store_dword v161, v169, s[10:11]
	s_or_b64 exec, exec, s[2:3]
	s_waitcnt vmcnt(33)
	v_pk_add_f32 v[78:79], v[78:79], v[204:205]
	v_pk_add_f32 v[80:81], v[80:81], v[206:207]
	v_pk_add_f32 v[74:75], v[74:75], v[208:209]
	v_pk_add_f32 v[76:77], v[76:77], v[210:211]
	v_pk_add_f32 v[70:71], v[70:71], v[212:213]
	v_pk_add_f32 v[72:73], v[72:73], v[214:215]
	v_pk_add_f32 v[66:67], v[66:67], v[216:217]
	v_pk_add_f32 v[68:69], v[68:69], v[218:219]
	v_add_u32_e32 v159, 0x80000, v156
	global_store_dwordx4 v159, v[78:81], s[12:13]
	global_store_dwordx4 v159, v[74:77], s[12:13] offset:16
	global_store_dwordx4 v159, v[70:73], s[12:13] offset:512
	global_store_dwordx4 v159, v[66:69], s[12:13] offset:528
	v_mul_f32_e32 v169, v81, v81
	v_mul_f32_e32 v168, v79, v79
	v_fmac_f32_e32 v168, v78, v78
	v_fmac_f32_e32 v169, v80, v80
	v_add_f32_e32 v168, v168, v169
	v_mul_f32_e32 v169, v75, v75
	v_fmac_f32_e32 v169, v74, v74
	v_add_f32_e32 v168, v169, v168
	v_mul_f32_e32 v169, v77, v77
	v_fmac_f32_e32 v169, v76, v76
	v_add_f32_e32 v170, v169, v168
	v_mul_f32_e32 v169, v73, v73
	v_mul_f32_e32 v168, v71, v71
	v_fmac_f32_e32 v168, v70, v70
	v_fmac_f32_e32 v169, v72, v72
	v_add_f32_e32 v168, v168, v169
	v_mul_f32_e32 v169, v67, v67
	v_fmac_f32_e32 v169, v66, v66
	v_add_f32_e32 v168, v169, v168
	v_mul_f32_e32 v169, v69, v69
	v_fmac_f32_e32 v169, v68, v68
	v_add_f32_e32 v168, v169, v168
	v_add_f32_e32 v168, v170, v168
	ds_bpermute_b32 v169, v166, v168
	v_pk_mul_f32 v[78:79], v[54:55], v[78:79]
	v_pk_mul_f32 v[80:81], v[56:57], v[80:81]
	v_pk_mul_f32 v[74:75], v[50:51], v[74:75]
	v_pk_mul_f32 v[76:77], v[52:53], v[76:77]
	v_cvt_pk_bf16_f32 v78, v78, v79
	v_cvt_pk_bf16_f32 v79, v80, v81
	v_cvt_pk_bf16_f32 v80, v74, v75
	v_cvt_pk_bf16_f32 v81, v76, v77
	v_pk_mul_f32 v[70:71], v[30:31], v[70:71]
	v_pk_mul_f32 v[72:73], v[32:33], v[72:73]
	v_pk_mul_f32 v[66:67], v[26:27], v[66:67]
	v_pk_mul_f32 v[68:69], v[28:29], v[68:69]
	v_cvt_pk_bf16_f32 v70, v70, v71
	v_cvt_pk_bf16_f32 v71, v72, v73
	v_cvt_pk_bf16_f32 v72, v66, v67
	v_cvt_pk_bf16_f32 v73, v68, v69
	v_lshrrev_b32_e32 v160, 1, v159
	global_store_dwordx4 v160, v[78:81], s[4:5]
	global_store_dwordx4 v160, v[70:73], s[4:5] offset:256
	s_waitcnt lgkmcnt(0)
	v_add_f32_e32 v169, v168, v169
	ds_bpermute_b32 v170, v167, v169
	v_add_u32_e32 v161, 0x2000, v174
	s_waitcnt lgkmcnt(0)
	v_add_f32_e32 v169, v169, v170
	s_and_saveexec_b64 s[2:3], s[6:7]
	global_store_dword v161, v169, s[10:11]
	s_or_b64 exec, exec, s[2:3]
	s_waitcnt vmcnt(29)
	v_pk_add_f32 v[62:63], v[62:63], v[126:127]
	v_pk_add_f32 v[64:65], v[64:65], v[128:129]
	v_pk_add_f32 v[58:59], v[58:59], v[122:123]
	v_pk_add_f32 v[60:61], v[60:61], v[124:125]
	v_pk_add_f32 v[46:47], v[46:47], v[118:119]
	v_pk_add_f32 v[48:49], v[48:49], v[120:121]
	v_pk_add_f32 v[42:43], v[42:43], v[114:115]
	v_pk_add_f32 v[44:45], v[44:45], v[116:117]
	v_add_u32_e32 v159, 0x90000, v156
	global_store_dwordx4 v159, v[62:65], s[12:13]
	global_store_dwordx4 v159, v[58:61], s[12:13] offset:16
	global_store_dwordx4 v159, v[46:49], s[12:13] offset:512
	global_store_dwordx4 v159, v[42:45], s[12:13] offset:528
	v_mul_f32_e32 v169, v65, v65
	v_mul_f32_e32 v168, v63, v63
	v_fmac_f32_e32 v168, v62, v62
	v_fmac_f32_e32 v169, v64, v64
	v_add_f32_e32 v168, v168, v169
	v_mul_f32_e32 v169, v59, v59
	v_fmac_f32_e32 v169, v58, v58
	v_add_f32_e32 v168, v169, v168
	v_mul_f32_e32 v169, v61, v61
	v_fmac_f32_e32 v169, v60, v60
	v_add_f32_e32 v170, v169, v168
	v_mul_f32_e32 v169, v49, v49
	v_mul_f32_e32 v168, v47, v47
	v_fmac_f32_e32 v168, v46, v46
	v_fmac_f32_e32 v169, v48, v48
	v_add_f32_e32 v168, v168, v169
	v_mul_f32_e32 v169, v43, v43
	v_fmac_f32_e32 v169, v42, v42
	v_add_f32_e32 v168, v169, v168
	v_mul_f32_e32 v169, v45, v45
	v_fmac_f32_e32 v169, v44, v44
	v_add_f32_e32 v168, v169, v168
	v_add_f32_e32 v168, v170, v168
	ds_bpermute_b32 v169, v166, v168
	v_pk_mul_f32 v[62:63], v[54:55], v[62:63]
	v_pk_mul_f32 v[64:65], v[56:57], v[64:65]
	v_pk_mul_f32 v[58:59], v[50:51], v[58:59]
	v_pk_mul_f32 v[60:61], v[52:53], v[60:61]
	v_cvt_pk_bf16_f32 v62, v62, v63
	v_cvt_pk_bf16_f32 v63, v64, v65
	v_cvt_pk_bf16_f32 v64, v58, v59
	v_cvt_pk_bf16_f32 v65, v60, v61
	v_pk_mul_f32 v[46:47], v[30:31], v[46:47]
	v_pk_mul_f32 v[48:49], v[32:33], v[48:49]
	v_pk_mul_f32 v[42:43], v[26:27], v[42:43]
	v_pk_mul_f32 v[44:45], v[28:29], v[44:45]
	v_cvt_pk_bf16_f32 v46, v46, v47
	v_cvt_pk_bf16_f32 v47, v48, v49
	v_cvt_pk_bf16_f32 v48, v42, v43
	v_cvt_pk_bf16_f32 v49, v44, v45
	v_lshrrev_b32_e32 v160, 1, v159
	global_store_dwordx4 v160, v[62:65], s[4:5]
	global_store_dwordx4 v160, v[46:49], s[4:5] offset:256
	s_waitcnt lgkmcnt(0)
	v_add_f32_e32 v169, v168, v169
	ds_bpermute_b32 v170, v167, v169
	v_add_u32_e32 v161, 0x2400, v174
	s_waitcnt lgkmcnt(0)
	v_add_f32_e32 v169, v169, v170
	s_and_saveexec_b64 s[2:3], s[6:7]
	global_store_dword v161, v169, s[10:11]
	s_or_b64 exec, exec, s[2:3]
	s_waitcnt vmcnt(32)
	v_pk_add_f32 v[38:39], v[38:39], v[188:189]
	v_pk_add_f32 v[40:41], v[40:41], v[190:191]
	v_pk_add_f32 v[34:35], v[34:35], v[192:193]
	v_pk_add_f32 v[36:37], v[36:37], v[194:195]
	v_pk_add_f32 v[22:23], v[22:23], v[196:197]
	v_pk_add_f32 v[24:25], v[24:25], v[198:199]
	v_pk_add_f32 v[18:19], v[18:19], v[200:201]
	v_pk_add_f32 v[20:21], v[20:21], v[202:203]
	v_add_u32_e32 v159, 0xa0000, v156
	global_store_dwordx4 v159, v[38:41], s[12:13]
	global_store_dwordx4 v159, v[34:37], s[12:13] offset:16
	global_store_dwordx4 v159, v[22:25], s[12:13] offset:512
	global_store_dwordx4 v159, v[18:21], s[12:13] offset:528
	v_mul_f32_e32 v169, v41, v41
	v_mul_f32_e32 v168, v39, v39
	v_fmac_f32_e32 v168, v38, v38
	v_fmac_f32_e32 v169, v40, v40
	v_add_f32_e32 v168, v168, v169
	v_mul_f32_e32 v169, v35, v35
	v_fmac_f32_e32 v169, v34, v34
	v_add_f32_e32 v168, v169, v168
	v_mul_f32_e32 v169, v37, v37
	v_fmac_f32_e32 v169, v36, v36
	v_add_f32_e32 v170, v169, v168
	v_mul_f32_e32 v169, v25, v25
	v_mul_f32_e32 v168, v23, v23
	v_fmac_f32_e32 v168, v22, v22
	v_fmac_f32_e32 v169, v24, v24
	v_add_f32_e32 v168, v168, v169
	v_mul_f32_e32 v169, v19, v19
	v_fmac_f32_e32 v169, v18, v18
	v_add_f32_e32 v168, v169, v168
	v_mul_f32_e32 v169, v21, v21
	v_fmac_f32_e32 v169, v20, v20
	v_add_f32_e32 v168, v169, v168
	v_add_f32_e32 v168, v170, v168
	ds_bpermute_b32 v169, v166, v168
	v_pk_mul_f32 v[38:39], v[54:55], v[38:39]
	v_pk_mul_f32 v[40:41], v[56:57], v[40:41]
	v_pk_mul_f32 v[34:35], v[50:51], v[34:35]
	v_pk_mul_f32 v[36:37], v[52:53], v[36:37]
	v_cvt_pk_bf16_f32 v38, v38, v39
	v_cvt_pk_bf16_f32 v39, v40, v41
	v_cvt_pk_bf16_f32 v40, v34, v35
	v_cvt_pk_bf16_f32 v41, v36, v37
	v_pk_mul_f32 v[22:23], v[30:31], v[22:23]
	v_pk_mul_f32 v[24:25], v[32:33], v[24:25]
	v_pk_mul_f32 v[18:19], v[26:27], v[18:19]
	v_pk_mul_f32 v[20:21], v[28:29], v[20:21]
	v_cvt_pk_bf16_f32 v22, v22, v23
	v_cvt_pk_bf16_f32 v23, v24, v25
	v_cvt_pk_bf16_f32 v24, v18, v19
	v_cvt_pk_bf16_f32 v25, v20, v21
	v_lshrrev_b32_e32 v160, 1, v159
	global_store_dwordx4 v160, v[38:41], s[4:5]
	global_store_dwordx4 v160, v[22:25], s[4:5] offset:256
	s_waitcnt lgkmcnt(0)
	v_add_f32_e32 v169, v168, v169
	ds_bpermute_b32 v170, v167, v169
	v_add_u32_e32 v161, 0x2800, v174
	s_waitcnt lgkmcnt(0)
	v_add_f32_e32 v169, v169, v170
	s_and_saveexec_b64 s[2:3], s[6:7]
	global_store_dword v161, v169, s[10:11]
	s_or_b64 exec, exec, s[2:3]
	s_waitcnt vmcnt(28)
	v_pk_add_f32 v[14:15], v[14:15], v[110:111]
	v_pk_add_f32 v[16:17], v[16:17], v[112:113]
	v_pk_add_f32 v[10:11], v[10:11], v[106:107]
	v_pk_add_f32 v[12:13], v[12:13], v[108:109]
	v_pk_add_f32 v[6:7], v[6:7], v[102:103]
	v_pk_add_f32 v[8:9], v[8:9], v[104:105]
	v_pk_add_f32 v[2:3], v[2:3], v[98:99]
	v_pk_add_f32 v[4:5], v[4:5], v[100:101]
	v_add_u32_e32 v159, 0xb0000, v156
	global_store_dwordx4 v159, v[14:17], s[12:13]
	global_store_dwordx4 v159, v[10:13], s[12:13] offset:16
	global_store_dwordx4 v159, v[6:9], s[12:13] offset:512
	global_store_dwordx4 v159, v[2:5], s[12:13] offset:528
	v_mul_f32_e32 v169, v17, v17
	v_mul_f32_e32 v168, v15, v15
	v_fmac_f32_e32 v168, v14, v14
	v_fmac_f32_e32 v169, v16, v16
	v_add_f32_e32 v168, v168, v169
	v_mul_f32_e32 v169, v11, v11
	v_fmac_f32_e32 v169, v10, v10
	v_add_f32_e32 v168, v169, v168
	v_mul_f32_e32 v169, v13, v13
	v_fmac_f32_e32 v169, v12, v12
	v_add_f32_e32 v170, v169, v168
	v_mul_f32_e32 v169, v9, v9
	v_mul_f32_e32 v168, v7, v7
	v_fmac_f32_e32 v168, v6, v6
	v_fmac_f32_e32 v169, v8, v8
	v_add_f32_e32 v168, v168, v169
	v_mul_f32_e32 v169, v3, v3
	v_fmac_f32_e32 v169, v2, v2
	v_add_f32_e32 v168, v169, v168
	v_mul_f32_e32 v169, v5, v5
	v_fmac_f32_e32 v169, v4, v4
	v_add_f32_e32 v168, v169, v168
	v_add_f32_e32 v168, v170, v168
	ds_bpermute_b32 v169, v166, v168
	v_pk_mul_f32 v[14:15], v[54:55], v[14:15]
	v_pk_mul_f32 v[16:17], v[56:57], v[16:17]
	v_pk_mul_f32 v[10:11], v[50:51], v[10:11]
	v_pk_mul_f32 v[12:13], v[52:53], v[12:13]
	v_cvt_pk_bf16_f32 v14, v14, v15
	v_cvt_pk_bf16_f32 v15, v16, v17
	v_cvt_pk_bf16_f32 v16, v10, v11
	v_cvt_pk_bf16_f32 v17, v12, v13
	v_pk_mul_f32 v[6:7], v[30:31], v[6:7]
	v_pk_mul_f32 v[8:9], v[32:33], v[8:9]
	v_pk_mul_f32 v[2:3], v[26:27], v[2:3]
	v_pk_mul_f32 v[4:5], v[28:29], v[4:5]
	v_cvt_pk_bf16_f32 v6, v6, v7
	v_cvt_pk_bf16_f32 v7, v8, v9
	v_cvt_pk_bf16_f32 v8, v2, v3
	v_cvt_pk_bf16_f32 v9, v4, v5
	v_lshrrev_b32_e32 v160, 1, v159
	global_store_dwordx4 v160, v[14:17], s[4:5]
	global_store_dwordx4 v160, v[6:9], s[4:5] offset:256
	s_waitcnt lgkmcnt(0)
	v_add_f32_e32 v169, v168, v169
	ds_bpermute_b32 v170, v167, v169
	v_add_u32_e32 v161, 0x2c00, v174
	s_waitcnt lgkmcnt(0)
	v_add_f32_e32 v169, v169, v170
	s_and_saveexec_b64 s[2:3], s[6:7]
	global_store_dword v161, v169, s[10:11]
	s_or_b64 exec, exec, s[2:3]
	s_andn2_b64 vcc, exec, s[8:9]
	s_mov_b64 s[2:3], -1
	s_cbranch_vccnz .LBB0_1686
	s_andn2_b64 vcc, exec, s[0:1]
	s_cbranch_vccnz .LBB0_1685
	s_barrier
	s_branch .LBB0_1685

.LBB0_1781:
	v_lshl_add_u32 v202, s37, 8, v170
	v_ashrrev_i32_e32 v203, 31, v202
	v_lshlrev_b64 v[130:131], 6, v[202:203]
	v_lshl_add_u64 v[130:131], v[168:169], 0, v[130:131]
	global_load_dwordx4 v[158:161], v[130:131], off
	v_or_b32_e32 v200, 16, v202
	v_ashrrev_i32_e32 v201, 31, v200
	v_lshlrev_b64 v[130:131], 6, v[200:201]
	v_lshl_add_u64 v[130:131], v[168:169], 0, v[130:131]
	global_load_dwordx4 v[154:157], v[130:131], off
	v_or_b32_e32 v198, 32, v202
	v_ashrrev_i32_e32 v199, 31, v198
	v_lshlrev_b64 v[130:131], 6, v[198:199]
	v_or_b32_e32 v196, 48, v202
	v_lshl_add_u64 v[130:131], v[168:169], 0, v[130:131]
	v_ashrrev_i32_e32 v197, 31, v196
	global_load_dwordx4 v[150:153], v[130:131], off
	v_lshlrev_b64 v[130:131], 6, v[196:197]
	v_add_u32_e32 v194, 0x80, v202
	v_lshl_add_u64 v[130:131], v[168:169], 0, v[130:131]
	v_ashrrev_i32_e32 v195, 31, v194
	global_load_dwordx4 v[146:149], v[130:131], off
	v_lshlrev_b64 v[130:131], 6, v[194:195]
	v_add_u32_e32 v192, 0x90, v202
	v_lshl_add_u64 v[130:131], v[168:169], 0, v[130:131]
	v_ashrrev_i32_e32 v193, 31, v192
	global_load_dwordx4 v[142:145], v[130:131], off
	v_lshlrev_b64 v[130:131], 6, v[192:193]
	v_add_u32_e32 v190, 0xa0, v202
	v_and_b32_e32 v175, 64, v230
	v_lshl_add_u64 v[130:131], v[168:169], 0, v[130:131]
	v_ashrrev_i32_e32 v191, 31, v190
	v_xor_b32_e32 v174, 16, v230
	v_add_u32_e32 v175, 64, v175
	global_load_dwordx4 v[138:141], v[130:131], off
	v_lshlrev_b64 v[130:131], 6, v[190:191]
	v_add_u32_e32 v188, 0xb0, v202
	v_cmp_lt_i32_e32 vcc, v174, v175
	v_lshl_add_u64 v[130:131], v[168:169], 0, v[130:131]
	v_ashrrev_i32_e32 v189, 31, v188
	v_cndmask_b32_e32 v174, v230, v174, vcc
	global_load_dwordx4 v[134:137], v[130:131], off
	v_lshlrev_b64 v[130:131], 6, v[188:189]
	v_lshlrev_b32_e32 v189, 2, v174
	v_xor_b32_e32 v174, 32, v230
	v_cmp_lt_i32_e32 vcc, v174, v175
	v_lshl_add_u64 v[130:131], v[168:169], 0, v[130:131]
	global_load_dwordx4 v[130:133], v[130:131], off
	v_cndmask_b32_e32 v174, v230, v174, vcc
	v_lshlrev_b32_e32 v191, 2, v174
	v_lshl_or_b32 v204, s36, 7, v183
	v_ashrrev_i32_e32 v205, 31, v204
	s_mov_b64 s[38:39], 0xc00
	s_mov_b64 s[40:41], 0x6000
	s_waitcnt vmcnt(0)
	v_mov_b32_e32 v174, v159
	v_mov_b32_e32 v175, v160
	v_mov_b32_e32 v159, v161
	v_pk_add_f32 v[158:159], v[174:175], v[158:159]
	s_nop 0
	v_add_f32_e32 v158, v158, v159
	ds_bpermute_b32 v159, v189, v158
	s_waitcnt lgkmcnt(0)
	v_add_f32_e32 v158, v158, v159
	ds_bpermute_b32 v159, v191, v158
	s_waitcnt lgkmcnt(0)
	v_add_f32_e32 v158, v158, v159
	v_fmamk_f32 v158, v158, 0x3a800000, v223
	s_nop 0
	s_nop 0
	s_nop 0
	s_nop 1
	s_nop 1
	s_nop 0
	v_mov_b32_e32 v160, v155
	v_mov_b32_e32 v161, v156
	v_mov_b32_e32 v155, v157
	v_pk_add_f32 v[154:155], v[160:161], v[154:155]
	v_rsq_f32_e32 v159, v158
	s_nop 0
	v_mul_f32_e32 v158, v158, v159
	v_fma_f32 v158, -v158, v159, 1.0
	v_mul_f32_e32 v158, 0.5, v158
	v_fma_f32 v158, v159, v158, v159
	v_add_f32_e32 v154, v154, v155
	ds_bpermute_b32 v155, v189, v154
	s_waitcnt lgkmcnt(0)
	v_add_f32_e32 v154, v154, v155
	ds_bpermute_b32 v155, v191, v154
	s_waitcnt lgkmcnt(0)
	v_add_f32_e32 v154, v154, v155
	v_fmamk_f32 v154, v154, 0x3a800000, v223
	s_nop 0
	s_nop 0
	s_nop 0
	s_nop 1
	s_nop 1
	s_nop 0
	v_pk_mul_f32 v[126:127], v[126:127], v[158:159] op_sel_hi:[1,0]
	v_pk_mul_f32 v[118:119], v[118:119], v[158:159] op_sel_hi:[1,0]
	v_pk_mul_f32 v[128:129], v[128:129], v[158:159] op_sel_hi:[1,0]
	v_mul_f32_e32 v118, v126, v118
	v_mul_f32_e32 v126, 0xbfb8aa3b, v126
	v_exp_f32_e32 v126, v126
	v_mul_f32_e32 v119, v127, v119
	v_pk_mul_f32 v[120:121], v[120:121], v[158:159] op_sel_hi:[1,0]
	v_add_f32_e32 v126, 1.0, v126
	v_rcp_f32_e32 v126, v126
	v_mov_b32_e32 v156, v151
	v_mov_b32_e32 v157, v152
	v_mul_f32_e32 v118, v118, v126
	v_mul_f32_e32 v126, 0xbfb8aa3b, v127
	v_exp_f32_e32 v126, v126
	v_mov_b32_e32 v151, v153
	v_pk_add_f32 v[150:151], v[156:157], v[150:151]
	v_pk_mul_f32 v[122:123], v[122:123], v[158:159] op_sel_hi:[1,0]
	v_add_f32_e32 v126, 1.0, v126
	v_rcp_f32_e32 v126, v126
	v_add_f32_e32 v150, v150, v151
	ds_bpermute_b32 v151, v189, v150
	v_pk_mul_f32 v[114:115], v[114:115], v[158:159] op_sel_hi:[1,0]
	v_mul_f32_e32 v119, v119, v126
	v_cvt_pk_bf16_f32 v118, v118, v119
	v_mul_f32_e32 v119, v128, v120
	v_mul_f32_e32 v120, 0xbfb8aa3b, v128
	v_exp_f32_e32 v120, v120
	s_waitcnt lgkmcnt(0)
	v_add_f32_e32 v150, v150, v151
	ds_bpermute_b32 v151, v191, v150
	v_mul_f32_e32 v114, v122, v114
	v_add_f32_e32 v120, 1.0, v120
	v_rcp_f32_e32 v120, v120
	v_mul_f32_e32 v115, v123, v115
	s_waitcnt lgkmcnt(0)
	v_add_f32_e32 v150, v150, v151
	v_fmamk_f32 v150, v150, 0x3a800000, v223
	v_mul_f32_e32 v119, v119, v120
	v_mul_f32_e32 v120, v129, v121
	v_mul_f32_e32 v121, 0xbfb8aa3b, v129
	v_exp_f32_e32 v121, v121
	v_pk_mul_f32 v[124:125], v[124:125], v[158:159] op_sel_hi:[1,0]
	v_add_f32_e32 v121, 1.0, v121
	v_rcp_f32_e32 v121, v121
	v_pk_mul_f32 v[116:117], v[116:117], v[158:159] op_sel_hi:[1,0]
	v_mul_f32_e32 v120, v120, v121
	v_cvt_pk_bf16_f32 v119, v119, v120
	v_mul_f32_e32 v120, 0xbfb8aa3b, v122
	v_exp_f32_e32 v120, v120
	s_nop 0
	v_add_f32_e32 v120, 1.0, v120
	v_rcp_f32_e32 v120, v120
	s_nop 0
	v_mul_f32_e32 v114, v114, v120
	v_mul_f32_e32 v120, 0xbfb8aa3b, v123
	v_exp_f32_e32 v120, v120
	v_rsq_f32_e32 v155, v154
	s_nop 0
	v_mul_f32_e32 v154, v154, v155
	v_fma_f32 v154, -v154, v155, 1.0
	v_mul_f32_e32 v154, 0.5, v154
	v_fma_f32 v154, v155, v154, v155
	v_add_f32_e32 v120, 1.0, v120
	v_rcp_f32_e32 v120, v120
	s_nop 0
	v_mul_f32_e32 v115, v115, v120
	v_cvt_pk_bf16_f32 v120, v114, v115
	v_mul_f32_e32 v115, 0xbfb8aa3b, v124
	v_mul_f32_e32 v114, v124, v116
	v_exp_f32_e32 v115, v115
	v_mul_f32_e32 v116, 0xbfb8aa3b, v125
	v_exp_f32_e32 v116, v116
	v_add_f32_e32 v115, 1.0, v115
	v_rcp_f32_e32 v115, v115
	v_add_f32_e32 v116, 1.0, v116
	v_rcp_f32_e32 v116, v116
	v_mul_f32_e32 v114, v114, v115
	v_mul_f32_e32 v115, v125, v117
	v_mul_f32_e32 v115, v115, v116
	v_cvt_pk_bf16_f32 v121, v114, v115
	v_mov_b64_e32 v[114:115], s[4:5]
	v_mad_i64_i32 v[122:123], s[2:3], v202, s64, v[114:115]
	v_lshlrev_b64 v[116:117], 1, v[204:205]
	v_lshl_add_u64 v[122:123], v[122:123], 0, v[116:117]
	v_pk_mul_f32 v[110:111], v[110:111], v[154:155] op_sel_hi:[1,0]
	global_store_dwordx4 v[122:123], v[118:121], off
	v_pk_mul_f32 v[102:103], v[102:103], v[154:155] op_sel_hi:[1,0]
	v_pk_mul_f32 v[112:113], v[112:113], v[154:155] op_sel_hi:[1,0]
	v_pk_mul_f32 v[118:119], v[100:101], v[154:155] op_sel_hi:[1,0]
	v_pk_mul_f32 v[100:101], v[98:99], v[154:155] op_sel_hi:[1,0]
	v_mul_f32_e32 v99, 0xbfb8aa3b, v110
	v_mul_f32_e32 v98, v110, v102
	v_exp_f32_e32 v99, v99
	v_mul_f32_e32 v102, 0xbfb8aa3b, v111
	v_exp_f32_e32 v102, v102
	v_add_f32_e32 v99, 1.0, v99
	v_rcp_f32_e32 v99, v99
	v_add_f32_e32 v102, 1.0, v102
	v_rcp_f32_e32 v102, v102
	v_mul_f32_e32 v98, v98, v99
	v_mul_f32_e32 v99, v111, v103
	v_mul_f32_e32 v99, v99, v102
	v_mul_f32_e32 v102, 0xbfb8aa3b, v112
	v_exp_f32_e32 v102, v102
	v_mul_f32_e32 v103, 0xbfb8aa3b, v113
	v_exp_f32_e32 v103, v103
	v_mov_b32_e32 v152, v147
	v_mov_b32_e32 v153, v148
	v_mov_b32_e32 v147, v149
	v_pk_add_f32 v[146:147], v[152:153], v[146:147]
	v_add_f32_e32 v102, 1.0, v102
	v_add_f32_e32 v146, v146, v147
	v_rcp_f32_e32 v102, v102
	v_add_f32_e32 v103, 1.0, v103
	ds_bpermute_b32 v147, v189, v146
	v_rcp_f32_e32 v103, v103
	v_pk_mul_f32 v[104:105], v[104:105], v[154:155] op_sel_hi:[1,0]
	v_cvt_pk_bf16_f32 v98, v98, v99
	v_pk_mul_f32 v[106:107], v[106:107], v[154:155] op_sel_hi:[1,0]
	v_mul_f32_e32 v99, v112, v104
	v_mul_f32_e32 v99, v99, v102
	v_mul_f32_e32 v102, v113, v105
	v_mul_f32_e32 v102, v102, v103
	s_waitcnt lgkmcnt(0)
	v_add_f32_e32 v146, v146, v147
	v_cvt_pk_bf16_f32 v99, v99, v102
	v_mul_f32_e32 v102, 0xbfb8aa3b, v106
	ds_bpermute_b32 v147, v191, v146
	v_exp_f32_e32 v102, v102
	v_mul_f32_e32 v100, v106, v100
	v_pk_mul_f32 v[108:109], v[108:109], v[154:155] op_sel_hi:[1,0]
	v_mul_f32_e32 v101, v107, v101
	v_add_f32_e32 v102, 1.0, v102
	s_waitcnt lgkmcnt(0)
	v_add_f32_e32 v146, v146, v147
	v_rcp_f32_e32 v102, v102
	v_fmamk_f32 v146, v146, 0x3a800000, v223
	v_mul_f32_e32 v100, v100, v102
	v_mul_f32_e32 v102, 0xbfb8aa3b, v107
	v_exp_f32_e32 v102, v102
	v_mul_f32_e32 v103, 0xbfb8aa3b, v109
	v_add_f32_e32 v102, 1.0, v102
	v_rcp_f32_e32 v102, v102
	s_nop 0
	v_mul_f32_e32 v101, v101, v102
	v_mul_f32_e32 v102, 0xbfb8aa3b, v108
	v_exp_f32_e32 v102, v102
	v_exp_f32_e32 v103, v103
	v_add_f32_e32 v102, 1.0, v102
	v_rcp_f32_e32 v102, v102
	v_add_f32_e32 v103, 1.0, v103
	v_rcp_f32_e32 v103, v103
	v_cvt_pk_bf16_f32 v100, v100, v101
	v_mul_f32_e32 v101, v108, v118
	v_rsq_f32_e32 v151, v150
	s_nop 0
	v_mul_f32_e32 v150, v150, v151
	v_fma_f32 v150, -v150, v151, 1.0
	v_mul_f32_e32 v150, 0.5, v150
	v_fma_f32 v150, v151, v150, v151
	v_mul_f32_e32 v101, v101, v102
	v_mul_f32_e32 v102, v109, v119
	v_mul_f32_e32 v102, v102, v103
	v_cvt_pk_bf16_f32 v101, v101, v102
	v_mad_i64_i32 v[102:103], s[2:3], v200, s64, v[114:115]
	v_lshl_add_u64 v[102:103], v[102:103], 0, v[116:117]
	v_pk_mul_f32 v[94:95], v[94:95], v[150:151] op_sel_hi:[1,0]
	global_store_dwordx4 v[102:103], v[98:101], off
	v_pk_mul_f32 v[86:87], v[86:87], v[150:151] op_sel_hi:[1,0]
	v_pk_mul_f32 v[96:97], v[96:97], v[150:151] op_sel_hi:[1,0]
	v_pk_mul_f32 v[98:99], v[84:85], v[150:151] op_sel_hi:[1,0]
	v_pk_mul_f32 v[84:85], v[82:83], v[150:151] op_sel_hi:[1,0]
	v_mul_f32_e32 v83, 0xbfb8aa3b, v94
	v_mul_f32_e32 v82, v94, v86
	v_exp_f32_e32 v83, v83
	v_mul_f32_e32 v86, 0xbfb8aa3b, v95
	v_exp_f32_e32 v86, v86
	v_add_f32_e32 v83, 1.0, v83
	v_rcp_f32_e32 v83, v83
	v_add_f32_e32 v86, 1.0, v86
	v_rcp_f32_e32 v86, v86
	v_mul_f32_e32 v82, v82, v83
	v_mul_f32_e32 v83, v95, v87
	v_mul_f32_e32 v83, v83, v86
	v_mul_f32_e32 v86, 0xbfb8aa3b, v96
	v_exp_f32_e32 v86, v86
	v_mul_f32_e32 v87, 0xbfb8aa3b, v97
	v_exp_f32_e32 v87, v87
	v_mov_b32_e32 v148, v143
	v_mov_b32_e32 v149, v144
	v_mov_b32_e32 v143, v145
	v_pk_add_f32 v[142:143], v[148:149], v[142:143]
	v_add_f32_e32 v86, 1.0, v86
	v_add_f32_e32 v142, v142, v143
	v_rcp_f32_e32 v86, v86
	v_add_f32_e32 v87, 1.0, v87
	ds_bpermute_b32 v143, v189, v142
	v_rcp_f32_e32 v87, v87
	v_pk_mul_f32 v[88:89], v[88:89], v[150:151] op_sel_hi:[1,0]
	v_cvt_pk_bf16_f32 v82, v82, v83
	v_pk_mul_f32 v[90:91], v[90:91], v[150:151] op_sel_hi:[1,0]
	v_mul_f32_e32 v83, v96, v88
	v_mul_f32_e32 v83, v83, v86
	v_mul_f32_e32 v86, v97, v89
	v_mul_f32_e32 v86, v86, v87
	s_waitcnt lgkmcnt(0)
	v_add_f32_e32 v142, v142, v143
	v_cvt_pk_bf16_f32 v83, v83, v86
	v_mul_f32_e32 v86, 0xbfb8aa3b, v90
	ds_bpermute_b32 v143, v191, v142
	v_exp_f32_e32 v86, v86
	v_mul_f32_e32 v84, v90, v84
	v_pk_mul_f32 v[92:93], v[92:93], v[150:151] op_sel_hi:[1,0]
	v_mul_f32_e32 v85, v91, v85
	v_add_f32_e32 v86, 1.0, v86
	s_waitcnt lgkmcnt(0)
	v_add_f32_e32 v142, v142, v143
	v_rcp_f32_e32 v86, v86
	v_fmamk_f32 v142, v142, 0x3a800000, v223
	v_mul_f32_e32 v84, v84, v86
	v_mul_f32_e32 v86, 0xbfb8aa3b, v91
	v_exp_f32_e32 v86, v86
	v_mul_f32_e32 v87, 0xbfb8aa3b, v93
	v_add_f32_e32 v86, 1.0, v86
	v_rcp_f32_e32 v86, v86
	s_nop 0
	v_mul_f32_e32 v85, v85, v86
	v_mul_f32_e32 v86, 0xbfb8aa3b, v92
	v_exp_f32_e32 v86, v86
	v_exp_f32_e32 v87, v87
	v_add_f32_e32 v86, 1.0, v86
	v_rcp_f32_e32 v86, v86
	v_add_f32_e32 v87, 1.0, v87
	v_rcp_f32_e32 v87, v87
	v_cvt_pk_bf16_f32 v84, v84, v85
	v_mul_f32_e32 v85, v92, v98
	v_rsq_f32_e32 v147, v146
	s_nop 0
	v_mul_f32_e32 v146, v146, v147
	v_fma_f32 v146, -v146, v147, 1.0
	v_mul_f32_e32 v146, 0.5, v146
	v_fma_f32 v146, v147, v146, v147
	v_mul_f32_e32 v85, v85, v86
	v_mul_f32_e32 v86, v93, v99
	v_mul_f32_e32 v86, v86, v87
	v_cvt_pk_bf16_f32 v85, v85, v86
	v_mad_i64_i32 v[86:87], s[2:3], v198, s64, v[114:115]
	v_lshl_add_u64 v[86:87], v[86:87], 0, v[116:117]
	v_pk_mul_f32 v[78:79], v[78:79], v[146:147] op_sel_hi:[1,0]
	global_store_dwordx4 v[86:87], v[82:85], off
	v_pk_mul_f32 v[70:71], v[70:71], v[146:147] op_sel_hi:[1,0]
	v_pk_mul_f32 v[80:81], v[80:81], v[146:147] op_sel_hi:[1,0]
	v_pk_mul_f32 v[82:83], v[68:69], v[146:147] op_sel_hi:[1,0]
	v_pk_mul_f32 v[68:69], v[66:67], v[146:147] op_sel_hi:[1,0]
	v_mul_f32_e32 v67, 0xbfb8aa3b, v78
	v_mul_f32_e32 v66, v78, v70
	v_exp_f32_e32 v67, v67
	v_mul_f32_e32 v70, 0xbfb8aa3b, v79
	v_exp_f32_e32 v70, v70
	v_add_f32_e32 v67, 1.0, v67
	v_rcp_f32_e32 v67, v67
	v_add_f32_e32 v70, 1.0, v70
	v_rcp_f32_e32 v70, v70
	v_mul_f32_e32 v66, v66, v67
	v_mul_f32_e32 v67, v79, v71
	v_mul_f32_e32 v67, v67, v70
	v_mul_f32_e32 v70, 0xbfb8aa3b, v80
	v_exp_f32_e32 v70, v70
	v_mul_f32_e32 v71, 0xbfb8aa3b, v81
	v_exp_f32_e32 v71, v71
	v_mov_b32_e32 v144, v139
	v_mov_b32_e32 v145, v140
	v_mov_b32_e32 v139, v141
	v_pk_add_f32 v[138:139], v[144:145], v[138:139]
	v_add_f32_e32 v70, 1.0, v70
	v_add_f32_e32 v138, v138, v139
	v_rcp_f32_e32 v70, v70
	v_add_f32_e32 v71, 1.0, v71
	ds_bpermute_b32 v139, v189, v138
	v_rcp_f32_e32 v71, v71
	v_pk_mul_f32 v[72:73], v[72:73], v[146:147] op_sel_hi:[1,0]
	v_cvt_pk_bf16_f32 v66, v66, v67
	v_pk_mul_f32 v[74:75], v[74:75], v[146:147] op_sel_hi:[1,0]
	v_mul_f32_e32 v67, v80, v72
	v_mul_f32_e32 v67, v67, v70
	v_mul_f32_e32 v70, v81, v73
	v_mul_f32_e32 v70, v70, v71
	s_waitcnt lgkmcnt(0)
	v_add_f32_e32 v138, v138, v139
	v_cvt_pk_bf16_f32 v67, v67, v70
	v_mul_f32_e32 v70, 0xbfb8aa3b, v74
	ds_bpermute_b32 v139, v191, v138
	v_exp_f32_e32 v70, v70
	v_mul_f32_e32 v68, v74, v68
	v_pk_mul_f32 v[76:77], v[76:77], v[146:147] op_sel_hi:[1,0]
	v_mul_f32_e32 v69, v75, v69
	v_add_f32_e32 v70, 1.0, v70
	s_waitcnt lgkmcnt(0)
	v_add_f32_e32 v138, v138, v139
	v_rcp_f32_e32 v70, v70
	v_fmamk_f32 v138, v138, 0x3a800000, v223
	v_mul_f32_e32 v68, v68, v70
	v_mul_f32_e32 v70, 0xbfb8aa3b, v75
	v_exp_f32_e32 v70, v70
	v_mul_f32_e32 v71, 0xbfb8aa3b, v77
	v_add_f32_e32 v70, 1.0, v70
	v_rcp_f32_e32 v70, v70
	s_nop 0
	v_mul_f32_e32 v69, v69, v70
	v_mul_f32_e32 v70, 0xbfb8aa3b, v76
	v_exp_f32_e32 v70, v70
	v_exp_f32_e32 v71, v71
	v_add_f32_e32 v70, 1.0, v70
	v_rcp_f32_e32 v70, v70
	v_add_f32_e32 v71, 1.0, v71
	v_rcp_f32_e32 v71, v71
	v_cvt_pk_bf16_f32 v68, v68, v69
	v_mul_f32_e32 v69, v76, v82
	v_rsq_f32_e32 v143, v142
	s_nop 0
	v_mul_f32_e32 v142, v142, v143
	v_fma_f32 v142, -v142, v143, 1.0
	v_mul_f32_e32 v142, 0.5, v142
	v_fma_f32 v142, v143, v142, v143
	v_mul_f32_e32 v69, v69, v70
	v_mul_f32_e32 v70, v77, v83
	v_mul_f32_e32 v70, v70, v71
	v_cvt_pk_bf16_f32 v69, v69, v70
	v_mad_i64_i32 v[70:71], s[2:3], v196, s64, v[114:115]
	v_lshl_add_u64 v[70:71], v[70:71], 0, v[116:117]
	v_pk_mul_f32 v[62:63], v[62:63], v[142:143] op_sel_hi:[1,0]
	global_store_dwordx4 v[70:71], v[66:69], off
	v_pk_mul_f32 v[54:55], v[54:55], v[142:143] op_sel_hi:[1,0]
	v_pk_mul_f32 v[64:65], v[64:65], v[142:143] op_sel_hi:[1,0]
	v_pk_mul_f32 v[66:67], v[52:53], v[142:143] op_sel_hi:[1,0]
	v_pk_mul_f32 v[52:53], v[50:51], v[142:143] op_sel_hi:[1,0]
	v_mul_f32_e32 v51, 0xbfb8aa3b, v62
	v_mul_f32_e32 v50, v62, v54
	v_exp_f32_e32 v51, v51
	v_mul_f32_e32 v54, 0xbfb8aa3b, v63
	v_exp_f32_e32 v54, v54
	v_add_f32_e32 v51, 1.0, v51
	v_rcp_f32_e32 v51, v51
	v_add_f32_e32 v54, 1.0, v54
	v_rcp_f32_e32 v54, v54
	v_mul_f32_e32 v50, v50, v51
	v_mul_f32_e32 v51, v63, v55
	v_mul_f32_e32 v51, v51, v54
	v_mul_f32_e32 v54, 0xbfb8aa3b, v64
	v_exp_f32_e32 v54, v54
	v_mul_f32_e32 v55, 0xbfb8aa3b, v65
	v_exp_f32_e32 v55, v55
	v_mov_b32_e32 v140, v135
	v_mov_b32_e32 v141, v136
	v_mov_b32_e32 v135, v137
	v_pk_add_f32 v[134:135], v[140:141], v[134:135]
	v_add_f32_e32 v54, 1.0, v54
	v_add_f32_e32 v134, v134, v135
	v_rcp_f32_e32 v54, v54
	v_add_f32_e32 v55, 1.0, v55
	ds_bpermute_b32 v135, v189, v134
	v_rcp_f32_e32 v55, v55
	v_pk_mul_f32 v[56:57], v[56:57], v[142:143] op_sel_hi:[1,0]
	v_cvt_pk_bf16_f32 v50, v50, v51
	v_pk_mul_f32 v[58:59], v[58:59], v[142:143] op_sel_hi:[1,0]
	v_mul_f32_e32 v51, v64, v56
	v_mul_f32_e32 v51, v51, v54
	v_mul_f32_e32 v54, v65, v57
	v_mul_f32_e32 v54, v54, v55
	s_waitcnt lgkmcnt(0)
	v_add_f32_e32 v134, v134, v135
	v_cvt_pk_bf16_f32 v51, v51, v54
	v_mul_f32_e32 v54, 0xbfb8aa3b, v58
	ds_bpermute_b32 v135, v191, v134
	v_exp_f32_e32 v54, v54
	v_mul_f32_e32 v52, v58, v52
	v_pk_mul_f32 v[60:61], v[60:61], v[142:143] op_sel_hi:[1,0]
	v_mul_f32_e32 v53, v59, v53
	v_add_f32_e32 v54, 1.0, v54
	s_waitcnt lgkmcnt(0)
	v_add_f32_e32 v134, v134, v135
	v_rcp_f32_e32 v54, v54
	v_fmamk_f32 v134, v134, 0x3a800000, v223
	v_mul_f32_e32 v52, v52, v54
	v_mul_f32_e32 v54, 0xbfb8aa3b, v59
	v_exp_f32_e32 v54, v54
	v_mul_f32_e32 v55, 0xbfb8aa3b, v61
	v_add_f32_e32 v54, 1.0, v54
	v_rcp_f32_e32 v54, v54
	s_nop 0
	v_mul_f32_e32 v53, v53, v54
	v_mul_f32_e32 v54, 0xbfb8aa3b, v60
	v_exp_f32_e32 v54, v54
	v_exp_f32_e32 v55, v55
	v_add_f32_e32 v54, 1.0, v54
	v_rcp_f32_e32 v54, v54
	v_add_f32_e32 v55, 1.0, v55
	v_rcp_f32_e32 v55, v55
	v_cvt_pk_bf16_f32 v52, v52, v53
	v_mul_f32_e32 v53, v60, v66
	v_rsq_f32_e32 v139, v138
	s_nop 0
	v_mul_f32_e32 v138, v138, v139
	v_fma_f32 v138, -v138, v139, 1.0
	v_mul_f32_e32 v138, 0.5, v138
	v_fma_f32 v138, v139, v138, v139
	v_mul_f32_e32 v53, v53, v54
	v_mul_f32_e32 v54, v61, v67
	v_mul_f32_e32 v54, v54, v55
	v_cvt_pk_bf16_f32 v53, v53, v54
	v_mad_i64_i32 v[54:55], s[2:3], v194, s64, v[114:115]
	v_lshl_add_u64 v[54:55], v[54:55], 0, v[116:117]
	v_pk_mul_f32 v[46:47], v[46:47], v[138:139] op_sel_hi:[1,0]
	global_store_dwordx4 v[54:55], v[50:53], off
	v_pk_mul_f32 v[38:39], v[38:39], v[138:139] op_sel_hi:[1,0]
	v_pk_mul_f32 v[48:49], v[48:49], v[138:139] op_sel_hi:[1,0]
	v_pk_mul_f32 v[50:51], v[36:37], v[138:139] op_sel_hi:[1,0]
	v_pk_mul_f32 v[36:37], v[34:35], v[138:139] op_sel_hi:[1,0]
	v_mul_f32_e32 v35, 0xbfb8aa3b, v46
	v_mul_f32_e32 v34, v46, v38
	v_exp_f32_e32 v35, v35
	v_mul_f32_e32 v38, 0xbfb8aa3b, v47
	v_exp_f32_e32 v38, v38
	v_add_f32_e32 v35, 1.0, v35
	v_rcp_f32_e32 v35, v35
	v_add_f32_e32 v38, 1.0, v38
	v_rcp_f32_e32 v38, v38
	v_mul_f32_e32 v34, v34, v35
	v_mul_f32_e32 v35, v47, v39
	v_mul_f32_e32 v35, v35, v38
	v_mul_f32_e32 v38, 0xbfb8aa3b, v48
	v_exp_f32_e32 v38, v38
	v_mul_f32_e32 v39, 0xbfb8aa3b, v49
	v_exp_f32_e32 v39, v39
	v_mov_b32_e32 v136, v131
	v_mov_b32_e32 v137, v132
	v_mov_b32_e32 v131, v133
	v_pk_add_f32 v[130:131], v[136:137], v[130:131]
	v_add_f32_e32 v38, 1.0, v38
	v_add_f32_e32 v130, v130, v131
	v_rcp_f32_e32 v38, v38
	v_add_f32_e32 v39, 1.0, v39
	ds_bpermute_b32 v131, v189, v130
	v_rcp_f32_e32 v39, v39
	v_pk_mul_f32 v[40:41], v[40:41], v[138:139] op_sel_hi:[1,0]
	v_cvt_pk_bf16_f32 v34, v34, v35
	v_pk_mul_f32 v[42:43], v[42:43], v[138:139] op_sel_hi:[1,0]
	v_mul_f32_e32 v35, v48, v40
	v_mul_f32_e32 v35, v35, v38
	v_mul_f32_e32 v38, v49, v41
	v_mul_f32_e32 v38, v38, v39
	s_waitcnt lgkmcnt(0)
	v_add_f32_e32 v130, v130, v131
	v_cvt_pk_bf16_f32 v35, v35, v38
	v_mul_f32_e32 v38, 0xbfb8aa3b, v42
	ds_bpermute_b32 v131, v191, v130
	v_exp_f32_e32 v38, v38
	v_mul_f32_e32 v36, v42, v36
	v_pk_mul_f32 v[44:45], v[44:45], v[138:139] op_sel_hi:[1,0]
	v_mul_f32_e32 v37, v43, v37
	v_add_f32_e32 v38, 1.0, v38
	s_waitcnt lgkmcnt(0)
	v_add_f32_e32 v130, v130, v131
	v_rcp_f32_e32 v38, v38
	v_fmamk_f32 v130, v130, 0x3a800000, v223
	v_mul_f32_e32 v36, v36, v38
	v_mul_f32_e32 v38, 0xbfb8aa3b, v43
	v_exp_f32_e32 v38, v38
	v_mul_f32_e32 v39, 0xbfb8aa3b, v45
	v_add_f32_e32 v38, 1.0, v38
	v_rcp_f32_e32 v38, v38
	s_nop 0
	v_mul_f32_e32 v37, v37, v38
	v_mul_f32_e32 v38, 0xbfb8aa3b, v44
	v_exp_f32_e32 v38, v38
	v_exp_f32_e32 v39, v39
	v_add_f32_e32 v38, 1.0, v38
	v_rcp_f32_e32 v38, v38
	v_add_f32_e32 v39, 1.0, v39
	v_rcp_f32_e32 v39, v39
	v_cvt_pk_bf16_f32 v36, v36, v37
	v_mul_f32_e32 v37, v44, v50
	v_rsq_f32_e32 v135, v134
	s_nop 0
	v_mul_f32_e32 v134, v134, v135
	v_fma_f32 v134, -v134, v135, 1.0
	v_mul_f32_e32 v134, 0.5, v134
	v_fma_f32 v134, v135, v134, v135
	v_mul_f32_e32 v37, v37, v38
	v_mul_f32_e32 v38, v45, v51
	v_mul_f32_e32 v38, v38, v39
	v_cvt_pk_bf16_f32 v37, v37, v38
	v_mad_i64_i32 v[38:39], s[2:3], v192, s64, v[114:115]
	v_lshl_add_u64 v[38:39], v[38:39], 0, v[116:117]
	v_pk_mul_f32 v[30:31], v[30:31], v[134:135] op_sel_hi:[1,0]
	global_store_dwordx4 v[38:39], v[34:37], off
	v_pk_mul_f32 v[22:23], v[22:23], v[134:135] op_sel_hi:[1,0]
	v_pk_mul_f32 v[32:33], v[32:33], v[134:135] op_sel_hi:[1,0]
	v_pk_mul_f32 v[34:35], v[20:21], v[134:135] op_sel_hi:[1,0]
	v_pk_mul_f32 v[20:21], v[18:19], v[134:135] op_sel_hi:[1,0]
	v_mul_f32_e32 v19, 0xbfb8aa3b, v30
	v_mul_f32_e32 v18, v30, v22
	v_exp_f32_e32 v19, v19
	v_mul_f32_e32 v22, 0xbfb8aa3b, v31
	v_exp_f32_e32 v22, v22
	v_pk_mul_f32 v[24:25], v[24:25], v[134:135] op_sel_hi:[1,0]
	v_add_f32_e32 v19, 1.0, v19
	v_rcp_f32_e32 v19, v19
	v_add_f32_e32 v22, 1.0, v22
	v_rcp_f32_e32 v22, v22
	v_pk_mul_f32 v[26:27], v[26:27], v[134:135] op_sel_hi:[1,0]
	v_mul_f32_e32 v18, v18, v19
	v_mul_f32_e32 v19, v31, v23
	v_mul_f32_e32 v19, v19, v22
	v_mul_f32_e32 v22, 0xbfb8aa3b, v32
	v_exp_f32_e32 v22, v22
	v_mul_f32_e32 v23, 0xbfb8aa3b, v33
	v_exp_f32_e32 v23, v23
	v_cvt_pk_bf16_f32 v18, v18, v19
	v_add_f32_e32 v22, 1.0, v22
	v_rcp_f32_e32 v22, v22
	v_add_f32_e32 v23, 1.0, v23
	v_rcp_f32_e32 v23, v23
	v_mul_f32_e32 v19, v32, v24
	v_mul_f32_e32 v19, v19, v22
	v_mul_f32_e32 v22, v33, v25
	v_mul_f32_e32 v22, v22, v23
	v_cvt_pk_bf16_f32 v19, v19, v22
	v_mul_f32_e32 v22, 0xbfb8aa3b, v26
	v_exp_f32_e32 v22, v22
	v_mul_f32_e32 v20, v26, v20
	v_pk_mul_f32 v[28:29], v[28:29], v[134:135] op_sel_hi:[1,0]
	v_mul_f32_e32 v21, v27, v21
	v_add_f32_e32 v22, 1.0, v22
	v_rcp_f32_e32 v22, v22
	v_mul_f32_e32 v23, 0xbfb8aa3b, v29
	v_exp_f32_e32 v23, v23
	v_mul_f32_e32 v20, v20, v22
	v_mul_f32_e32 v22, 0xbfb8aa3b, v27
	v_exp_f32_e32 v22, v22
	v_add_f32_e32 v23, 1.0, v23
	v_rcp_f32_e32 v23, v23
	v_add_f32_e32 v22, 1.0, v22
	v_rcp_f32_e32 v22, v22
	v_rsq_f32_e32 v131, v130
	s_nop 0
	v_mul_f32_e32 v130, v130, v131
	v_fma_f32 v130, -v130, v131, 1.0
	v_mul_f32_e32 v130, 0.5, v130
	v_fma_f32 v130, v131, v130, v131
	v_pk_mul_f32 v[14:15], v[14:15], v[130:131] op_sel_hi:[1,0]
	v_pk_mul_f32 v[6:7], v[6:7], v[130:131] op_sel_hi:[1,0]
	v_mul_f32_e32 v21, v21, v22
	v_mul_f32_e32 v22, 0xbfb8aa3b, v28
	v_exp_f32_e32 v22, v22
	v_cvt_pk_bf16_f32 v20, v20, v21
	v_mul_f32_e32 v21, v28, v34
	v_pk_mul_f32 v[16:17], v[16:17], v[130:131] op_sel_hi:[1,0]
	v_add_f32_e32 v22, 1.0, v22
	v_rcp_f32_e32 v22, v22
	v_pk_mul_f32 v[8:9], v[8:9], v[130:131] op_sel_hi:[1,0]
	v_pk_mul_f32 v[10:11], v[10:11], v[130:131] op_sel_hi:[1,0]
	v_pk_mul_f32 v[12:13], v[12:13], v[130:131] op_sel_hi:[1,0]
	v_mul_f32_e32 v21, v21, v22
	v_mul_f32_e32 v22, v29, v35
	v_mul_f32_e32 v22, v22, v23
	v_cvt_pk_bf16_f32 v21, v21, v22
	v_mad_i64_i32 v[22:23], s[2:3], v190, s64, v[114:115]
	v_lshl_add_u64 v[22:23], v[22:23], 0, v[116:117]
	global_store_dwordx4 v[22:23], v[18:21], off
	s_andn2_b64 vcc, exec, s[6:7]
	s_nop 0
	v_pk_mul_f32 v[18:19], v[4:5], v[130:131] op_sel_hi:[1,0]
	v_pk_mul_f32 v[4:5], v[2:3], v[130:131] op_sel_hi:[1,0]
	v_mul_f32_e32 v3, 0xbfb8aa3b, v14
	v_mul_f32_e32 v2, v14, v6
	v_exp_f32_e32 v3, v3
	v_mul_f32_e32 v6, 0xbfb8aa3b, v15
	v_exp_f32_e32 v6, v6
	v_mul_f32_e32 v4, v10, v4
	v_add_f32_e32 v3, 1.0, v3
	v_rcp_f32_e32 v3, v3
	v_add_f32_e32 v6, 1.0, v6
	v_rcp_f32_e32 v6, v6
	v_mul_f32_e32 v5, v11, v5
	v_mul_f32_e32 v2, v2, v3
	v_mul_f32_e32 v3, v15, v7
	v_mul_f32_e32 v3, v3, v6
	v_mul_f32_e32 v6, 0xbfb8aa3b, v16
	v_exp_f32_e32 v6, v6
	v_mul_f32_e32 v7, 0xbfb8aa3b, v17
	v_exp_f32_e32 v7, v7
	v_cvt_pk_bf16_f32 v2, v2, v3
	v_add_f32_e32 v6, 1.0, v6
	v_rcp_f32_e32 v6, v6
	v_add_f32_e32 v7, 1.0, v7
	v_rcp_f32_e32 v7, v7
	v_mul_f32_e32 v3, v16, v8
	v_mul_f32_e32 v3, v3, v6
	v_mul_f32_e32 v6, v17, v9
	v_mul_f32_e32 v6, v6, v7
	v_cvt_pk_bf16_f32 v3, v3, v6
	v_mul_f32_e32 v6, 0xbfb8aa3b, v10
	v_exp_f32_e32 v6, v6
	v_mul_f32_e32 v7, 0xbfb8aa3b, v13
	v_exp_f32_e32 v7, v7
	v_add_f32_e32 v6, 1.0, v6
	v_rcp_f32_e32 v6, v6
	v_add_f32_e32 v7, 1.0, v7
	v_rcp_f32_e32 v7, v7
	v_mul_f32_e32 v4, v4, v6
	v_mul_f32_e32 v6, 0xbfb8aa3b, v11
	v_exp_f32_e32 v6, v6
	s_nop 0
	v_add_f32_e32 v6, 1.0, v6
	v_rcp_f32_e32 v6, v6
	s_nop 0
	v_mul_f32_e32 v5, v5, v6
	v_mul_f32_e32 v6, 0xbfb8aa3b, v12
	v_exp_f32_e32 v6, v6
	v_cvt_pk_bf16_f32 v4, v4, v5
	v_mul_f32_e32 v5, v12, v18
	v_add_f32_e32 v6, 1.0, v6
	v_rcp_f32_e32 v6, v6
	s_nop 0
	v_mul_f32_e32 v5, v5, v6
	v_mul_f32_e32 v6, v13, v19
	v_mul_f32_e32 v6, v6, v7
	v_cvt_pk_bf16_f32 v5, v5, v6
	v_mad_i64_i32 v[6:7], s[2:3], v188, s64, v[114:115]
	v_lshl_add_u64 v[6:7], v[6:7], 0, v[116:117]
	s_mov_b64 s[2:3], -1
	global_store_dwordx4 v[6:7], v[2:5], off
	s_cbranch_vccnz .LBB0_1774
	s_andn2_b64 vcc, exec, s[0:1]
	s_cbranch_vccnz .LBB0_1773
	s_barrier
	s_branch .LBB0_1773

.LBB0_1861:
	v_lshl_add_u32 v158, s46, 8, v162
	v_lshl_or_b32 v159, s45, 8, v164
	v_lshlrev_b32_e32 v160, 2, v159
	v_lshl_add_u32 v156, v158, 12, v160
	global_load_dwordx4 v[54:57], v160, s[0:1]
	global_load_dwordx4 v[50:53], v160, s[0:1] offset:16
	global_load_dwordx4 v[30:33], v160, s[0:1] offset:512
	global_load_dwordx4 v[26:29], v160, s[0:1] offset:528
	global_load_dwordx4 v[188:191], v156, s[12:13]
	global_load_dwordx4 v[192:195], v156, s[12:13] offset:16
	global_load_dwordx4 v[196:199], v156, s[12:13] offset:512
	global_load_dwordx4 v[200:203], v156, s[12:13] offset:528
	v_add_u32_e32 v157, 0x10000, v156
	global_load_dwordx4 v[204:207], v157, s[12:13]
	global_load_dwordx4 v[208:211], v157, s[12:13] offset:16
	global_load_dwordx4 v[212:215], v157, s[12:13] offset:512
	global_load_dwordx4 v[216:219], v157, s[12:13] offset:528
	s_lshl_b32 s22, s45, 2
	s_add_i32 s22, s22, s39
	s_lshl_b32 s22, s22, 2
	v_lshlrev_b32_e32 v174, 6, v158
	v_add_u32_e32 v174, s22, v174
	v_mbcnt_hi_u32_b32 v166, -1, v253
	v_xor_b32_e32 v167, 32, v166
	v_xor_b32_e32 v166, 16, v166
	v_lshlrev_b32_e32 v166, 2, v166
	v_lshlrev_b32_e32 v167, 2, v167
	s_waitcnt vmcnt(4)
	v_pk_fma_f32 v[142:143], v[142:143], 0.5, v[188:189] op_sel_hi:[1,0,1]
	v_pk_fma_f32 v[144:145], v[144:145], 0.5, v[190:191] op_sel_hi:[1,0,1]
	v_pk_fma_f32 v[138:139], v[138:139], 0.5, v[192:193] op_sel_hi:[1,0,1]
	v_pk_fma_f32 v[140:141], v[140:141], 0.5, v[194:195] op_sel_hi:[1,0,1]
	v_pk_fma_f32 v[134:135], v[134:135], 0.5, v[196:197] op_sel_hi:[1,0,1]
	v_pk_fma_f32 v[136:137], v[136:137], 0.5, v[198:199] op_sel_hi:[1,0,1]
	v_pk_fma_f32 v[130:131], v[130:131], 0.5, v[200:201] op_sel_hi:[1,0,1]
	v_pk_fma_f32 v[132:133], v[132:133], 0.5, v[202:203] op_sel_hi:[1,0,1]
	v_add_u32_e32 v157, 0x20000, v156
	global_load_dwordx4 v[188:191], v157, s[12:13]
	global_load_dwordx4 v[192:195], v157, s[12:13] offset:16
	global_load_dwordx4 v[196:199], v157, s[12:13] offset:512
	global_load_dwordx4 v[200:203], v157, s[12:13] offset:528
	v_mov_b32_e32 v159, v156
	global_store_dwordx4 v159, v[142:145], s[12:13]
	global_store_dwordx4 v159, v[138:141], s[12:13] offset:16
	global_store_dwordx4 v159, v[134:137], s[12:13] offset:512
	global_store_dwordx4 v159, v[130:133], s[12:13] offset:528
	v_mul_f32_e32 v169, v145, v145
	v_mul_f32_e32 v168, v143, v143
	v_fmac_f32_e32 v168, v142, v142
	v_fmac_f32_e32 v169, v144, v144
	v_add_f32_e32 v168, v168, v169
	v_mul_f32_e32 v169, v139, v139
	v_fmac_f32_e32 v169, v138, v138
	v_add_f32_e32 v168, v169, v168
	v_mul_f32_e32 v169, v141, v141
	v_fmac_f32_e32 v169, v140, v140
	v_add_f32_e32 v170, v169, v168
	v_mul_f32_e32 v169, v137, v137
	v_mul_f32_e32 v168, v135, v135
	v_fmac_f32_e32 v168, v134, v134
	v_fmac_f32_e32 v169, v136, v136
	v_add_f32_e32 v168, v168, v169
	v_mul_f32_e32 v169, v131, v131
	v_fmac_f32_e32 v169, v130, v130
	v_add_f32_e32 v168, v169, v168
	v_mul_f32_e32 v169, v133, v133
	v_fmac_f32_e32 v169, v132, v132
	v_add_f32_e32 v168, v169, v168
	v_add_f32_e32 v168, v170, v168
	ds_bpermute_b32 v169, v166, v168
	v_pk_mul_f32 v[142:143], v[54:55], v[142:143]
	v_pk_mul_f32 v[144:145], v[56:57], v[144:145]
	v_pk_mul_f32 v[138:139], v[50:51], v[138:139]
	v_pk_mul_f32 v[140:141], v[52:53], v[140:141]
	v_cvt_pk_bf16_f32 v142, v142, v143
	v_cvt_pk_bf16_f32 v143, v144, v145
	v_cvt_pk_bf16_f32 v144, v138, v139
	v_cvt_pk_bf16_f32 v145, v140, v141
	v_pk_mul_f32 v[134:135], v[30:31], v[134:135]
	v_pk_mul_f32 v[136:137], v[32:33], v[136:137]
	v_pk_mul_f32 v[130:131], v[26:27], v[130:131]
	v_pk_mul_f32 v[132:133], v[28:29], v[132:133]
	v_cvt_pk_bf16_f32 v134, v134, v135
	v_cvt_pk_bf16_f32 v135, v136, v137
	v_cvt_pk_bf16_f32 v136, v130, v131
	v_cvt_pk_bf16_f32 v137, v132, v133
	v_lshrrev_b32_e32 v160, 1, v159
	global_store_dwordx4 v160, v[142:145], s[16:17]
	global_store_dwordx4 v160, v[134:137], s[16:17] offset:256
	s_waitcnt lgkmcnt(0)
	v_add_f32_e32 v169, v168, v169
	ds_bpermute_b32 v170, v167, v169
	v_mov_b32_e32 v161, v174
	s_waitcnt lgkmcnt(0)
	v_add_f32_e32 v169, v169, v170
	s_and_saveexec_b64 s[2:3], s[4:5]
	global_store_dword v161, v169, s[14:15]
	s_or_b64 exec, exec, s[2:3]
	v_add_u32_e32 v157, 0x30000, v156
	global_load_dwordx4 v[142:145], v157, s[12:13]
	global_load_dwordx4 v[138:141], v157, s[12:13] offset:16
	global_load_dwordx4 v[134:137], v157, s[12:13] offset:512
	global_load_dwordx4 v[130:133], v157, s[12:13] offset:528
	s_waitcnt vmcnt(15)
	v_pk_fma_f32 v[126:127], v[126:127], 0.5, v[204:205] op_sel_hi:[1,0,1]
	v_pk_fma_f32 v[128:129], v[128:129], 0.5, v[206:207] op_sel_hi:[1,0,1]
	v_pk_fma_f32 v[122:123], v[122:123], 0.5, v[208:209] op_sel_hi:[1,0,1]
	v_pk_fma_f32 v[124:125], v[124:125], 0.5, v[210:211] op_sel_hi:[1,0,1]
	v_pk_fma_f32 v[118:119], v[118:119], 0.5, v[212:213] op_sel_hi:[1,0,1]
	v_pk_fma_f32 v[120:121], v[120:121], 0.5, v[214:215] op_sel_hi:[1,0,1]
	v_pk_fma_f32 v[114:115], v[114:115], 0.5, v[216:217] op_sel_hi:[1,0,1]
	v_pk_fma_f32 v[116:117], v[116:117], 0.5, v[218:219] op_sel_hi:[1,0,1]
	v_add_u32_e32 v157, 0x80000, v156
	global_load_dwordx4 v[204:207], v157, s[12:13]
	global_load_dwordx4 v[208:211], v157, s[12:13] offset:16
	global_load_dwordx4 v[212:215], v157, s[12:13] offset:512
	global_load_dwordx4 v[216:219], v157, s[12:13] offset:528
	v_add_u32_e32 v159, 0x10000, v156
	global_store_dwordx4 v159, v[126:129], s[12:13]
	global_store_dwordx4 v159, v[122:125], s[12:13] offset:16
	global_store_dwordx4 v159, v[118:121], s[12:13] offset:512
	global_store_dwordx4 v159, v[114:117], s[12:13] offset:528
	v_mul_f32_e32 v169, v129, v129
	v_mul_f32_e32 v168, v127, v127
	v_fmac_f32_e32 v168, v126, v126
	v_fmac_f32_e32 v169, v128, v128
	v_add_f32_e32 v168, v168, v169
	v_mul_f32_e32 v169, v123, v123
	v_fmac_f32_e32 v169, v122, v122
	v_add_f32_e32 v168, v169, v168
	v_mul_f32_e32 v169, v125, v125
	v_fmac_f32_e32 v169, v124, v124
	v_add_f32_e32 v170, v169, v168
	v_mul_f32_e32 v169, v121, v121
	v_mul_f32_e32 v168, v119, v119
	v_fmac_f32_e32 v168, v118, v118
	v_fmac_f32_e32 v169, v120, v120
	v_add_f32_e32 v168, v168, v169
	v_mul_f32_e32 v169, v115, v115
	v_fmac_f32_e32 v169, v114, v114
	v_add_f32_e32 v168, v169, v168
	v_mul_f32_e32 v169, v117, v117
	v_fmac_f32_e32 v169, v116, v116
	v_add_f32_e32 v168, v169, v168
	v_add_f32_e32 v168, v170, v168
	ds_bpermute_b32 v169, v166, v168
	v_pk_mul_f32 v[126:127], v[54:55], v[126:127]
	v_pk_mul_f32 v[128:129], v[56:57], v[128:129]
	v_pk_mul_f32 v[122:123], v[50:51], v[122:123]
	v_pk_mul_f32 v[124:125], v[52:53], v[124:125]
	v_cvt_pk_bf16_f32 v126, v126, v127
	v_cvt_pk_bf16_f32 v127, v128, v129
	v_cvt_pk_bf16_f32 v128, v122, v123
	v_cvt_pk_bf16_f32 v129, v124, v125
	v_pk_mul_f32 v[118:119], v[30:31], v[118:119]
	v_pk_mul_f32 v[120:121], v[32:33], v[120:121]
	v_pk_mul_f32 v[114:115], v[26:27], v[114:115]
	v_pk_mul_f32 v[116:117], v[28:29], v[116:117]
	v_cvt_pk_bf16_f32 v118, v118, v119
	v_cvt_pk_bf16_f32 v119, v120, v121
	v_cvt_pk_bf16_f32 v120, v114, v115
	v_cvt_pk_bf16_f32 v121, v116, v117
	v_lshrrev_b32_e32 v160, 1, v159
	global_store_dwordx4 v160, v[126:129], s[16:17]
	global_store_dwordx4 v160, v[118:121], s[16:17] offset:256
	s_waitcnt lgkmcnt(0)
	v_add_f32_e32 v169, v168, v169
	ds_bpermute_b32 v170, v167, v169
	v_add_u32_e32 v161, 0x400, v174
	s_waitcnt lgkmcnt(0)
	v_add_f32_e32 v169, v169, v170
	s_and_saveexec_b64 s[2:3], s[4:5]
	global_store_dword v161, v169, s[14:15]
	s_or_b64 exec, exec, s[2:3]
	v_add_u32_e32 v157, 0x90000, v156
	global_load_dwordx4 v[126:129], v157, s[12:13]
	global_load_dwordx4 v[122:125], v157, s[12:13] offset:16
	global_load_dwordx4 v[118:121], v157, s[12:13] offset:512
	global_load_dwordx4 v[114:117], v157, s[12:13] offset:528
	s_waitcnt vmcnt(26)
	v_pk_fma_f32 v[110:111], v[110:111], 0.5, v[188:189] op_sel_hi:[1,0,1]
	v_pk_fma_f32 v[112:113], v[112:113], 0.5, v[190:191] op_sel_hi:[1,0,1]
	v_pk_fma_f32 v[106:107], v[106:107], 0.5, v[192:193] op_sel_hi:[1,0,1]
	v_pk_fma_f32 v[108:109], v[108:109], 0.5, v[194:195] op_sel_hi:[1,0,1]
	v_pk_fma_f32 v[102:103], v[102:103], 0.5, v[196:197] op_sel_hi:[1,0,1]
	v_pk_fma_f32 v[104:105], v[104:105], 0.5, v[198:199] op_sel_hi:[1,0,1]
	v_pk_fma_f32 v[98:99], v[98:99], 0.5, v[200:201] op_sel_hi:[1,0,1]
	v_pk_fma_f32 v[100:101], v[100:101], 0.5, v[202:203] op_sel_hi:[1,0,1]
	v_add_u32_e32 v157, 0xa0000, v156
	global_load_dwordx4 v[188:191], v157, s[12:13]
	global_load_dwordx4 v[192:195], v157, s[12:13] offset:16
	global_load_dwordx4 v[196:199], v157, s[12:13] offset:512
	global_load_dwordx4 v[200:203], v157, s[12:13] offset:528
	v_add_u32_e32 v159, 0x20000, v156
	global_store_dwordx4 v159, v[110:113], s[12:13]
	global_store_dwordx4 v159, v[106:109], s[12:13] offset:16
	global_store_dwordx4 v159, v[102:105], s[12:13] offset:512
	global_store_dwordx4 v159, v[98:101], s[12:13] offset:528
	v_mul_f32_e32 v169, v113, v113
	v_mul_f32_e32 v168, v111, v111
	v_fmac_f32_e32 v168, v110, v110
	v_fmac_f32_e32 v169, v112, v112
	v_add_f32_e32 v168, v168, v169
	v_mul_f32_e32 v169, v107, v107
	v_fmac_f32_e32 v169, v106, v106
	v_add_f32_e32 v168, v169, v168
	v_mul_f32_e32 v169, v109, v109
	v_fmac_f32_e32 v169, v108, v108
	v_add_f32_e32 v170, v169, v168
	v_mul_f32_e32 v169, v105, v105
	v_mul_f32_e32 v168, v103, v103
	v_fmac_f32_e32 v168, v102, v102
	v_fmac_f32_e32 v169, v104, v104
	v_add_f32_e32 v168, v168, v169
	v_mul_f32_e32 v169, v99, v99
	v_fmac_f32_e32 v169, v98, v98
	v_add_f32_e32 v168, v169, v168
	v_mul_f32_e32 v169, v101, v101
	v_fmac_f32_e32 v169, v100, v100
	v_add_f32_e32 v168, v169, v168
	v_add_f32_e32 v168, v170, v168
	ds_bpermute_b32 v169, v166, v168
	v_pk_mul_f32 v[110:111], v[54:55], v[110:111]
	v_pk_mul_f32 v[112:113], v[56:57], v[112:113]
	v_pk_mul_f32 v[106:107], v[50:51], v[106:107]
	v_pk_mul_f32 v[108:109], v[52:53], v[108:109]
	v_cvt_pk_bf16_f32 v110, v110, v111
	v_cvt_pk_bf16_f32 v111, v112, v113
	v_cvt_pk_bf16_f32 v112, v106, v107
	v_cvt_pk_bf16_f32 v113, v108, v109
	v_pk_mul_f32 v[102:103], v[30:31], v[102:103]
	v_pk_mul_f32 v[104:105], v[32:33], v[104:105]
	v_pk_mul_f32 v[98:99], v[26:27], v[98:99]
	v_pk_mul_f32 v[100:101], v[28:29], v[100:101]
	v_cvt_pk_bf16_f32 v102, v102, v103
	v_cvt_pk_bf16_f32 v103, v104, v105
	v_cvt_pk_bf16_f32 v104, v98, v99
	v_cvt_pk_bf16_f32 v105, v100, v101
	v_lshrrev_b32_e32 v160, 1, v159
	global_store_dwordx4 v160, v[110:113], s[16:17]
	global_store_dwordx4 v160, v[102:105], s[16:17] offset:256
	s_waitcnt lgkmcnt(0)
	v_add_f32_e32 v169, v168, v169
	ds_bpermute_b32 v170, v167, v169
	v_add_u32_e32 v161, 0x800, v174
	s_waitcnt lgkmcnt(0)
	v_add_f32_e32 v169, v169, v170
	s_and_saveexec_b64 s[2:3], s[4:5]
	global_store_dword v161, v169, s[14:15]
	s_or_b64 exec, exec, s[2:3]
	v_add_u32_e32 v157, 0xb0000, v156
	global_load_dwordx4 v[110:113], v157, s[12:13]
	global_load_dwordx4 v[106:109], v157, s[12:13] offset:16
	global_load_dwordx4 v[102:105], v157, s[12:13] offset:512
	global_load_dwordx4 v[98:101], v157, s[12:13] offset:528
	s_waitcnt vmcnt(30)
	v_pk_fma_f32 v[94:95], v[94:95], 0.5, v[142:143] op_sel_hi:[1,0,1]
	v_pk_fma_f32 v[96:97], v[96:97], 0.5, v[144:145] op_sel_hi:[1,0,1]
	v_pk_fma_f32 v[90:91], v[90:91], 0.5, v[138:139] op_sel_hi:[1,0,1]
	v_pk_fma_f32 v[92:93], v[92:93], 0.5, v[140:141] op_sel_hi:[1,0,1]
	v_pk_fma_f32 v[86:87], v[86:87], 0.5, v[134:135] op_sel_hi:[1,0,1]
	v_pk_fma_f32 v[88:89], v[88:89], 0.5, v[136:137] op_sel_hi:[1,0,1]
	v_pk_fma_f32 v[82:83], v[82:83], 0.5, v[130:131] op_sel_hi:[1,0,1]
	v_pk_fma_f32 v[84:85], v[84:85], 0.5, v[132:133] op_sel_hi:[1,0,1]
	v_add_u32_e32 v159, 0x30000, v156
	global_store_dwordx4 v159, v[94:97], s[12:13]
	global_store_dwordx4 v159, v[90:93], s[12:13] offset:16
	global_store_dwordx4 v159, v[86:89], s[12:13] offset:512
	global_store_dwordx4 v159, v[82:85], s[12:13] offset:528
	v_mul_f32_e32 v169, v97, v97
	v_mul_f32_e32 v168, v95, v95
	v_fmac_f32_e32 v168, v94, v94
	v_fmac_f32_e32 v169, v96, v96
	v_add_f32_e32 v168, v168, v169
	v_mul_f32_e32 v169, v91, v91
	v_fmac_f32_e32 v169, v90, v90
	v_add_f32_e32 v168, v169, v168
	v_mul_f32_e32 v169, v93, v93
	v_fmac_f32_e32 v169, v92, v92
	v_add_f32_e32 v170, v169, v168
	v_mul_f32_e32 v169, v89, v89
	v_mul_f32_e32 v168, v87, v87
	v_fmac_f32_e32 v168, v86, v86
	v_fmac_f32_e32 v169, v88, v88
	v_add_f32_e32 v168, v168, v169
	v_mul_f32_e32 v169, v83, v83
	v_fmac_f32_e32 v169, v82, v82
	v_add_f32_e32 v168, v169, v168
	v_mul_f32_e32 v169, v85, v85
	v_fmac_f32_e32 v169, v84, v84
	v_add_f32_e32 v168, v169, v168
	v_add_f32_e32 v168, v170, v168
	ds_bpermute_b32 v169, v166, v168
	v_pk_mul_f32 v[94:95], v[54:55], v[94:95]
	v_pk_mul_f32 v[96:97], v[56:57], v[96:97]
	v_pk_mul_f32 v[90:91], v[50:51], v[90:91]
	v_pk_mul_f32 v[92:93], v[52:53], v[92:93]
	v_cvt_pk_bf16_f32 v94, v94, v95
	v_cvt_pk_bf16_f32 v95, v96, v97
	v_cvt_pk_bf16_f32 v96, v90, v91
	v_cvt_pk_bf16_f32 v97, v92, v93
	v_pk_mul_f32 v[86:87], v[30:31], v[86:87]
	v_pk_mul_f32 v[88:89], v[32:33], v[88:89]
	v_pk_mul_f32 v[82:83], v[26:27], v[82:83]
	v_pk_mul_f32 v[84:85], v[28:29], v[84:85]
	v_cvt_pk_bf16_f32 v86, v86, v87
	v_cvt_pk_bf16_f32 v87, v88, v89
	v_cvt_pk_bf16_f32 v88, v82, v83
	v_cvt_pk_bf16_f32 v89, v84, v85
	v_lshrrev_b32_e32 v160, 1, v159
	global_store_dwordx4 v160, v[94:97], s[16:17]
	global_store_dwordx4 v160, v[86:89], s[16:17] offset:256
	s_waitcnt lgkmcnt(0)
	v_add_f32_e32 v169, v168, v169
	ds_bpermute_b32 v170, v167, v169
	v_add_u32_e32 v161, 0xc00, v174
	s_waitcnt lgkmcnt(0)
	v_add_f32_e32 v169, v169, v170
	s_and_saveexec_b64 s[2:3], s[4:5]
	global_store_dword v161, v169, s[14:15]
	s_or_b64 exec, exec, s[2:3]
	s_waitcnt vmcnt(33)
	v_pk_fma_f32 v[78:79], v[78:79], 0.5, v[204:205] op_sel_hi:[1,0,1]
	v_pk_fma_f32 v[80:81], v[80:81], 0.5, v[206:207] op_sel_hi:[1,0,1]
	v_pk_fma_f32 v[74:75], v[74:75], 0.5, v[208:209] op_sel_hi:[1,0,1]
	v_pk_fma_f32 v[76:77], v[76:77], 0.5, v[210:211] op_sel_hi:[1,0,1]
	v_pk_fma_f32 v[70:71], v[70:71], 0.5, v[212:213] op_sel_hi:[1,0,1]
	v_pk_fma_f32 v[72:73], v[72:73], 0.5, v[214:215] op_sel_hi:[1,0,1]
	v_pk_fma_f32 v[66:67], v[66:67], 0.5, v[216:217] op_sel_hi:[1,0,1]
	v_pk_fma_f32 v[68:69], v[68:69], 0.5, v[218:219] op_sel_hi:[1,0,1]
	v_add_u32_e32 v159, 0x80000, v156
	global_store_dwordx4 v159, v[78:81], s[12:13]
	global_store_dwordx4 v159, v[74:77], s[12:13] offset:16
	global_store_dwordx4 v159, v[70:73], s[12:13] offset:512
	global_store_dwordx4 v159, v[66:69], s[12:13] offset:528
	v_mul_f32_e32 v169, v81, v81
	v_mul_f32_e32 v168, v79, v79
	v_fmac_f32_e32 v168, v78, v78
	v_fmac_f32_e32 v169, v80, v80
	v_add_f32_e32 v168, v168, v169
	v_mul_f32_e32 v169, v75, v75
	v_fmac_f32_e32 v169, v74, v74
	v_add_f32_e32 v168, v169, v168
	v_mul_f32_e32 v169, v77, v77
	v_fmac_f32_e32 v169, v76, v76
	v_add_f32_e32 v170, v169, v168
	v_mul_f32_e32 v169, v73, v73
	v_mul_f32_e32 v168, v71, v71
	v_fmac_f32_e32 v168, v70, v70
	v_fmac_f32_e32 v169, v72, v72
	v_add_f32_e32 v168, v168, v169
	v_mul_f32_e32 v169, v67, v67
	v_fmac_f32_e32 v169, v66, v66
	v_add_f32_e32 v168, v169, v168
	v_mul_f32_e32 v169, v69, v69
	v_fmac_f32_e32 v169, v68, v68
	v_add_f32_e32 v168, v169, v168
	v_add_f32_e32 v168, v170, v168
	ds_bpermute_b32 v169, v166, v168
	v_pk_mul_f32 v[78:79], v[54:55], v[78:79]
	v_pk_mul_f32 v[80:81], v[56:57], v[80:81]
	v_pk_mul_f32 v[74:75], v[50:51], v[74:75]
	v_pk_mul_f32 v[76:77], v[52:53], v[76:77]
	v_cvt_pk_bf16_f32 v78, v78, v79
	v_cvt_pk_bf16_f32 v79, v80, v81
	v_cvt_pk_bf16_f32 v80, v74, v75
	v_cvt_pk_bf16_f32 v81, v76, v77
	v_pk_mul_f32 v[70:71], v[30:31], v[70:71]
	v_pk_mul_f32 v[72:73], v[32:33], v[72:73]
	v_pk_mul_f32 v[66:67], v[26:27], v[66:67]
	v_pk_mul_f32 v[68:69], v[28:29], v[68:69]
	v_cvt_pk_bf16_f32 v70, v70, v71
	v_cvt_pk_bf16_f32 v71, v72, v73
	v_cvt_pk_bf16_f32 v72, v66, v67
	v_cvt_pk_bf16_f32 v73, v68, v69
	v_lshrrev_b32_e32 v160, 1, v159
	global_store_dwordx4 v160, v[78:81], s[16:17]
	global_store_dwordx4 v160, v[70:73], s[16:17] offset:256
	s_waitcnt lgkmcnt(0)
	v_add_f32_e32 v169, v168, v169
	ds_bpermute_b32 v170, v167, v169
	v_add_u32_e32 v161, 0x2000, v174
	s_waitcnt lgkmcnt(0)
	v_add_f32_e32 v169, v169, v170
	s_and_saveexec_b64 s[2:3], s[4:5]
	global_store_dword v161, v169, s[14:15]
	s_or_b64 exec, exec, s[2:3]
	s_waitcnt vmcnt(29)
	v_pk_fma_f32 v[62:63], v[62:63], 0.5, v[126:127] op_sel_hi:[1,0,1]
	v_pk_fma_f32 v[64:65], v[64:65], 0.5, v[128:129] op_sel_hi:[1,0,1]
	v_pk_fma_f32 v[58:59], v[58:59], 0.5, v[122:123] op_sel_hi:[1,0,1]
	v_pk_fma_f32 v[60:61], v[60:61], 0.5, v[124:125] op_sel_hi:[1,0,1]
	v_pk_fma_f32 v[46:47], v[46:47], 0.5, v[118:119] op_sel_hi:[1,0,1]
	v_pk_fma_f32 v[48:49], v[48:49], 0.5, v[120:121] op_sel_hi:[1,0,1]
	v_pk_fma_f32 v[42:43], v[42:43], 0.5, v[114:115] op_sel_hi:[1,0,1]
	v_pk_fma_f32 v[44:45], v[44:45], 0.5, v[116:117] op_sel_hi:[1,0,1]
	v_add_u32_e32 v159, 0x90000, v156
	global_store_dwordx4 v159, v[62:65], s[12:13]
	global_store_dwordx4 v159, v[58:61], s[12:13] offset:16
	global_store_dwordx4 v159, v[46:49], s[12:13] offset:512
	global_store_dwordx4 v159, v[42:45], s[12:13] offset:528
	v_mul_f32_e32 v169, v65, v65
	v_mul_f32_e32 v168, v63, v63
	v_fmac_f32_e32 v168, v62, v62
	v_fmac_f32_e32 v169, v64, v64
	v_add_f32_e32 v168, v168, v169
	v_mul_f32_e32 v169, v59, v59
	v_fmac_f32_e32 v169, v58, v58
	v_add_f32_e32 v168, v169, v168
	v_mul_f32_e32 v169, v61, v61
	v_fmac_f32_e32 v169, v60, v60
	v_add_f32_e32 v170, v169, v168
	v_mul_f32_e32 v169, v49, v49
	v_mul_f32_e32 v168, v47, v47
	v_fmac_f32_e32 v168, v46, v46
	v_fmac_f32_e32 v169, v48, v48
	v_add_f32_e32 v168, v168, v169
	v_mul_f32_e32 v169, v43, v43
	v_fmac_f32_e32 v169, v42, v42
	v_add_f32_e32 v168, v169, v168
	v_mul_f32_e32 v169, v45, v45
	v_fmac_f32_e32 v169, v44, v44
	v_add_f32_e32 v168, v169, v168
	v_add_f32_e32 v168, v170, v168
	ds_bpermute_b32 v169, v166, v168
	v_pk_mul_f32 v[62:63], v[54:55], v[62:63]
	v_pk_mul_f32 v[64:65], v[56:57], v[64:65]
	v_pk_mul_f32 v[58:59], v[50:51], v[58:59]
	v_pk_mul_f32 v[60:61], v[52:53], v[60:61]
	v_cvt_pk_bf16_f32 v62, v62, v63
	v_cvt_pk_bf16_f32 v63, v64, v65
	v_cvt_pk_bf16_f32 v64, v58, v59
	v_cvt_pk_bf16_f32 v65, v60, v61
	v_pk_mul_f32 v[46:47], v[30:31], v[46:47]
	v_pk_mul_f32 v[48:49], v[32:33], v[48:49]
	v_pk_mul_f32 v[42:43], v[26:27], v[42:43]
	v_pk_mul_f32 v[44:45], v[28:29], v[44:45]
	v_cvt_pk_bf16_f32 v46, v46, v47
	v_cvt_pk_bf16_f32 v47, v48, v49
	v_cvt_pk_bf16_f32 v48, v42, v43
	v_cvt_pk_bf16_f32 v49, v44, v45
	v_lshrrev_b32_e32 v160, 1, v159
	global_store_dwordx4 v160, v[62:65], s[16:17]
	global_store_dwordx4 v160, v[46:49], s[16:17] offset:256
	s_waitcnt lgkmcnt(0)
	v_add_f32_e32 v169, v168, v169
	ds_bpermute_b32 v170, v167, v169
	v_add_u32_e32 v161, 0x2400, v174
	s_waitcnt lgkmcnt(0)
	v_add_f32_e32 v169, v169, v170
	s_and_saveexec_b64 s[2:3], s[4:5]
	global_store_dword v161, v169, s[14:15]
	s_or_b64 exec, exec, s[2:3]
	s_waitcnt vmcnt(32)
	v_pk_fma_f32 v[38:39], v[38:39], 0.5, v[188:189] op_sel_hi:[1,0,1]
	v_pk_fma_f32 v[40:41], v[40:41], 0.5, v[190:191] op_sel_hi:[1,0,1]
	v_pk_fma_f32 v[34:35], v[34:35], 0.5, v[192:193] op_sel_hi:[1,0,1]
	v_pk_fma_f32 v[36:37], v[36:37], 0.5, v[194:195] op_sel_hi:[1,0,1]
	v_pk_fma_f32 v[22:23], v[22:23], 0.5, v[196:197] op_sel_hi:[1,0,1]
	v_pk_fma_f32 v[24:25], v[24:25], 0.5, v[198:199] op_sel_hi:[1,0,1]
	v_pk_fma_f32 v[18:19], v[18:19], 0.5, v[200:201] op_sel_hi:[1,0,1]
	v_pk_fma_f32 v[20:21], v[20:21], 0.5, v[202:203] op_sel_hi:[1,0,1]
	v_add_u32_e32 v159, 0xa0000, v156
	global_store_dwordx4 v159, v[38:41], s[12:13]
	global_store_dwordx4 v159, v[34:37], s[12:13] offset:16
	global_store_dwordx4 v159, v[22:25], s[12:13] offset:512
	global_store_dwordx4 v159, v[18:21], s[12:13] offset:528
	v_mul_f32_e32 v169, v41, v41
	v_mul_f32_e32 v168, v39, v39
	v_fmac_f32_e32 v168, v38, v38
	v_fmac_f32_e32 v169, v40, v40
	v_add_f32_e32 v168, v168, v169
	v_mul_f32_e32 v169, v35, v35
	v_fmac_f32_e32 v169, v34, v34
	v_add_f32_e32 v168, v169, v168
	v_mul_f32_e32 v169, v37, v37
	v_fmac_f32_e32 v169, v36, v36
	v_add_f32_e32 v170, v169, v168
	v_mul_f32_e32 v169, v25, v25
	v_mul_f32_e32 v168, v23, v23
	v_fmac_f32_e32 v168, v22, v22
	v_fmac_f32_e32 v169, v24, v24
	v_add_f32_e32 v168, v168, v169
	v_mul_f32_e32 v169, v19, v19
	v_fmac_f32_e32 v169, v18, v18
	v_add_f32_e32 v168, v169, v168
	v_mul_f32_e32 v169, v21, v21
	v_fmac_f32_e32 v169, v20, v20
	v_add_f32_e32 v168, v169, v168
	v_add_f32_e32 v168, v170, v168
	ds_bpermute_b32 v169, v166, v168
	v_pk_mul_f32 v[38:39], v[54:55], v[38:39]
	v_pk_mul_f32 v[40:41], v[56:57], v[40:41]
	v_pk_mul_f32 v[34:35], v[50:51], v[34:35]
	v_pk_mul_f32 v[36:37], v[52:53], v[36:37]
	v_cvt_pk_bf16_f32 v38, v38, v39
	v_cvt_pk_bf16_f32 v39, v40, v41
	v_cvt_pk_bf16_f32 v40, v34, v35
	v_cvt_pk_bf16_f32 v41, v36, v37
	v_pk_mul_f32 v[22:23], v[30:31], v[22:23]
	v_pk_mul_f32 v[24:25], v[32:33], v[24:25]
	v_pk_mul_f32 v[18:19], v[26:27], v[18:19]
	v_pk_mul_f32 v[20:21], v[28:29], v[20:21]
	v_cvt_pk_bf16_f32 v22, v22, v23
	v_cvt_pk_bf16_f32 v23, v24, v25
	v_cvt_pk_bf16_f32 v24, v18, v19
	v_cvt_pk_bf16_f32 v25, v20, v21
	v_lshrrev_b32_e32 v160, 1, v159
	global_store_dwordx4 v160, v[38:41], s[16:17]
	global_store_dwordx4 v160, v[22:25], s[16:17] offset:256
	s_waitcnt lgkmcnt(0)
	v_add_f32_e32 v169, v168, v169
	ds_bpermute_b32 v170, v167, v169
	v_add_u32_e32 v161, 0x2800, v174
	s_waitcnt lgkmcnt(0)
	v_add_f32_e32 v169, v169, v170
	s_and_saveexec_b64 s[2:3], s[4:5]
	global_store_dword v161, v169, s[14:15]
	s_or_b64 exec, exec, s[2:3]
	s_waitcnt vmcnt(28)
	v_pk_fma_f32 v[14:15], v[14:15], 0.5, v[110:111] op_sel_hi:[1,0,1]
	v_pk_fma_f32 v[16:17], v[16:17], 0.5, v[112:113] op_sel_hi:[1,0,1]
	v_pk_fma_f32 v[10:11], v[10:11], 0.5, v[106:107] op_sel_hi:[1,0,1]
	v_pk_fma_f32 v[12:13], v[12:13], 0.5, v[108:109] op_sel_hi:[1,0,1]
	v_pk_fma_f32 v[6:7], v[6:7], 0.5, v[102:103] op_sel_hi:[1,0,1]
	v_pk_fma_f32 v[8:9], v[8:9], 0.5, v[104:105] op_sel_hi:[1,0,1]
	v_pk_fma_f32 v[2:3], v[2:3], 0.5, v[98:99] op_sel_hi:[1,0,1]
	v_pk_fma_f32 v[4:5], v[4:5], 0.5, v[100:101] op_sel_hi:[1,0,1]
	v_add_u32_e32 v159, 0xb0000, v156
	global_store_dwordx4 v159, v[14:17], s[12:13]
	global_store_dwordx4 v159, v[10:13], s[12:13] offset:16
	global_store_dwordx4 v159, v[6:9], s[12:13] offset:512
	global_store_dwordx4 v159, v[2:5], s[12:13] offset:528
	v_mul_f32_e32 v169, v17, v17
	v_mul_f32_e32 v168, v15, v15
	v_fmac_f32_e32 v168, v14, v14
	v_fmac_f32_e32 v169, v16, v16
	v_add_f32_e32 v168, v168, v169
	v_mul_f32_e32 v169, v11, v11
	v_fmac_f32_e32 v169, v10, v10
	v_add_f32_e32 v168, v169, v168
	v_mul_f32_e32 v169, v13, v13
	v_fmac_f32_e32 v169, v12, v12
	v_add_f32_e32 v170, v169, v168
	v_mul_f32_e32 v169, v9, v9
	v_mul_f32_e32 v168, v7, v7
	v_fmac_f32_e32 v168, v6, v6
	v_fmac_f32_e32 v169, v8, v8
	v_add_f32_e32 v168, v168, v169
	v_mul_f32_e32 v169, v3, v3
	v_fmac_f32_e32 v169, v2, v2
	v_add_f32_e32 v168, v169, v168
	v_mul_f32_e32 v169, v5, v5
	v_fmac_f32_e32 v169, v4, v4
	v_add_f32_e32 v168, v169, v168
	v_add_f32_e32 v168, v170, v168
	ds_bpermute_b32 v169, v166, v168
	v_pk_mul_f32 v[14:15], v[54:55], v[14:15]
	v_pk_mul_f32 v[16:17], v[56:57], v[16:17]
	v_pk_mul_f32 v[10:11], v[50:51], v[10:11]
	v_pk_mul_f32 v[12:13], v[52:53], v[12:13]
	v_cvt_pk_bf16_f32 v14, v14, v15
	v_cvt_pk_bf16_f32 v15, v16, v17
	v_cvt_pk_bf16_f32 v16, v10, v11
	v_cvt_pk_bf16_f32 v17, v12, v13
	v_pk_mul_f32 v[6:7], v[30:31], v[6:7]
	v_pk_mul_f32 v[8:9], v[32:33], v[8:9]
	v_pk_mul_f32 v[2:3], v[26:27], v[2:3]
	v_pk_mul_f32 v[4:5], v[28:29], v[4:5]
	v_cvt_pk_bf16_f32 v6, v6, v7
	v_cvt_pk_bf16_f32 v7, v8, v9
	v_cvt_pk_bf16_f32 v8, v2, v3
	v_cvt_pk_bf16_f32 v9, v4, v5
	v_lshrrev_b32_e32 v160, 1, v159
	global_store_dwordx4 v160, v[14:17], s[16:17]
	global_store_dwordx4 v160, v[6:9], s[16:17] offset:256
	s_waitcnt lgkmcnt(0)
	v_add_f32_e32 v169, v168, v169
	ds_bpermute_b32 v170, v167, v169
	v_add_u32_e32 v161, 0x2c00, v174
	s_waitcnt lgkmcnt(0)
	v_add_f32_e32 v169, v169, v170
	s_and_saveexec_b64 s[2:3], s[4:5]
	global_store_dword v161, v169, s[14:15]
	s_or_b64 exec, exec, s[2:3]
	s_and_b64 vcc, exec, s[6:7]
	s_mov_b64 s[2:3], -1
	s_cbranch_vccnz .LBB0_1846
	s_andn2_b64 vcc, exec, s[10:11]
	s_cbranch_vccnz .LBB0_1845
	s_barrier
	s_branch .LBB0_1845

.LBB0_1934:
	global_load_dwordx4 v[24:27], v[16:17], off
	global_load_dwordx4 v[28:31], v[18:19], off offset:-2048
	global_load_dwordx4 v[32:35], v[18:19], off offset:-1024
	global_load_dwordx4 v[36:39], v[18:19], off
	global_load_dwordx4 v[40:43], v[18:19], off offset:1024
	s_add_i32 s8, s8, s68
	v_lshl_add_u64 v[16:17], v[16:17], 0, s[2:3]
	s_cmpk_gt_i32 s8, 0x7fff
	s_waitcnt vmcnt(4)
	v_mov_b32_e32 v44, v25
	v_mov_b32_e32 v45, v26
	v_mov_b32_e32 v25, v27
	v_pk_add_f32 v[24:25], v[44:45], v[24:25]
	s_waitcnt vmcnt(3)
	v_pk_mul_f32 v[26:27], v[2:3], v[30:31]
	v_add_f32_e32 v24, v24, v25
	ds_bpermute_b32 v25, v20, v24
	s_waitcnt vmcnt(2)
	v_pk_mul_f32 v[30:31], v[6:7], v[34:35]
	s_waitcnt vmcnt(1)
	v_pk_mul_f32 v[34:35], v[10:11], v[38:39]
	s_waitcnt vmcnt(0)
	v_pk_mul_f32 v[38:39], v[14:15], v[42:43]
	v_pk_mul_f32 v[28:29], v[0:1], v[28:29]
	s_waitcnt lgkmcnt(0)
	v_add_f32_e32 v24, v24, v25
	ds_bpermute_b32 v25, v21, v24
	v_pk_mul_f32 v[32:33], v[4:5], v[32:33]
	v_pk_mul_f32 v[36:37], v[8:9], v[36:37]
	v_pk_mul_f32 v[40:41], v[12:13], v[40:41]
	s_waitcnt lgkmcnt(0)
	v_add_f32_e32 v24, v24, v25
	v_fmamk_f32 v24, v24, 0x3a800000, v22
	s_nop 1
	s_nop 0
	s_nop 1
	s_nop 1
	s_nop 1
	v_rsq_f32_e32 v25, v24
	s_nop 0
	v_mul_f32_e32 v42, v24, v25
	v_fma_f32 v42, -v42, v25, 1.0
	v_mul_f32_e32 v42, 0.5, v42
	v_fma_f32 v42, v25, v42, v25
	v_pk_mul_f32 v[26:27], v[42:43], v[26:27] op_sel_hi:[0,1]
	v_pk_mul_f32 v[24:25], v[42:43], v[28:29] op_sel_hi:[0,1]
	v_pk_mul_f32 v[30:31], v[42:43], v[30:31] op_sel_hi:[0,1]
	v_pk_mul_f32 v[28:29], v[42:43], v[32:33] op_sel_hi:[0,1]
	v_pk_mul_f32 v[34:35], v[42:43], v[34:35] op_sel_hi:[0,1]
	v_pk_mul_f32 v[32:33], v[42:43], v[36:37] op_sel_hi:[0,1]
	v_pk_mul_f32 v[38:39], v[42:43], v[38:39] op_sel_hi:[0,1]
	v_pk_mul_f32 v[36:37], v[42:43], v[40:41] op_sel_hi:[0,1]
	global_store_dwordx4 v[18:19], v[24:27], off offset:-2048
	global_store_dwordx4 v[18:19], v[28:31], off offset:-1024
	global_store_dwordx4 v[18:19], v[32:35], off
	global_store_dwordx4 v[18:19], v[36:39], off offset:1024
	v_lshl_add_u64 v[18:19], v[18:19], 0, s[4:5]
	s_cbranch_scc0 .LBB0_1934
